# speedup vs baseline: 1.0240x; 1.0240x over previous
.Lbk64_350:
	s_waitcnt vmcnt(0)
	s_barrier
	ds_read_b128 v[192:195], v227
	ds_read_b128 v[196:199], v228
	ds_read_b128 v[200:203], v227 offset:2048
	ds_read_b128 v[204:207], v228 offset:2048
	ds_read_b128 v[208:211], v227 offset:4096
	ds_read_b128 v[212:215], v228 offset:4096
	ds_read_b128 v[216:219], v227 offset:6144
	ds_read_b128 v[220:223], v228 offset:6144
	s_add_u32 s18, s18, 0x80
	s_addc_u32 s19, s19, 0
	s_add_u32 s16, s16, 0x80
	s_addc_u32 s17, s17, 0
	s_waitcnt lgkmcnt(0)
	s_barrier
	ds_read_b128 v[154:157], v229 offset:0
	ds_read_b128 v[158:161], v230 offset:0
	ds_read_b128 v[162:165], v229 offset:2048
	ds_read_b128 v[166:169], v230 offset:2048
	s_waitcnt lgkmcnt(2)
	v_mfma_f32_16x16x32_bf16 v[126:129], v[192:195], v[154:157], v[126:129]
	v_mfma_f32_16x16x32_bf16 v[114:117], v[200:203], v[154:157], v[114:117]
	v_mfma_f32_16x16x32_bf16 v[86:89], v[208:211], v[154:157], v[86:89]
	v_mfma_f32_16x16x32_bf16 v[54:57], v[216:219], v[154:157], v[54:57]
	v_readfirstlane_b32 s32, v145
	s_lshl_b32 m0, s32, 3
	v_mov_b32_e32 v226, v224
	global_load_lds_dwordx4 v226, s[18:19]
	v_mfma_f32_16x16x32_bf16 v[126:129], v[196:199], v[158:161], v[126:129]
	v_mfma_f32_16x16x32_bf16 v[114:117], v[204:207], v[158:161], v[114:117]
	v_mfma_f32_16x16x32_bf16 v[86:89], v[212:215], v[158:161], v[86:89]
	v_mfma_f32_16x16x32_bf16 v[54:57], v[220:223], v[158:161], v[54:57]
	s_add_u32 m0, m0, 0x400
	v_add_u32_e32 v226, 0xac00, v224
	global_load_lds_dwordx4 v226, s[18:19]
	ds_read_b128 v[154:157], v229 offset:4096
	ds_read_b128 v[158:161], v230 offset:4096
	s_waitcnt lgkmcnt(2)
	v_mfma_f32_16x16x32_bf16 v[122:125], v[192:195], v[162:165], v[122:125]
	v_mfma_f32_16x16x32_bf16 v[102:105], v[200:203], v[162:165], v[102:105]
	v_mfma_f32_16x16x32_bf16 v[70:73], v[208:211], v[162:165], v[70:73]
	v_mfma_f32_16x16x32_bf16 v[38:41], v[216:219], v[162:165], v[38:41]
	s_add_u32 m0, m0, 0x400
	v_add_u32_e32 v226, 0x15800, v224
	global_load_lds_dwordx4 v226, s[18:19]
	v_mfma_f32_16x16x32_bf16 v[122:125], v[196:199], v[166:169], v[122:125]
	v_mfma_f32_16x16x32_bf16 v[102:105], v[204:207], v[166:169], v[102:105]
	v_mfma_f32_16x16x32_bf16 v[70:73], v[212:215], v[166:169], v[70:73]
	v_mfma_f32_16x16x32_bf16 v[38:41], v[220:223], v[166:169], v[38:41]
	s_add_u32 m0, m0, 0x400
	v_add_u32_e32 v226, 0x20400, v224
	global_load_lds_dwordx4 v226, s[18:19]
	ds_read_b128 v[162:165], v229 offset:6144
	ds_read_b128 v[166:169], v230 offset:6144
	s_waitcnt lgkmcnt(2)
	v_mfma_f32_16x16x32_bf16 v[118:121], v[192:195], v[154:157], v[118:121]
	v_mfma_f32_16x16x32_bf16 v[90:93], v[200:203], v[154:157], v[90:93]
	v_mfma_f32_16x16x32_bf16 v[58:61], v[208:211], v[154:157], v[58:61]
	v_mfma_f32_16x16x32_bf16 v[26:29], v[216:219], v[154:157], v[26:29]
	s_add_u32 m0, m0, 0x400
	v_add_u32_e32 v226, 0x2b000, v224
	global_load_lds_dwordx4 v226, s[18:19]
	v_mfma_f32_16x16x32_bf16 v[118:121], v[196:199], v[158:161], v[118:121]
	v_mfma_f32_16x16x32_bf16 v[90:93], v[204:207], v[158:161], v[90:93]
	v_mfma_f32_16x16x32_bf16 v[58:61], v[212:215], v[158:161], v[58:61]
	v_mfma_f32_16x16x32_bf16 v[26:29], v[220:223], v[158:161], v[26:29]
	s_add_u32 m0, m0, 0x400
	v_add_u32_e32 v226, 0x35c00, v224
	global_load_lds_dwordx4 v226, s[18:19]
	ds_read_b128 v[154:157], v229 offset:8192
	ds_read_b128 v[158:161], v230 offset:8192
	s_waitcnt lgkmcnt(2)
	v_mfma_f32_16x16x32_bf16 v[110:113], v[192:195], v[162:165], v[110:113]
	v_mfma_f32_16x16x32_bf16 v[78:81], v[200:203], v[162:165], v[78:81]
	v_mfma_f32_16x16x32_bf16 v[46:49], v[208:211], v[162:165], v[46:49]
	v_mfma_f32_16x16x32_bf16 v[18:21], v[216:219], v[162:165], v[18:21]
	s_add_u32 m0, m0, 0x400
	v_add_u32_e32 v226, 0x40800, v224
	global_load_lds_dwordx4 v226, s[18:19]
	v_mfma_f32_16x16x32_bf16 v[110:113], v[196:199], v[166:169], v[110:113]
	v_mfma_f32_16x16x32_bf16 v[78:81], v[204:207], v[166:169], v[78:81]
	v_mfma_f32_16x16x32_bf16 v[46:49], v[212:215], v[166:169], v[46:49]
	v_mfma_f32_16x16x32_bf16 v[18:21], v[220:223], v[166:169], v[18:21]
	s_add_u32 m0, m0, 0x400
	v_add_u32_e32 v226, 0x4b400, v224
	global_load_lds_dwordx4 v226, s[18:19]
	ds_read_b128 v[162:165], v229 offset:10240
	ds_read_b128 v[166:169], v230 offset:10240
	s_waitcnt lgkmcnt(2)
	v_mfma_f32_16x16x32_bf16 v[106:109], v[192:195], v[154:157], v[106:109]
	v_mfma_f32_16x16x32_bf16 v[74:77], v[200:203], v[154:157], v[74:77]
	v_mfma_f32_16x16x32_bf16 v[42:45], v[208:211], v[154:157], v[42:45]
	v_mfma_f32_16x16x32_bf16 v[14:17], v[216:219], v[154:157], v[14:17]
	s_add_u32 m0, s25, 44
	s_and_b32 m0, m0, 1
	s_lshl_b32 m0, m0, 14
	s_add_u32 m0, m0, 0x8000
	v_readfirstlane_b32 s32, v145
	s_lshl_b32 s32, s32, 2
	s_add_u32 m0, m0, s32
	v_mov_b32_e32 v226, v225
	global_load_lds_dwordx4 v226, s[16:17]
	v_mfma_f32_16x16x32_bf16 v[106:109], v[196:199], v[158:161], v[106:109]
	v_mfma_f32_16x16x32_bf16 v[74:77], v[204:207], v[158:161], v[74:77]
	v_mfma_f32_16x16x32_bf16 v[42:45], v[212:215], v[158:161], v[42:45]
	v_mfma_f32_16x16x32_bf16 v[14:17], v[220:223], v[158:161], v[14:17]
	s_add_u32 m0, m0, 0x400
	v_add_u32_e32 v226, 0xac00, v225
	global_load_lds_dwordx4 v226, s[16:17]
	ds_read_b128 v[154:157], v229 offset:12288
	ds_read_b128 v[158:161], v230 offset:12288
	s_waitcnt lgkmcnt(2)
	v_mfma_f32_16x16x32_bf16 v[98:101], v[192:195], v[162:165], v[98:101]
	v_mfma_f32_16x16x32_bf16 v[66:69], v[200:203], v[162:165], v[66:69]
	v_mfma_f32_16x16x32_bf16 v[34:37], v[208:211], v[162:165], v[34:37]
	v_mfma_f32_16x16x32_bf16 v[10:13], v[216:219], v[162:165], v[10:13]
	s_add_u32 m0, m0, 0x400
	v_add_u32_e32 v226, 0x15800, v225
	global_load_lds_dwordx4 v226, s[16:17]
	v_mfma_f32_16x16x32_bf16 v[98:101], v[196:199], v[166:169], v[98:101]
	v_mfma_f32_16x16x32_bf16 v[66:69], v[204:207], v[166:169], v[66:69]
	v_mfma_f32_16x16x32_bf16 v[34:37], v[212:215], v[166:169], v[34:37]
	v_mfma_f32_16x16x32_bf16 v[10:13], v[220:223], v[166:169], v[10:13]
	s_add_u32 m0, m0, 0x400
	v_add_u32_e32 v226, 0x20400, v225
	global_load_lds_dwordx4 v226, s[16:17]
	ds_read_b128 v[162:165], v229 offset:14336
	ds_read_b128 v[166:169], v230 offset:14336
	s_waitcnt lgkmcnt(2)
	v_mfma_f32_16x16x32_bf16 v[94:97], v[192:195], v[154:157], v[94:97]
	v_mfma_f32_16x16x32_bf16 v[62:65], v[200:203], v[154:157], v[62:65]
	v_mfma_f32_16x16x32_bf16 v[30:33], v[208:211], v[154:157], v[30:33]
	v_mfma_f32_16x16x32_bf16 v[6:9], v[216:219], v[154:157], v[6:9]
	v_mfma_f32_16x16x32_bf16 v[94:97], v[196:199], v[158:161], v[94:97]
	v_mfma_f32_16x16x32_bf16 v[62:65], v[204:207], v[158:161], v[62:65]
	v_mfma_f32_16x16x32_bf16 v[30:33], v[212:215], v[158:161], v[30:33]
	v_mfma_f32_16x16x32_bf16 v[6:9], v[220:223], v[158:161], v[6:9]
	s_waitcnt lgkmcnt(0)
	v_mfma_f32_16x16x32_bf16 v[82:85], v[192:195], v[162:165], v[82:85]
	v_mfma_f32_16x16x32_bf16 v[50:53], v[200:203], v[162:165], v[50:53]
	v_mfma_f32_16x16x32_bf16 v[22:25], v[208:211], v[162:165], v[22:25]
	v_mfma_f32_16x16x32_bf16 v[2:5], v[216:219], v[162:165], v[2:5]
	v_mfma_f32_16x16x32_bf16 v[82:85], v[196:199], v[166:169], v[82:85]
	v_mfma_f32_16x16x32_bf16 v[50:53], v[204:207], v[166:169], v[50:53]
	v_mfma_f32_16x16x32_bf16 v[22:25], v[212:215], v[166:169], v[22:25]
	v_mfma_f32_16x16x32_bf16 v[2:5], v[220:223], v[166:169], v[2:5]
	v_xor_b32_e32 v229, 0x4000, v229
	v_xor_b32_e32 v230, 0x4000, v230
	s_add_i32 s25, s25, 1
	s_cmp_lg_u32 s25, 42
	s_cbranch_scc1 .Lbk64_350
	s_waitcnt vmcnt(0)
	s_barrier
	ds_read_b128 v[192:195], v227
	ds_read_b128 v[196:199], v228
	ds_read_b128 v[200:203], v227 offset:2048
	ds_read_b128 v[204:207], v228 offset:2048
	ds_read_b128 v[208:211], v227 offset:4096
	ds_read_b128 v[212:215], v228 offset:4096
	ds_read_b128 v[216:219], v227 offset:6144
	ds_read_b128 v[220:223], v228 offset:6144
	s_waitcnt lgkmcnt(0)
	s_barrier
	ds_read_b128 v[154:157], v229 offset:0
	ds_read_b128 v[158:161], v230 offset:0
	ds_read_b128 v[162:165], v229 offset:2048
	ds_read_b128 v[166:169], v230 offset:2048
	s_waitcnt lgkmcnt(2)
	v_mfma_f32_16x16x32_bf16 v[126:129], v[192:195], v[154:157], v[126:129]
	v_mfma_f32_16x16x32_bf16 v[114:117], v[200:203], v[154:157], v[114:117]
	v_mfma_f32_16x16x32_bf16 v[86:89], v[208:211], v[154:157], v[86:89]
	v_mfma_f32_16x16x32_bf16 v[54:57], v[216:219], v[154:157], v[54:57]
	v_mfma_f32_16x16x32_bf16 v[126:129], v[196:199], v[158:161], v[126:129]
	v_mfma_f32_16x16x32_bf16 v[114:117], v[204:207], v[158:161], v[114:117]
	v_mfma_f32_16x16x32_bf16 v[86:89], v[212:215], v[158:161], v[86:89]
	v_mfma_f32_16x16x32_bf16 v[54:57], v[220:223], v[158:161], v[54:57]
	ds_read_b128 v[154:157], v229 offset:4096
	ds_read_b128 v[158:161], v230 offset:4096
	s_waitcnt lgkmcnt(2)
	v_mfma_f32_16x16x32_bf16 v[122:125], v[192:195], v[162:165], v[122:125]
	v_mfma_f32_16x16x32_bf16 v[102:105], v[200:203], v[162:165], v[102:105]
	v_mfma_f32_16x16x32_bf16 v[70:73], v[208:211], v[162:165], v[70:73]
	v_mfma_f32_16x16x32_bf16 v[38:41], v[216:219], v[162:165], v[38:41]
	v_mfma_f32_16x16x32_bf16 v[122:125], v[196:199], v[166:169], v[122:125]
	v_mfma_f32_16x16x32_bf16 v[102:105], v[204:207], v[166:169], v[102:105]
	v_mfma_f32_16x16x32_bf16 v[70:73], v[212:215], v[166:169], v[70:73]
	v_mfma_f32_16x16x32_bf16 v[38:41], v[220:223], v[166:169], v[38:41]
	ds_read_b128 v[162:165], v229 offset:6144
	ds_read_b128 v[166:169], v230 offset:6144
	s_waitcnt lgkmcnt(2)
	v_mfma_f32_16x16x32_bf16 v[118:121], v[192:195], v[154:157], v[118:121]
	v_mfma_f32_16x16x32_bf16 v[90:93], v[200:203], v[154:157], v[90:93]
	v_mfma_f32_16x16x32_bf16 v[58:61], v[208:211], v[154:157], v[58:61]
	v_mfma_f32_16x16x32_bf16 v[26:29], v[216:219], v[154:157], v[26:29]
	v_mfma_f32_16x16x32_bf16 v[118:121], v[196:199], v[158:161], v[118:121]
	v_mfma_f32_16x16x32_bf16 v[90:93], v[204:207], v[158:161], v[90:93]
	v_mfma_f32_16x16x32_bf16 v[58:61], v[212:215], v[158:161], v[58:61]
	v_mfma_f32_16x16x32_bf16 v[26:29], v[220:223], v[158:161], v[26:29]
	ds_read_b128 v[154:157], v229 offset:8192
	ds_read_b128 v[158:161], v230 offset:8192
	s_waitcnt lgkmcnt(2)
	v_mfma_f32_16x16x32_bf16 v[110:113], v[192:195], v[162:165], v[110:113]
	v_mfma_f32_16x16x32_bf16 v[78:81], v[200:203], v[162:165], v[78:81]
	v_mfma_f32_16x16x32_bf16 v[46:49], v[208:211], v[162:165], v[46:49]
	v_mfma_f32_16x16x32_bf16 v[18:21], v[216:219], v[162:165], v[18:21]
	v_mfma_f32_16x16x32_bf16 v[110:113], v[196:199], v[166:169], v[110:113]
	v_mfma_f32_16x16x32_bf16 v[78:81], v[204:207], v[166:169], v[78:81]
	v_mfma_f32_16x16x32_bf16 v[46:49], v[212:215], v[166:169], v[46:49]
	v_mfma_f32_16x16x32_bf16 v[18:21], v[220:223], v[166:169], v[18:21]
	ds_read_b128 v[162:165], v229 offset:10240
	ds_read_b128 v[166:169], v230 offset:10240
	s_waitcnt lgkmcnt(2)
	v_mfma_f32_16x16x32_bf16 v[106:109], v[192:195], v[154:157], v[106:109]
	v_mfma_f32_16x16x32_bf16 v[74:77], v[200:203], v[154:157], v[74:77]
	v_mfma_f32_16x16x32_bf16 v[42:45], v[208:211], v[154:157], v[42:45]
	v_mfma_f32_16x16x32_bf16 v[14:17], v[216:219], v[154:157], v[14:17]
	v_mfma_f32_16x16x32_bf16 v[106:109], v[196:199], v[158:161], v[106:109]
	v_mfma_f32_16x16x32_bf16 v[74:77], v[204:207], v[158:161], v[74:77]
	v_mfma_f32_16x16x32_bf16 v[42:45], v[212:215], v[158:161], v[42:45]
	v_mfma_f32_16x16x32_bf16 v[14:17], v[220:223], v[158:161], v[14:17]
	ds_read_b128 v[154:157], v229 offset:12288
	ds_read_b128 v[158:161], v230 offset:12288
	s_waitcnt lgkmcnt(2)
	v_mfma_f32_16x16x32_bf16 v[98:101], v[192:195], v[162:165], v[98:101]
	v_mfma_f32_16x16x32_bf16 v[66:69], v[200:203], v[162:165], v[66:69]
	v_mfma_f32_16x16x32_bf16 v[34:37], v[208:211], v[162:165], v[34:37]
	v_mfma_f32_16x16x32_bf16 v[10:13], v[216:219], v[162:165], v[10:13]
	v_mfma_f32_16x16x32_bf16 v[98:101], v[196:199], v[166:169], v[98:101]
	v_mfma_f32_16x16x32_bf16 v[66:69], v[204:207], v[166:169], v[66:69]
	v_mfma_f32_16x16x32_bf16 v[34:37], v[212:215], v[166:169], v[34:37]
	v_mfma_f32_16x16x32_bf16 v[10:13], v[220:223], v[166:169], v[10:13]
	ds_read_b128 v[162:165], v229 offset:14336
	ds_read_b128 v[166:169], v230 offset:14336
	s_waitcnt lgkmcnt(2)
	v_mfma_f32_16x16x32_bf16 v[94:97], v[192:195], v[154:157], v[94:97]
	v_mfma_f32_16x16x32_bf16 v[62:65], v[200:203], v[154:157], v[62:65]
	v_mfma_f32_16x16x32_bf16 v[30:33], v[208:211], v[154:157], v[30:33]
	v_mfma_f32_16x16x32_bf16 v[6:9], v[216:219], v[154:157], v[6:9]
	v_mfma_f32_16x16x32_bf16 v[94:97], v[196:199], v[158:161], v[94:97]
	v_mfma_f32_16x16x32_bf16 v[62:65], v[204:207], v[158:161], v[62:65]
	v_mfma_f32_16x16x32_bf16 v[30:33], v[212:215], v[158:161], v[30:33]
	v_mfma_f32_16x16x32_bf16 v[6:9], v[220:223], v[158:161], v[6:9]
	s_waitcnt lgkmcnt(0)
	v_mfma_f32_16x16x32_bf16 v[82:85], v[192:195], v[162:165], v[82:85]
	v_mfma_f32_16x16x32_bf16 v[50:53], v[200:203], v[162:165], v[50:53]
	v_mfma_f32_16x16x32_bf16 v[22:25], v[208:211], v[162:165], v[22:25]
	v_mfma_f32_16x16x32_bf16 v[2:5], v[216:219], v[162:165], v[2:5]
	v_mfma_f32_16x16x32_bf16 v[82:85], v[196:199], v[166:169], v[82:85]
	v_mfma_f32_16x16x32_bf16 v[50:53], v[204:207], v[166:169], v[50:53]
	v_mfma_f32_16x16x32_bf16 v[22:25], v[212:215], v[166:169], v[22:25]
	v_mfma_f32_16x16x32_bf16 v[2:5], v[220:223], v[166:169], v[2:5]
	s_nop 7
	s_nop 7
	s_waitcnt vmcnt(6)
	v_add_u32_e32 v145, v149, v147
	s_waitcnt vmcnt(0)
	s_waitcnt lgkmcnt(0)
	s_lshl_b32 s16, s5, 7
	s_ashr_i32 s17, s16, 31
	s_lshl_b64 s[16:17], s[16:17], 1
	v_and_b32_e32 v1, 0xfffffc0, v1
	v_lshl_or_b32 v1, v143, 2, v1
	v_mul_lo_u32 v1, v1, s33
	v_lshl_or_b32 v1, v142, 2, v1
	s_lshl_b32 s18, s5, 1
	s_ashr_i32 s19, s18, 31
	s_lshl_b64 s[18:19], s[18:19], 2
	s_add_i32 s24, s24, 1
	v_mov_b64_e32 v[158:159], v[62:63]
	v_mov_b64_e32 v[160:161], v[64:65]
	v_mov_b64_e32 v[162:163], v[30:31]
	v_mov_b64_e32 v[164:165], v[32:33]
	v_mov_b64_e32 v[130:131], v[22:23]
	v_mov_b64_e32 v[132:133], v[24:25]
	s_waitcnt lgkmcnt(0)
	v_mov_b64_e32 v[224:225], v[38:39]
	v_mov_b64_e32 v[226:227], v[40:41]
	v_mov_b64_e32 v[38:39], v[34:35]
	v_mov_b64_e32 v[40:41], v[36:37]
	v_mov_b64_e32 v[34:35], v[2:3]
	v_mov_b64_e32 v[36:37], v[4:5]
	s_nop 2
	v_mov_b32_e32 v2, v170
	v_mov_b64_e32 v[208:209], v[114:115]
	v_mov_b64_e32 v[210:211], v[116:117]
	v_add_u32_e32 v2, s4, v2
	v_ashrrev_i32_e32 v3, 31, v2
	v_lshlrev_b64 v[2:3], 11, v[2:3]
	v_lshl_add_u64 v[2:3], s[8:9], 0, v[2:3]
	v_lshl_add_u64 v[2:3], v[2:3], 0, s[16:17]
	v_mov_b64_e32 v[212:213], v[54:55]
	v_mov_b64_e32 v[214:215], v[56:57]
	v_mov_b64_e32 v[216:217], v[122:123]
	v_mov_b64_e32 v[218:219], v[124:125]
	v_mov_b64_e32 v[220:221], v[102:103]
	v_mov_b64_e32 v[222:223], v[104:105]
	v_mov_b64_e32 v[228:229], v[118:119]
	v_mov_b64_e32 v[230:231], v[120:121]
	v_mov_b64_e32 v[232:233], v[58:59]
	v_mov_b64_e32 v[234:235], v[60:61]
	v_mov_b64_e32 v[236:237], v[26:27]
	v_mov_b64_e32 v[238:239], v[28:29]
	v_mov_b64_e32 v[240:241], v[110:111]
	v_mov_b64_e32 v[242:243], v[112:113]
	v_mov_b64_e32 v[244:245], v[78:79]
	v_mov_b64_e32 v[246:247], v[80:81]
	v_mov_b64_e32 v[248:249], v[46:47]
	v_mov_b64_e32 v[250:251], v[48:49]
	v_mov_b64_e32 v[62:63], v[106:107]
	v_mov_b64_e32 v[64:65], v[108:109]
	v_mov_b64_e32 v[46:47], v[74:75]
	v_mov_b64_e32 v[48:49], v[76:77]
	v_mov_b64_e32 v[74:75], v[98:99]
	v_mov_b64_e32 v[76:77], v[100:101]
	v_mov_b64_e32 v[54:55], v[66:67]
	v_mov_b64_e32 v[56:57], v[68:69]
	v_mov_b64_e32 v[58:59], v[158:159]
	v_mov_b64_e32 v[60:61], v[160:161]
	v_mov_b64_e32 v[66:67], v[50:51]
	v_mov_b64_e32 v[68:69], v[52:53]
	flat_load_dwordx4 v[138:141], v[2:3]
	flat_load_dwordx4 v[122:125], v[2:3] offset:16
	flat_load_dwordx4 v[118:121], v[2:3] offset:32
	flat_load_dwordx4 v[114:117], v[2:3] offset:48
	flat_load_dwordx4 v[110:113], v[2:3] offset:64
	flat_load_dwordx4 v[106:109], v[2:3] offset:80
	flat_load_dwordx4 v[102:105], v[2:3] offset:96
	flat_load_dwordx4 v[98:101], v[2:3] offset:112
	s_waitcnt vmcnt(0) lgkmcnt(0)
	s_barrier
	s_nop 7
	ds_write2_b32 v1, v126, v216 offset1:16
	ds_write2_b32 v1, v127, v217 offset0:68 offset1:84
	ds_write2_b32 v1, v128, v218 offset0:136 offset1:152
	ds_write2_b32 v1, v129, v219 offset0:204 offset1:220
	ds_write2_b32 v1, v228, v240 offset0:32 offset1:48
	ds_write2_b32 v1, v229, v241 offset0:100 offset1:116
	ds_write2_b32 v1, v230, v242 offset0:168 offset1:184
	ds_write2_b32 v1, v231, v243 offset0:236 offset1:252
	v_mov_b64_e32 v[180:181], v[18:19]
	v_mov_b64_e32 v[182:183], v[20:21]
	v_mov_b64_e32 v[78:79], v[94:95]
	v_mov_b64_e32 v[80:81], v[96:97]
	v_add_u32_e32 v135, 0x3000, v1
	v_add_u32_e32 v134, 0x3400, v1
	v_mov_b32_e32 v136, v170
	v_mov_b64_e32 v[50:51], v[130:131]
	v_mov_b64_e32 v[52:53], v[132:133]
	v_lshlrev_b32_e32 v137, 16, v138
	s_nop 1
	v_add_u32_e32 v130, 0x1000, v1
	v_add_u32_e32 v131, 0x1400, v1
	v_add_u32_e32 v132, 0x2000, v1
	v_add_u32_e32 v133, 0x2400, v1
	ds_write2_b32 v130, v208, v220 offset0:64 offset1:80
	ds_write2_b32 v130, v209, v221 offset0:132 offset1:148
	ds_write2_b32 v130, v210, v222 offset0:200 offset1:216
	ds_write2_b32 v131, v211, v223 offset0:12 offset1:28
	ds_write2_b32 v130, v90, v244 offset0:96 offset1:112
	ds_write2_b32 v130, v91, v245 offset0:164 offset1:180
	ds_write2_b32 v130, v92, v246 offset0:232 offset1:248
	ds_write2_b32 v131, v93, v247 offset0:44 offset1:60
	ds_write2_b32 v132, v86, v70 offset0:128 offset1:144
	ds_write2_b32 v132, v87, v71 offset0:196 offset1:212
	ds_write2_b32 v133, v88, v72 offset0:8 offset1:24
	ds_write2_b32 v133, v89, v73 offset0:76 offset1:92
	ds_write2_b32 v132, v232, v248 offset0:160 offset1:176
	ds_write2_b32 v132, v233, v249 offset0:228 offset1:244
	ds_write2_b32 v133, v234, v250 offset0:40 offset1:56
	ds_write2_b32 v133, v235, v251 offset0:108 offset1:124
	ds_write2_b32 v135, v212, v224 offset0:192 offset1:208
	ds_write2_b32 v134, v213, v225 offset0:4 offset1:20
	ds_write2_b32 v134, v214, v226 offset0:72 offset1:88
	ds_write2_b32 v134, v215, v227 offset0:140 offset1:156
	ds_write2_b32 v135, v236, v180 offset0:224 offset1:240
	ds_write2_b32 v134, v237, v181 offset0:36 offset1:52
	ds_write2_b32 v134, v238, v182 offset0:104 offset1:120
	ds_write2_b32 v134, v239, v183 offset0:172 offset1:188
	s_waitcnt lgkmcnt(0)
	s_barrier
	v_mov_b64_e32 v[30:31], v[42:43]
	v_mov_b64_e32 v[32:33], v[44:45]
	v_add_u32_e32 v126, s4, v136
	v_ashrrev_i32_e32 v127, 31, v126
	v_lshlrev_b64 v[2:3], 11, v[126:127]
	v_lshl_add_u64 v[2:3], s[8:9], 0, v[2:3]
	v_lshl_add_u64 v[128:129], v[2:3], 0, s[16:17]
	v_mul_lo_u32 v136, v136, s33
	v_mov_b64_e32 v[18:19], v[14:15]
	v_mov_b64_e32 v[20:21], v[16:17]
	v_and_b32_e32 v138, 0xffff0000, v138
	v_mov_b64_e32 v[22:23], v[10:11]
	v_mov_b64_e32 v[24:25], v[12:13]
	v_mov_b64_e32 v[42:43], v[162:163]
	v_mov_b64_e32 v[44:45], v[164:165]
	v_mov_b64_e32 v[26:27], v[6:7]
	v_mov_b64_e32 v[28:29], v[8:9]
	flat_load_dwordx4 v[94:97], v[128:129] offset:128
	flat_load_dwordx4 v[90:93], v[128:129] offset:144
	flat_load_dwordx4 v[86:89], v[128:129] offset:160
	flat_load_dwordx4 v[70:73], v[128:129] offset:176
	flat_load_dwordx4 v[14:17], v[128:129] offset:192
	flat_load_dwordx4 v[10:13], v[128:129] offset:208
	flat_load_dwordx4 v[6:9], v[128:129] offset:224
	flat_load_dwordx4 v[2:5], v[128:129] offset:240
	ds_read_b128 v[142:145], v136
	ds_read_b128 v[154:157], v136 offset:16
	s_waitcnt lgkmcnt(0)
	v_add_f32_e32 v137, v142, v137
	v_add_f32_e32 v138, v143, v138
	v_cvt_pk_bf16_f32 v138, v137, v138
	v_lshlrev_b32_e32 v137, 16, v139
	v_and_b32_e32 v139, 0xffff0000, v139
	v_add_f32_e32 v137, v144, v137
	v_add_f32_e32 v139, v145, v139
	v_cvt_pk_bf16_f32 v139, v137, v139
	v_lshlrev_b32_e32 v137, 16, v140
	v_and_b32_e32 v140, 0xffff0000, v140
	v_add_f32_e32 v137, v154, v137
	v_add_f32_e32 v140, v155, v140
	v_cvt_pk_bf16_f32 v140, v137, v140
	v_lshlrev_b32_e32 v137, 16, v141
	v_and_b32_e32 v141, 0xffff0000, v141
	v_add_f32_e32 v137, v156, v137
	v_add_f32_e32 v141, v157, v141
	v_and_b32_e32 v142, 0xffff0000, v138
	v_cvt_pk_bf16_f32 v141, v137, v141
	v_lshlrev_b32_e32 v137, 16, v138
	v_mul_f32_e32 v153, v142, v142
	v_lshlrev_b32_e32 v143, 16, v139
	v_fmac_f32_e32 v153, v137, v137
	v_and_b32_e32 v144, 0xffff0000, v139
	v_fmac_f32_e32 v153, v143, v143
	v_lshlrev_b32_e32 v145, 16, v140
	v_fmac_f32_e32 v153, v144, v144
	ds_write_b128 v136, v[138:141]
	v_and_b32_e32 v147, 0xffff0000, v140
	v_lshlrev_b32_e32 v149, 16, v141
	v_and_b32_e32 v151, 0xffff0000, v141
	v_fmac_f32_e32 v153, v145, v145
	ds_read_b128 v[138:141], v136 offset:32
	ds_read_b128 v[142:145], v136 offset:48
	v_lshlrev_b32_e32 v137, 16, v122
	v_and_b32_e32 v122, 0xffff0000, v122
	v_fmac_f32_e32 v153, v147, v147
	s_waitcnt lgkmcnt(0)
	v_add_f32_e32 v137, v138, v137
	v_add_f32_e32 v122, v139, v122
	v_cvt_pk_bf16_f32 v122, v137, v122
	v_lshlrev_b32_e32 v137, 16, v123
	v_and_b32_e32 v123, 0xffff0000, v123
	v_add_f32_e32 v137, v140, v137
	v_add_f32_e32 v123, v141, v123
	v_cvt_pk_bf16_f32 v123, v137, v123
	v_lshlrev_b32_e32 v137, 16, v124
	v_and_b32_e32 v124, 0xffff0000, v124
	v_add_f32_e32 v137, v142, v137
	v_add_f32_e32 v124, v143, v124
	v_cvt_pk_bf16_f32 v124, v137, v124
	v_lshlrev_b32_e32 v137, 16, v125
	v_and_b32_e32 v125, 0xffff0000, v125
	v_add_f32_e32 v137, v144, v137
	v_add_f32_e32 v125, v145, v125
	v_and_b32_e32 v138, 0xffff0000, v122
	v_cvt_pk_bf16_f32 v125, v137, v125
	v_lshlrev_b32_e32 v137, 16, v122
	v_mul_f32_e32 v138, v138, v138
	v_lshlrev_b32_e32 v139, 16, v123
	v_fmac_f32_e32 v138, v137, v137
	v_and_b32_e32 v140, 0xffff0000, v123
	v_fmac_f32_e32 v138, v139, v139
	v_lshlrev_b32_e32 v141, 16, v124
	v_fmac_f32_e32 v138, v140, v140
	v_and_b32_e32 v142, 0xffff0000, v124
	v_fmac_f32_e32 v138, v141, v141
	v_lshlrev_b32_e32 v143, 16, v125
	v_fmac_f32_e32 v138, v142, v142
	v_fmac_f32_e32 v153, v149, v149
	v_and_b32_e32 v144, 0xffff0000, v125
	v_fmac_f32_e32 v138, v143, v143
	v_fmac_f32_e32 v153, v151, v151
	v_fmac_f32_e32 v138, v144, v144
	ds_write_b128 v136, v[122:125] offset:16
	v_add_f32_e32 v137, v153, v138
	ds_read_b128 v[122:125], v136 offset:64
	ds_read_b128 v[138:141], v136 offset:80
	v_lshlrev_b32_e32 v142, 16, v118
	v_and_b32_e32 v118, 0xffff0000, v118
	s_waitcnt lgkmcnt(0)
	v_add_f32_e32 v122, v122, v142
	v_add_f32_e32 v118, v123, v118
	v_cvt_pk_bf16_f32 v118, v122, v118
	v_lshlrev_b32_e32 v122, 16, v119
	v_and_b32_e32 v119, 0xffff0000, v119
	v_add_f32_e32 v122, v124, v122
	v_add_f32_e32 v119, v125, v119
	v_cvt_pk_bf16_f32 v119, v122, v119
	v_lshlrev_b32_e32 v122, 16, v120
	v_and_b32_e32 v120, 0xffff0000, v120
	v_add_f32_e32 v122, v138, v122
	v_add_f32_e32 v120, v139, v120
	v_cvt_pk_bf16_f32 v120, v122, v120
	v_lshlrev_b32_e32 v122, 16, v121
	v_and_b32_e32 v121, 0xffff0000, v121
	v_add_f32_e32 v122, v140, v122
	v_add_f32_e32 v121, v141, v121
	v_and_b32_e32 v123, 0xffff0000, v118
	v_cvt_pk_bf16_f32 v121, v122, v121
	v_lshlrev_b32_e32 v122, 16, v118
	v_mul_f32_e32 v123, v123, v123
	v_lshlrev_b32_e32 v124, 16, v119
	v_fmac_f32_e32 v123, v122, v122
	v_and_b32_e32 v125, 0xffff0000, v119
	v_fmac_f32_e32 v123, v124, v124
	v_lshlrev_b32_e32 v138, 16, v120
	v_fmac_f32_e32 v123, v125, v125
	v_and_b32_e32 v139, 0xffff0000, v120
	v_fmac_f32_e32 v123, v138, v138
	v_lshlrev_b32_e32 v140, 16, v121
	v_fmac_f32_e32 v123, v139, v139
	v_and_b32_e32 v141, 0xffff0000, v121
	v_fmac_f32_e32 v123, v140, v140
	v_fmac_f32_e32 v123, v141, v141
	ds_write_b128 v136, v[118:121] offset:32
	v_add_f32_e32 v137, v137, v123
	ds_read_b128 v[118:121], v136 offset:96
	ds_read_b128 v[122:125], v136 offset:112
	v_lshlrev_b32_e32 v138, 16, v114
	v_and_b32_e32 v114, 0xffff0000, v114
	s_waitcnt lgkmcnt(0)
	v_add_f32_e32 v118, v118, v138
	v_add_f32_e32 v114, v119, v114
	v_cvt_pk_bf16_f32 v114, v118, v114
	v_lshlrev_b32_e32 v118, 16, v115
	v_and_b32_e32 v115, 0xffff0000, v115
	v_add_f32_e32 v118, v120, v118
	v_add_f32_e32 v115, v121, v115
	v_cvt_pk_bf16_f32 v115, v118, v115
	v_lshlrev_b32_e32 v118, 16, v116
	v_and_b32_e32 v116, 0xffff0000, v116
	v_add_f32_e32 v118, v122, v118
	v_add_f32_e32 v116, v123, v116
	v_cvt_pk_bf16_f32 v116, v118, v116
	v_lshlrev_b32_e32 v118, 16, v117
	v_and_b32_e32 v117, 0xffff0000, v117
	v_add_f32_e32 v118, v124, v118
	v_add_f32_e32 v117, v125, v117
	v_and_b32_e32 v119, 0xffff0000, v114
	v_cvt_pk_bf16_f32 v117, v118, v117
	v_lshlrev_b32_e32 v118, 16, v114
	v_mul_f32_e32 v119, v119, v119
	v_lshlrev_b32_e32 v120, 16, v115
	v_fmac_f32_e32 v119, v118, v118
	v_and_b32_e32 v121, 0xffff0000, v115
	v_fmac_f32_e32 v119, v120, v120
	v_lshlrev_b32_e32 v122, 16, v116
	v_fmac_f32_e32 v119, v121, v121
	v_and_b32_e32 v123, 0xffff0000, v116
	v_fmac_f32_e32 v119, v122, v122
	v_lshlrev_b32_e32 v124, 16, v117
	v_fmac_f32_e32 v119, v123, v123
	v_and_b32_e32 v125, 0xffff0000, v117
	v_fmac_f32_e32 v119, v124, v124
	v_fmac_f32_e32 v119, v125, v125
	ds_write_b128 v136, v[114:117] offset:48
	v_add_f32_e32 v122, v137, v119
	ds_read_b128 v[114:117], v136 offset:128
	ds_read_b128 v[118:121], v136 offset:144
	v_lshlrev_b32_e32 v123, 16, v110
	v_and_b32_e32 v110, 0xffff0000, v110
	s_waitcnt lgkmcnt(0)
	v_add_f32_e32 v114, v114, v123
	v_add_f32_e32 v110, v115, v110
	v_cvt_pk_bf16_f32 v110, v114, v110
	v_lshlrev_b32_e32 v114, 16, v111
	v_and_b32_e32 v111, 0xffff0000, v111
	v_add_f32_e32 v114, v116, v114
	v_add_f32_e32 v111, v117, v111
	v_cvt_pk_bf16_f32 v111, v114, v111
	v_lshlrev_b32_e32 v114, 16, v112
	v_and_b32_e32 v112, 0xffff0000, v112
	v_add_f32_e32 v114, v118, v114
	v_add_f32_e32 v112, v119, v112
	v_cvt_pk_bf16_f32 v112, v114, v112
	v_lshlrev_b32_e32 v114, 16, v113
	v_and_b32_e32 v113, 0xffff0000, v113
	v_add_f32_e32 v114, v120, v114
	v_add_f32_e32 v113, v121, v113
	v_and_b32_e32 v115, 0xffff0000, v110
	v_cvt_pk_bf16_f32 v113, v114, v113
	v_lshlrev_b32_e32 v114, 16, v110
	v_mul_f32_e32 v115, v115, v115
	v_lshlrev_b32_e32 v116, 16, v111
	v_fmac_f32_e32 v115, v114, v114
	v_and_b32_e32 v117, 0xffff0000, v111
	v_fmac_f32_e32 v115, v116, v116
	v_lshlrev_b32_e32 v118, 16, v112
	v_fmac_f32_e32 v115, v117, v117
	v_and_b32_e32 v119, 0xffff0000, v112
	v_fmac_f32_e32 v115, v118, v118
	v_lshlrev_b32_e32 v120, 16, v113
	v_fmac_f32_e32 v115, v119, v119
	v_and_b32_e32 v121, 0xffff0000, v113
	v_fmac_f32_e32 v115, v120, v120
	v_fmac_f32_e32 v115, v121, v121
	ds_write_b128 v136, v[110:113] offset:64
	v_add_f32_e32 v118, v122, v115
	ds_read_b128 v[110:113], v136 offset:160
	ds_read_b128 v[114:117], v136 offset:176
	v_lshlrev_b32_e32 v119, 16, v106
	v_and_b32_e32 v106, 0xffff0000, v106
	s_waitcnt lgkmcnt(0)
	v_add_f32_e32 v110, v110, v119
	v_add_f32_e32 v106, v111, v106
	v_cvt_pk_bf16_f32 v106, v110, v106
	v_lshlrev_b32_e32 v110, 16, v107
	v_and_b32_e32 v107, 0xffff0000, v107
	v_add_f32_e32 v110, v112, v110
	v_add_f32_e32 v107, v113, v107
	v_cvt_pk_bf16_f32 v107, v110, v107
	v_lshlrev_b32_e32 v110, 16, v108
	v_and_b32_e32 v108, 0xffff0000, v108
	v_add_f32_e32 v110, v114, v110
	v_add_f32_e32 v108, v115, v108
	v_cvt_pk_bf16_f32 v108, v110, v108
	v_lshlrev_b32_e32 v110, 16, v109
	v_and_b32_e32 v109, 0xffff0000, v109
	v_add_f32_e32 v110, v116, v110
	v_add_f32_e32 v109, v117, v109
	v_and_b32_e32 v111, 0xffff0000, v106
	v_cvt_pk_bf16_f32 v109, v110, v109
	v_lshlrev_b32_e32 v110, 16, v106
	v_mul_f32_e32 v111, v111, v111
	v_lshlrev_b32_e32 v112, 16, v107
	v_fmac_f32_e32 v111, v110, v110
	v_and_b32_e32 v113, 0xffff0000, v107
	v_fmac_f32_e32 v111, v112, v112
	v_lshlrev_b32_e32 v114, 16, v108
	v_fmac_f32_e32 v111, v113, v113
	v_and_b32_e32 v115, 0xffff0000, v108
	v_fmac_f32_e32 v111, v114, v114
	v_lshlrev_b32_e32 v116, 16, v109
	v_fmac_f32_e32 v111, v115, v115
	v_and_b32_e32 v117, 0xffff0000, v109
	v_fmac_f32_e32 v111, v116, v116
	v_fmac_f32_e32 v111, v117, v117
	ds_write_b128 v136, v[106:109] offset:80
	v_add_f32_e32 v114, v118, v111
	ds_read_b128 v[106:109], v136 offset:192
	ds_read_b128 v[110:113], v136 offset:208
	v_lshlrev_b32_e32 v115, 16, v102
	v_and_b32_e32 v102, 0xffff0000, v102
	s_waitcnt lgkmcnt(0)
	v_add_f32_e32 v106, v106, v115
	v_add_f32_e32 v102, v107, v102
	v_cvt_pk_bf16_f32 v102, v106, v102
	v_lshlrev_b32_e32 v106, 16, v103
	v_and_b32_e32 v103, 0xffff0000, v103
	v_add_f32_e32 v106, v108, v106
	v_add_f32_e32 v103, v109, v103
	v_cvt_pk_bf16_f32 v103, v106, v103
	v_lshlrev_b32_e32 v106, 16, v104
	v_and_b32_e32 v104, 0xffff0000, v104
	v_add_f32_e32 v106, v110, v106
	v_add_f32_e32 v104, v111, v104
	v_cvt_pk_bf16_f32 v104, v106, v104
	v_lshlrev_b32_e32 v106, 16, v105
	v_and_b32_e32 v105, 0xffff0000, v105
	v_add_f32_e32 v106, v112, v106
	v_add_f32_e32 v105, v113, v105
	v_and_b32_e32 v107, 0xffff0000, v102
	v_cvt_pk_bf16_f32 v105, v106, v105
	v_lshlrev_b32_e32 v106, 16, v102
	v_mul_f32_e32 v107, v107, v107
	v_lshlrev_b32_e32 v108, 16, v103
	v_fmac_f32_e32 v107, v106, v106
	v_and_b32_e32 v109, 0xffff0000, v103
	v_fmac_f32_e32 v107, v108, v108
	v_lshlrev_b32_e32 v110, 16, v104
	v_fmac_f32_e32 v107, v109, v109
	v_and_b32_e32 v111, 0xffff0000, v104
	v_fmac_f32_e32 v107, v110, v110
	v_lshlrev_b32_e32 v112, 16, v105
	v_fmac_f32_e32 v107, v111, v111
	v_and_b32_e32 v113, 0xffff0000, v105
	v_fmac_f32_e32 v107, v112, v112
	v_fmac_f32_e32 v107, v113, v113
	ds_write_b128 v136, v[102:105] offset:96
	v_add_f32_e32 v110, v114, v107
	ds_read_b128 v[102:105], v136 offset:224
	ds_read_b128 v[106:109], v136 offset:240
	v_lshlrev_b32_e32 v111, 16, v98
	v_and_b32_e32 v98, 0xffff0000, v98
	s_waitcnt lgkmcnt(0)
	v_add_f32_e32 v102, v102, v111
	v_add_f32_e32 v98, v103, v98
	v_cvt_pk_bf16_f32 v98, v102, v98
	v_lshlrev_b32_e32 v102, 16, v99
	v_and_b32_e32 v99, 0xffff0000, v99
	v_add_f32_e32 v102, v104, v102
	v_add_f32_e32 v99, v105, v99
	v_cvt_pk_bf16_f32 v99, v102, v99
	v_lshlrev_b32_e32 v102, 16, v100
	v_and_b32_e32 v100, 0xffff0000, v100
	v_add_f32_e32 v102, v106, v102
	v_add_f32_e32 v100, v107, v100
	v_cvt_pk_bf16_f32 v100, v102, v100
	v_lshlrev_b32_e32 v102, 16, v101
	v_and_b32_e32 v101, 0xffff0000, v101
	v_add_f32_e32 v102, v108, v102
	v_add_f32_e32 v101, v109, v101
	v_and_b32_e32 v103, 0xffff0000, v98
	v_cvt_pk_bf16_f32 v101, v102, v101
	v_lshlrev_b32_e32 v102, 16, v98
	v_mul_f32_e32 v103, v103, v103
	v_lshlrev_b32_e32 v104, 16, v99
	v_fmac_f32_e32 v103, v102, v102
	v_and_b32_e32 v105, 0xffff0000, v99
	v_fmac_f32_e32 v103, v104, v104
	v_lshlrev_b32_e32 v106, 16, v100
	v_fmac_f32_e32 v103, v105, v105
	v_and_b32_e32 v107, 0xffff0000, v100
	v_fmac_f32_e32 v103, v106, v106
	v_lshlrev_b32_e32 v108, 16, v101
	v_fmac_f32_e32 v103, v107, v107
	v_and_b32_e32 v109, 0xffff0000, v101
	v_fmac_f32_e32 v103, v108, v108
	ds_write_b128 v136, v[98:101] offset:112
	v_and_b32_e32 v102, 63, v170
	v_lshrrev_b32_e32 v108, 3, v102
	v_sub_u32_e32 v108, v108, v102
	v_and_b32_e32 v102, 7, v102
	v_lshlrev_b32_e32 v102, 4, v102
	v_mul_i32_i24_e32 v98, 0x800, v108
	v_add_u32_e32 v98, v98, v102
	v_mul_i32_i24_e32 v108, 0x110, v108
	v_add3_u32 v108, v108, v102, v136
	s_waitcnt lgkmcnt(0)
	ds_read_b128 v[104:107], v108 offset:0
	v_mov_b32_e32 v100, v98
	v_ashrrev_i32_e32 v101, 31, v100
	v_lshl_add_u64 v[116:117], v[100:101], 0, v[128:129]
	s_waitcnt lgkmcnt(0)
	global_store_dwordx4 v[116:117], v[104:107], off
	ds_read_b128 v[112:115], v108 offset:2176
	v_add_u32_e32 v100, 0x4000, v98
	v_ashrrev_i32_e32 v101, 31, v100
	v_lshl_add_u64 v[116:117], v[100:101], 0, v[128:129]
	s_waitcnt lgkmcnt(0)
	global_store_dwordx4 v[116:117], v[112:115], off
	ds_read_b128 v[104:107], v108 offset:4352
	v_add_u32_e32 v100, 0x8000, v98
	v_ashrrev_i32_e32 v101, 31, v100
	v_lshl_add_u64 v[116:117], v[100:101], 0, v[128:129]
	s_waitcnt lgkmcnt(0)
	global_store_dwordx4 v[116:117], v[104:107], off
	ds_read_b128 v[112:115], v108 offset:6528
	v_add_u32_e32 v100, 0xc000, v98
	v_ashrrev_i32_e32 v101, 31, v100
	v_lshl_add_u64 v[116:117], v[100:101], 0, v[128:129]
	s_waitcnt lgkmcnt(0)
	global_store_dwordx4 v[116:117], v[112:115], off
	ds_read_b128 v[104:107], v108 offset:8704
	v_add_u32_e32 v100, 0x10000, v98
	v_ashrrev_i32_e32 v101, 31, v100
	v_lshl_add_u64 v[116:117], v[100:101], 0, v[128:129]
	s_waitcnt lgkmcnt(0)
	global_store_dwordx4 v[116:117], v[104:107], off
	ds_read_b128 v[112:115], v108 offset:10880
	v_add_u32_e32 v100, 0x14000, v98
	v_ashrrev_i32_e32 v101, 31, v100
	v_lshl_add_u64 v[116:117], v[100:101], 0, v[128:129]
	s_waitcnt lgkmcnt(0)
	global_store_dwordx4 v[116:117], v[112:115], off
	ds_read_b128 v[104:107], v108 offset:13056
	v_add_u32_e32 v100, 0x18000, v98
	v_ashrrev_i32_e32 v101, 31, v100
	v_lshl_add_u64 v[116:117], v[100:101], 0, v[128:129]
	s_waitcnt lgkmcnt(0)
	global_store_dwordx4 v[116:117], v[104:107], off
	ds_read_b128 v[112:115], v108 offset:15232
	v_add_u32_e32 v100, 0x1c000, v98
	v_ashrrev_i32_e32 v101, 31, v100
	v_lshl_add_u64 v[116:117], v[100:101], 0, v[128:129]
	s_waitcnt lgkmcnt(0)
	global_store_dwordx4 v[116:117], v[112:115], off
	v_fmac_f32_e32 v103, v109, v109
	v_add_f32_e32 v102, v110, v103
	v_lshlrev_b64 v[98:99], 6, v[126:127]
	v_lshl_add_u64 v[98:99], s[6:7], 0, v[98:99]
	v_lshl_add_u64 v[98:99], v[98:99], 0, s[18:19]
	flat_store_dword v[98:99], v102
	s_waitcnt lgkmcnt(0)
	s_barrier
	ds_write2_b32 v1, v62, v74 offset1:16
	ds_write2_b32 v1, v63, v75 offset0:68 offset1:84
	ds_write2_b32 v1, v64, v76 offset0:136 offset1:152
	ds_write2_b32 v1, v65, v77 offset0:204 offset1:220
	ds_write2_b32 v1, v78, v82 offset0:32 offset1:48
	ds_write2_b32 v1, v79, v83 offset0:100 offset1:116
	ds_write2_b32 v1, v80, v84 offset0:168 offset1:184
	ds_write2_b32 v1, v81, v85 offset0:236 offset1:252
	ds_write2_b32 v130, v46, v54 offset0:64 offset1:80
	ds_write2_b32 v130, v47, v55 offset0:132 offset1:148
	ds_write2_b32 v130, v48, v56 offset0:200 offset1:216
	ds_write2_b32 v131, v49, v57 offset0:12 offset1:28
	ds_write2_b32 v130, v58, v66 offset0:96 offset1:112
	ds_write2_b32 v130, v59, v67 offset0:164 offset1:180
	ds_write2_b32 v130, v60, v68 offset0:232 offset1:248
	ds_write2_b32 v131, v61, v69 offset0:44 offset1:60
	ds_write2_b32 v132, v30, v38 offset0:128 offset1:144
	ds_write2_b32 v132, v31, v39 offset0:196 offset1:212
	ds_write2_b32 v133, v32, v40 offset0:8 offset1:24
	ds_write2_b32 v133, v33, v41 offset0:76 offset1:92
	ds_write2_b32 v132, v42, v50 offset0:160 offset1:176
	ds_write2_b32 v132, v43, v51 offset0:228 offset1:244
	ds_write2_b32 v133, v44, v52 offset0:40 offset1:56
	ds_write2_b32 v133, v45, v53 offset0:108 offset1:124
	ds_write2_b32 v135, v18, v22 offset0:192 offset1:208
	ds_write2_b32 v134, v19, v23 offset0:4 offset1:20
	ds_write2_b32 v134, v20, v24 offset0:72 offset1:88
	ds_write2_b32 v134, v21, v25 offset0:140 offset1:156
	ds_write2_b32 v135, v26, v34 offset0:224 offset1:240
	ds_write2_b32 v134, v27, v35 offset0:36 offset1:52
	ds_write2_b32 v134, v28, v36 offset0:104 offset1:120
	ds_write2_b32 v134, v29, v37 offset0:172 offset1:188
	v_mov_b32_e32 v1, v170
	s_waitcnt lgkmcnt(0)
	s_barrier
	s_waitcnt vmcnt(0)
	v_lshlrev_b32_e32 v28, 16, v94
	v_add_u32_e32 v18, s4, v1
	v_ashrrev_i32_e32 v19, 31, v18
	v_lshlrev_b64 v[20:21], 11, v[18:19]
	v_lshl_add_u64 v[20:21], s[38:39], 0, v[20:21]
	v_mul_lo_u32 v1, v1, s33
	v_lshl_add_u64 v[32:33], v[20:21], 0, s[16:17]
	ds_read_b128 v[20:23], v1
	ds_read_b128 v[24:27], v1 offset:16
	s_mov_b64 s[4:5], 0
	s_waitcnt lgkmcnt(1)
	v_add_f32_e32 v20, v20, v28
	v_and_b32_e32 v28, 0xffff0000, v94
	v_add_f32_e32 v21, v21, v28
	v_cvt_pk_bf16_f32 v28, v20, v21
	v_and_b32_e32 v21, 0xffff0000, v95
	v_lshlrev_b32_e32 v20, 16, v95
	v_add_f32_e32 v21, v23, v21
	v_add_f32_e32 v20, v22, v20
	v_cvt_pk_bf16_f32 v29, v20, v21
	v_and_b32_e32 v21, 0xffff0000, v96
	v_lshlrev_b32_e32 v20, 16, v96
	s_waitcnt lgkmcnt(0)
	v_add_f32_e32 v21, v25, v21
	v_add_f32_e32 v20, v24, v20
	v_cvt_pk_bf16_f32 v30, v20, v21
	v_and_b32_e32 v21, 0xffff0000, v97
	v_lshlrev_b32_e32 v20, 16, v97
	v_add_f32_e32 v21, v27, v21
	v_add_f32_e32 v20, v26, v20
	v_cvt_pk_bf16_f32 v31, v20, v21
	v_and_b32_e32 v21, 0xffff0000, v28
	v_lshlrev_b32_e32 v20, 16, v28
	v_mul_f32_e32 v34, v21, v21
	v_lshlrev_b32_e32 v22, 16, v29
	v_fmac_f32_e32 v34, v20, v20
	v_and_b32_e32 v23, 0xffff0000, v29
	v_fmac_f32_e32 v34, v22, v22
	v_lshlrev_b32_e32 v24, 16, v30
	v_fmac_f32_e32 v34, v23, v23
	v_and_b32_e32 v25, 0xffff0000, v30
	v_fmac_f32_e32 v34, v24, v24
	v_add_co_u32_e32 v20, vcc, s90, v32
	v_lshlrev_b32_e32 v26, 16, v31
	v_fmac_f32_e32 v34, v25, v25
	v_addc_co_u32_e32 v21, vcc, 0, v33, vcc
	v_and_b32_e32 v27, 0xffff0000, v31
	v_fmac_f32_e32 v34, v26, v26
	v_mul_u32_u24_e32 v35, 0x110, v170
	ds_write_b128 v35, v[28:31]
	v_fmac_f32_e32 v34, v27, v27
	ds_read_b128 v[22:25], v1 offset:32
	ds_read_b128 v[26:29], v1 offset:48
	v_lshlrev_b32_e32 v30, 16, v90
	s_waitcnt lgkmcnt(0)
	v_add_f32_e32 v22, v22, v30
	v_and_b32_e32 v30, 0xffff0000, v90
	v_add_f32_e32 v23, v23, v30
	v_cvt_pk_bf16_f32 v22, v22, v23
	v_lshlrev_b32_e32 v23, 16, v91
	v_add_f32_e32 v23, v24, v23
	v_and_b32_e32 v24, 0xffff0000, v91
	v_add_f32_e32 v24, v25, v24
	v_cvt_pk_bf16_f32 v23, v23, v24
	v_lshlrev_b32_e32 v24, 16, v92
	v_and_b32_e32 v25, 0xffff0000, v92
	v_add_f32_e32 v24, v26, v24
	v_add_f32_e32 v25, v27, v25
	v_cvt_pk_bf16_f32 v24, v24, v25
	v_lshlrev_b32_e32 v25, 16, v93
	v_and_b32_e32 v26, 0xffff0000, v93
	v_add_f32_e32 v25, v28, v25
	v_add_f32_e32 v26, v29, v26
	v_and_b32_e32 v27, 0xffff0000, v22
	v_cvt_pk_bf16_f32 v25, v25, v26
	v_lshlrev_b32_e32 v26, 16, v22
	v_mul_f32_e32 v27, v27, v27
	v_lshlrev_b32_e32 v28, 16, v23
	v_fmac_f32_e32 v27, v26, v26
	v_and_b32_e32 v29, 0xffff0000, v23
	v_fmac_f32_e32 v27, v28, v28
	v_lshlrev_b32_e32 v30, 16, v24
	v_fmac_f32_e32 v27, v29, v29
	v_and_b32_e32 v31, 0xffff0000, v24
	v_fmac_f32_e32 v27, v30, v30
	v_lshlrev_b32_e32 v32, 16, v25
	v_fmac_f32_e32 v27, v31, v31
	v_and_b32_e32 v33, 0xffff0000, v25
	v_fmac_f32_e32 v27, v32, v32
	v_fmac_f32_e32 v27, v33, v33
	ds_write_b128 v35, v[22:25] offset:16
	v_add_f32_e32 v30, v34, v27
	ds_read_b128 v[22:25], v1 offset:64
	ds_read_b128 v[26:29], v1 offset:80
	v_lshlrev_b32_e32 v31, 16, v86
	s_waitcnt lgkmcnt(0)
	v_add_f32_e32 v22, v22, v31
	v_and_b32_e32 v31, 0xffff0000, v86
	v_add_f32_e32 v23, v23, v31
	v_cvt_pk_bf16_f32 v22, v22, v23
	v_lshlrev_b32_e32 v23, 16, v87
	v_add_f32_e32 v23, v24, v23
	v_and_b32_e32 v24, 0xffff0000, v87
	v_add_f32_e32 v24, v25, v24
	v_cvt_pk_bf16_f32 v23, v23, v24
	v_lshlrev_b32_e32 v24, 16, v88
	v_and_b32_e32 v25, 0xffff0000, v88
	v_add_f32_e32 v24, v26, v24
	v_add_f32_e32 v25, v27, v25
	v_cvt_pk_bf16_f32 v24, v24, v25
	v_lshlrev_b32_e32 v25, 16, v89
	v_and_b32_e32 v26, 0xffff0000, v89
	v_add_f32_e32 v25, v28, v25
	v_add_f32_e32 v26, v29, v26
	v_and_b32_e32 v27, 0xffff0000, v22
	v_cvt_pk_bf16_f32 v25, v25, v26
	v_lshlrev_b32_e32 v26, 16, v22
	v_mul_f32_e32 v27, v27, v27
	v_lshlrev_b32_e32 v28, 16, v23
	v_fmac_f32_e32 v27, v26, v26
	v_and_b32_e32 v29, 0xffff0000, v23
	v_fmac_f32_e32 v27, v28, v28
	v_lshlrev_b32_e32 v31, 16, v24
	v_fmac_f32_e32 v27, v29, v29
	v_and_b32_e32 v32, 0xffff0000, v24
	v_fmac_f32_e32 v27, v31, v31
	v_lshlrev_b32_e32 v33, 16, v25
	v_fmac_f32_e32 v27, v32, v32
	v_and_b32_e32 v34, 0xffff0000, v25
	v_fmac_f32_e32 v27, v33, v33
	v_fmac_f32_e32 v27, v34, v34
	ds_write_b128 v35, v[22:25] offset:32
	v_add_f32_e32 v30, v30, v27
	ds_read_b128 v[22:25], v1 offset:96
	ds_read_b128 v[26:29], v1 offset:112
	v_lshlrev_b32_e32 v31, 16, v70
	s_waitcnt lgkmcnt(0)
	v_add_f32_e32 v22, v22, v31
	v_and_b32_e32 v31, 0xffff0000, v70
	v_add_f32_e32 v23, v23, v31
	v_cvt_pk_bf16_f32 v22, v22, v23
	v_lshlrev_b32_e32 v23, 16, v71
	v_add_f32_e32 v23, v24, v23
	v_and_b32_e32 v24, 0xffff0000, v71
	v_add_f32_e32 v24, v25, v24
	v_cvt_pk_bf16_f32 v23, v23, v24
	v_lshlrev_b32_e32 v24, 16, v72
	v_and_b32_e32 v25, 0xffff0000, v72
	v_add_f32_e32 v24, v26, v24
	v_add_f32_e32 v25, v27, v25
	v_cvt_pk_bf16_f32 v24, v24, v25
	v_lshlrev_b32_e32 v25, 16, v73
	v_and_b32_e32 v26, 0xffff0000, v73
	v_add_f32_e32 v25, v28, v25
	v_add_f32_e32 v26, v29, v26
	v_and_b32_e32 v27, 0xffff0000, v22
	v_cvt_pk_bf16_f32 v25, v25, v26
	v_lshlrev_b32_e32 v26, 16, v22
	v_mul_f32_e32 v27, v27, v27
	v_lshlrev_b32_e32 v28, 16, v23
	v_fmac_f32_e32 v27, v26, v26
	v_and_b32_e32 v29, 0xffff0000, v23
	v_fmac_f32_e32 v27, v28, v28
	v_lshlrev_b32_e32 v31, 16, v24
	v_fmac_f32_e32 v27, v29, v29
	v_and_b32_e32 v32, 0xffff0000, v24
	v_fmac_f32_e32 v27, v31, v31
	v_lshlrev_b32_e32 v33, 16, v25
	v_fmac_f32_e32 v27, v32, v32
	v_and_b32_e32 v34, 0xffff0000, v25
	v_fmac_f32_e32 v27, v33, v33
	v_fmac_f32_e32 v27, v34, v34
	ds_write_b128 v35, v[22:25] offset:48
	v_add_f32_e32 v30, v30, v27
	ds_read_b128 v[22:25], v1 offset:128
	ds_read_b128 v[26:29], v1 offset:144
	v_lshlrev_b32_e32 v31, 16, v14
	v_and_b32_e32 v14, 0xffff0000, v14
	s_waitcnt lgkmcnt(0)
	v_add_f32_e32 v22, v22, v31
	v_add_f32_e32 v14, v23, v14
	v_cvt_pk_bf16_f32 v14, v22, v14
	v_lshlrev_b32_e32 v22, 16, v15
	v_and_b32_e32 v15, 0xffff0000, v15
	v_add_f32_e32 v22, v24, v22
	v_add_f32_e32 v15, v25, v15
	v_cvt_pk_bf16_f32 v15, v22, v15
	v_lshlrev_b32_e32 v22, 16, v16
	v_and_b32_e32 v16, 0xffff0000, v16
	v_add_f32_e32 v22, v26, v22
	v_add_f32_e32 v16, v27, v16
	v_cvt_pk_bf16_f32 v16, v22, v16
	v_lshlrev_b32_e32 v22, 16, v17
	v_and_b32_e32 v17, 0xffff0000, v17
	v_add_f32_e32 v22, v28, v22
	v_add_f32_e32 v17, v29, v17
	v_and_b32_e32 v23, 0xffff0000, v14
	v_cvt_pk_bf16_f32 v17, v22, v17
	v_lshlrev_b32_e32 v22, 16, v14
	v_mul_f32_e32 v23, v23, v23
	v_lshlrev_b32_e32 v24, 16, v15
	v_fmac_f32_e32 v23, v22, v22
	v_and_b32_e32 v25, 0xffff0000, v15
	v_fmac_f32_e32 v23, v24, v24
	v_lshlrev_b32_e32 v26, 16, v16
	v_fmac_f32_e32 v23, v25, v25
	v_and_b32_e32 v27, 0xffff0000, v16
	v_fmac_f32_e32 v23, v26, v26
	v_lshlrev_b32_e32 v28, 16, v17
	v_fmac_f32_e32 v23, v27, v27
	v_and_b32_e32 v29, 0xffff0000, v17
	v_fmac_f32_e32 v23, v28, v28
	v_fmac_f32_e32 v23, v29, v29
	ds_write_b128 v35, v[14:17] offset:64
	v_add_f32_e32 v26, v30, v23
	ds_read_b128 v[14:17], v1 offset:160
	ds_read_b128 v[22:25], v1 offset:176
	v_lshlrev_b32_e32 v27, 16, v10
	v_and_b32_e32 v10, 0xffff0000, v10
	s_waitcnt lgkmcnt(0)
	v_add_f32_e32 v14, v14, v27
	v_add_f32_e32 v10, v15, v10
	v_cvt_pk_bf16_f32 v10, v14, v10
	v_lshlrev_b32_e32 v14, 16, v11
	v_and_b32_e32 v11, 0xffff0000, v11
	v_add_f32_e32 v14, v16, v14
	v_add_f32_e32 v11, v17, v11
	v_cvt_pk_bf16_f32 v11, v14, v11
	v_lshlrev_b32_e32 v14, 16, v12
	v_and_b32_e32 v12, 0xffff0000, v12
	v_add_f32_e32 v14, v22, v14
	v_add_f32_e32 v12, v23, v12
	v_cvt_pk_bf16_f32 v12, v14, v12
	v_lshlrev_b32_e32 v14, 16, v13
	v_and_b32_e32 v13, 0xffff0000, v13
	v_add_f32_e32 v14, v24, v14
	v_add_f32_e32 v13, v25, v13
	v_and_b32_e32 v15, 0xffff0000, v10
	v_cvt_pk_bf16_f32 v13, v14, v13
	v_lshlrev_b32_e32 v14, 16, v10
	v_mul_f32_e32 v15, v15, v15
	v_lshlrev_b32_e32 v16, 16, v11
	v_fmac_f32_e32 v15, v14, v14
	v_and_b32_e32 v17, 0xffff0000, v11
	v_fmac_f32_e32 v15, v16, v16
	v_lshlrev_b32_e32 v22, 16, v12
	v_fmac_f32_e32 v15, v17, v17
	v_and_b32_e32 v23, 0xffff0000, v12
	v_fmac_f32_e32 v15, v22, v22
	v_lshlrev_b32_e32 v24, 16, v13
	v_fmac_f32_e32 v15, v23, v23
	v_and_b32_e32 v25, 0xffff0000, v13
	v_fmac_f32_e32 v15, v24, v24
	v_fmac_f32_e32 v15, v25, v25
	ds_write_b128 v35, v[10:13] offset:80
	v_add_f32_e32 v22, v26, v15
	ds_read_b128 v[10:13], v1 offset:192
	ds_read_b128 v[14:17], v1 offset:208
	v_lshlrev_b32_e32 v23, 16, v6
	v_and_b32_e32 v6, 0xffff0000, v6
	s_waitcnt lgkmcnt(0)
	v_add_f32_e32 v10, v10, v23
	v_add_f32_e32 v6, v11, v6
	v_cvt_pk_bf16_f32 v6, v10, v6
	v_lshlrev_b32_e32 v10, 16, v7
	v_and_b32_e32 v7, 0xffff0000, v7
	v_add_f32_e32 v10, v12, v10
	v_add_f32_e32 v7, v13, v7
	v_cvt_pk_bf16_f32 v7, v10, v7
	v_lshlrev_b32_e32 v10, 16, v8
	v_and_b32_e32 v8, 0xffff0000, v8
	v_add_f32_e32 v10, v14, v10
	v_add_f32_e32 v8, v15, v8
	v_cvt_pk_bf16_f32 v8, v10, v8
	v_lshlrev_b32_e32 v10, 16, v9
	v_and_b32_e32 v9, 0xffff0000, v9
	v_add_f32_e32 v10, v16, v10
	v_add_f32_e32 v9, v17, v9
	v_and_b32_e32 v11, 0xffff0000, v6
	v_cvt_pk_bf16_f32 v9, v10, v9
	v_lshlrev_b32_e32 v10, 16, v6
	v_mul_f32_e32 v11, v11, v11
	v_lshlrev_b32_e32 v12, 16, v7
	v_fmac_f32_e32 v11, v10, v10
	v_and_b32_e32 v13, 0xffff0000, v7
	v_fmac_f32_e32 v11, v12, v12
	v_lshlrev_b32_e32 v14, 16, v8
	v_fmac_f32_e32 v11, v13, v13
	v_and_b32_e32 v15, 0xffff0000, v8
	v_fmac_f32_e32 v11, v14, v14
	v_lshlrev_b32_e32 v16, 16, v9
	v_fmac_f32_e32 v11, v15, v15
	v_and_b32_e32 v17, 0xffff0000, v9
	v_fmac_f32_e32 v11, v16, v16
	v_fmac_f32_e32 v11, v17, v17
	ds_write_b128 v35, v[6:9] offset:96
	v_add_f32_e32 v14, v22, v11
	ds_read_b128 v[6:9], v1 offset:224
	ds_read_b128 v[10:13], v1 offset:240
	v_lshlrev_b32_e32 v1, 16, v2
	v_and_b32_e32 v2, 0xffff0000, v2
	s_waitcnt lgkmcnt(0)
	v_add_f32_e32 v1, v6, v1
	v_add_f32_e32 v2, v7, v2
	v_cvt_pk_bf16_f32 v2, v1, v2
	v_lshlrev_b32_e32 v1, 16, v3
	v_and_b32_e32 v3, 0xffff0000, v3
	v_add_f32_e32 v1, v8, v1
	v_add_f32_e32 v3, v9, v3
	v_cvt_pk_bf16_f32 v3, v1, v3
	v_lshlrev_b32_e32 v1, 16, v4
	v_and_b32_e32 v4, 0xffff0000, v4
	v_add_f32_e32 v1, v10, v1
	v_add_f32_e32 v4, v11, v4
	v_cvt_pk_bf16_f32 v4, v1, v4
	v_lshlrev_b32_e32 v1, 16, v5
	v_and_b32_e32 v5, 0xffff0000, v5
	v_add_f32_e32 v1, v12, v1
	v_add_f32_e32 v5, v13, v5
	v_and_b32_e32 v6, 0xffff0000, v2
	v_cvt_pk_bf16_f32 v5, v1, v5
	v_lshlrev_b32_e32 v1, 16, v2
	v_mul_f32_e32 v6, v6, v6
	v_lshlrev_b32_e32 v7, 16, v3
	v_fmac_f32_e32 v6, v1, v1
	v_and_b32_e32 v8, 0xffff0000, v3
	v_fmac_f32_e32 v6, v7, v7
	v_lshlrev_b32_e32 v9, 16, v4
	v_fmac_f32_e32 v6, v8, v8
	v_and_b32_e32 v10, 0xffff0000, v4
	v_fmac_f32_e32 v6, v9, v9
	v_lshlrev_b32_e32 v11, 16, v5
	v_fmac_f32_e32 v6, v10, v10
	v_and_b32_e32 v12, 0xffff0000, v5
	v_fmac_f32_e32 v6, v11, v11
	ds_write_b128 v35, v[2:5] offset:112
	v_and_b32_e32 v7, 63, v170
	v_lshrrev_b32_e32 v13, 3, v7
	v_sub_u32_e32 v13, v13, v7
	v_and_b32_e32 v7, 7, v7
	v_lshlrev_b32_e32 v7, 4, v7
	v_mul_i32_i24_e32 v2, 0x800, v13
	v_add_u32_e32 v2, v2, v7
	v_mul_i32_i24_e32 v13, 0x110, v13
	v_add3_u32 v13, v13, v7, v35
	s_waitcnt lgkmcnt(0)
	ds_read_b128 v[8:11], v13 offset:0
	v_mov_b32_e32 v4, v2
	v_ashrrev_i32_e32 v5, 31, v4
	v_lshl_add_u64 v[16:17], v[4:5], 0, v[20:21]
	s_waitcnt lgkmcnt(0)
	global_store_dwordx4 v[16:17], v[8:11], off offset:128
	ds_read_b128 v[24:27], v13 offset:2176
	v_add_u32_e32 v4, 0x4000, v2
	v_ashrrev_i32_e32 v5, 31, v4
	v_lshl_add_u64 v[16:17], v[4:5], 0, v[20:21]
	s_waitcnt lgkmcnt(0)
	global_store_dwordx4 v[16:17], v[24:27], off offset:128
	ds_read_b128 v[8:11], v13 offset:4352
	v_add_u32_e32 v4, 0x8000, v2
	v_ashrrev_i32_e32 v5, 31, v4
	v_lshl_add_u64 v[16:17], v[4:5], 0, v[20:21]
	s_waitcnt lgkmcnt(0)
	global_store_dwordx4 v[16:17], v[8:11], off offset:128
	ds_read_b128 v[24:27], v13 offset:6528
	v_add_u32_e32 v4, 0xc000, v2
	v_ashrrev_i32_e32 v5, 31, v4
	v_lshl_add_u64 v[16:17], v[4:5], 0, v[20:21]
	s_waitcnt lgkmcnt(0)
	global_store_dwordx4 v[16:17], v[24:27], off offset:128
	ds_read_b128 v[8:11], v13 offset:8704
	v_add_u32_e32 v4, 0x10000, v2
	v_ashrrev_i32_e32 v5, 31, v4
	v_lshl_add_u64 v[16:17], v[4:5], 0, v[20:21]
	s_waitcnt lgkmcnt(0)
	global_store_dwordx4 v[16:17], v[8:11], off offset:128
	ds_read_b128 v[24:27], v13 offset:10880
	v_add_u32_e32 v4, 0x14000, v2
	v_ashrrev_i32_e32 v5, 31, v4
	v_lshl_add_u64 v[16:17], v[4:5], 0, v[20:21]
	s_waitcnt lgkmcnt(0)
	global_store_dwordx4 v[16:17], v[24:27], off offset:128
	ds_read_b128 v[8:11], v13 offset:13056
	v_add_u32_e32 v4, 0x18000, v2
	v_ashrrev_i32_e32 v5, 31, v4
	v_lshl_add_u64 v[16:17], v[4:5], 0, v[20:21]
	s_waitcnt lgkmcnt(0)
	global_store_dwordx4 v[16:17], v[8:11], off offset:128
	ds_read_b128 v[24:27], v13 offset:15232
	v_add_u32_e32 v4, 0x1c000, v2
	v_ashrrev_i32_e32 v5, 31, v4
	v_lshl_add_u64 v[16:17], v[4:5], 0, v[20:21]
	s_waitcnt lgkmcnt(0)
	global_store_dwordx4 v[16:17], v[24:27], off offset:128
	v_fmac_f32_e32 v6, v12, v12
	v_add_f32_e32 v1, v14, v6
	v_lshlrev_b64 v[2:3], 6, v[18:19]
	v_lshl_add_u64 v[2:3], s[6:7], 0, v[2:3]
	v_lshl_add_u64 v[2:3], v[2:3], 0, s[18:19]
	flat_store_dword v[2:3], v1 offset:4
	s_branch .LBB0_342

.LBB0_465:
	s_mul_i32 s17, s5, 0x6000
	s_add_i32 s25, s17, 0xffffa000
	s_cmp_lg_u32 s5, 0
	s_cselect_b32 s25, s25, 0xc000
	v_add_u32_e32 v151, s25, v145
	v_add_u32_e32 v153, 0x1000, v151
	v_readfirstlane_b32 s25, v151
	s_waitcnt vmcnt(6)
	s_barrier
	v_lshl_add_u64 v[154:155], v[140:141], 0, s[18:19]
	s_mov_b32 m0, s25
	v_readfirstlane_b32 s25, v153
	v_add_u32_e32 v153, 0x2000, v151
	global_load_lds_dwordx4 v[154:155], off
	v_lshl_add_u64 v[154:155], v[138:139], 0, s[18:19]
	s_mov_b32 m0, s25
	v_readfirstlane_b32 s25, v153
	v_add_u32_e32 v153, 0x3000, v151
	global_load_lds_dwordx4 v[154:155], off
	v_lshl_add_u64 v[154:155], v[136:137], 0, s[18:19]
	s_mov_b32 m0, s25
	v_readfirstlane_b32 s25, v153
	v_add_u32_e32 v153, 0x4000, v151
	global_load_lds_dwordx4 v[154:155], off
	v_lshl_add_u64 v[154:155], v[134:135], 0, s[18:19]
	s_mov_b32 m0, s25
	v_readfirstlane_b32 s25, v153
	v_add_u32_e32 v151, 0x5000, v151
	global_load_lds_dwordx4 v[154:155], off
	v_lshl_add_u64 v[154:155], v[132:133], 0, s[18:19]
	s_mov_b32 m0, s25
	v_readfirstlane_b32 s25, v151
	global_load_lds_dwordx4 v[154:155], off
	v_lshl_add_u64 v[154:155], v[130:131], 0, s[18:19]
	s_mov_b32 m0, s25
	v_or_b32_e32 v151, s17, v149
	global_load_lds_dwordx4 v[154:155], off
	v_add_u32_e32 v151, v151, v147
	ds_read_b128 v[154:157], v151
	ds_read_b128 v[158:161], v151 offset:1024
	ds_read_b128 v[162:165], v151 offset:2048
	ds_read_b128 v[166:169], v151 offset:3072
	v_or_b32_e32 v151, s17, v144
	ds_read_b128 v[180:183], v151 offset:16384
	ds_read_b128 v[192:195], v151 offset:17408
	ds_read_b128 v[196:199], v151 offset:18432
	ds_read_b128 v[200:203], v151 offset:19456
	ds_read_b128 v[204:207], v151 offset:20480
	ds_read_b128 v[208:211], v151 offset:21504
	ds_read_b128 v[212:215], v151 offset:22528
	ds_read_b128 v[216:219], v151 offset:23552
	s_add_i32 s17, s5, 1
	s_waitcnt lgkmcnt(0)
	v_mfma_f32_16x16x32_bf16 v[126:129], v[154:157], v[180:183], v[126:129]
	s_cmp_lg_u32 s5, 2
	s_cselect_b32 s5, s17, 0
	s_add_u32 s18, s18, 64
	v_mfma_f32_16x16x32_bf16 v[114:117], v[158:161], v[180:183], v[114:117]
	s_addc_u32 s19, s19, 0
	s_cmpk_eq_i32 s18, 0x180
	v_mfma_f32_16x16x32_bf16 v[86:89], v[162:165], v[180:183], v[86:89]
	v_mfma_f32_16x16x32_bf16 v[54:57], v[166:169], v[180:183], v[54:57]
	v_mfma_f32_16x16x32_bf16 v[122:125], v[154:157], v[192:195], v[122:125]
	v_mfma_f32_16x16x32_bf16 v[102:105], v[158:161], v[192:195], v[102:105]
	v_mfma_f32_16x16x32_bf16 v[70:73], v[162:165], v[192:195], v[70:73]
	v_mfma_f32_16x16x32_bf16 v[38:41], v[166:169], v[192:195], v[38:41]
	v_mfma_f32_16x16x32_bf16 v[118:121], v[154:157], v[196:199], v[118:121]
	v_mfma_f32_16x16x32_bf16 v[90:93], v[158:161], v[196:199], v[90:93]
	v_mfma_f32_16x16x32_bf16 v[58:61], v[162:165], v[196:199], v[58:61]
	v_mfma_f32_16x16x32_bf16 v[26:29], v[166:169], v[196:199], v[26:29]
	v_mfma_f32_16x16x32_bf16 v[110:113], v[154:157], v[200:203], v[110:113]
	v_mfma_f32_16x16x32_bf16 v[78:81], v[158:161], v[200:203], v[78:81]
	v_mfma_f32_16x16x32_bf16 v[46:49], v[162:165], v[200:203], v[46:49]
	v_mfma_f32_16x16x32_bf16 v[18:21], v[166:169], v[200:203], v[18:21]
	v_mfma_f32_16x16x32_bf16 v[106:109], v[154:157], v[204:207], v[106:109]
	v_mfma_f32_16x16x32_bf16 v[74:77], v[158:161], v[204:207], v[74:77]
	v_mfma_f32_16x16x32_bf16 v[42:45], v[162:165], v[204:207], v[42:45]
	v_mfma_f32_16x16x32_bf16 v[14:17], v[166:169], v[204:207], v[14:17]
	v_mfma_f32_16x16x32_bf16 v[98:101], v[154:157], v[208:211], v[98:101]
	v_mfma_f32_16x16x32_bf16 v[66:69], v[158:161], v[208:211], v[66:69]
	v_mfma_f32_16x16x32_bf16 v[34:37], v[162:165], v[208:211], v[34:37]
	v_mfma_f32_16x16x32_bf16 v[10:13], v[166:169], v[208:211], v[10:13]
	v_mfma_f32_16x16x32_bf16 v[94:97], v[154:157], v[212:215], v[94:97]
	v_mfma_f32_16x16x32_bf16 v[62:65], v[158:161], v[212:215], v[62:65]
	v_mfma_f32_16x16x32_bf16 v[30:33], v[162:165], v[212:215], v[30:33]
	v_mfma_f32_16x16x32_bf16 v[6:9], v[166:169], v[212:215], v[6:9]
	v_mfma_f32_16x16x32_bf16 v[82:85], v[154:157], v[216:219], v[82:85]
	v_mfma_f32_16x16x32_bf16 v[50:53], v[158:161], v[216:219], v[50:53]
	v_mfma_f32_16x16x32_bf16 v[22:25], v[162:165], v[216:219], v[22:25]
	v_mfma_f32_16x16x32_bf16 v[2:5], v[166:169], v[216:219], v[2:5]
	s_cbranch_scc0 .LBB0_465
	s_waitcnt vmcnt(6)
	s_barrier
	v_add_u32_e32 v145, v149, v147
	ds_read_b128 v[130:133], v145
	ds_read_b128 v[134:137], v145 offset:1024
	ds_read_b128 v[138:141], v145 offset:2048
	ds_read_b128 v[154:157], v145 offset:3072
	ds_read_b128 v[158:161], v144 offset:16384
	ds_read_b128 v[162:165], v144 offset:17408
	ds_read_b128 v[166:169], v144 offset:18432
	ds_read_b128 v[180:183], v144 offset:19456
	ds_read_b128 v[192:195], v144 offset:20480
	ds_read_b128 v[196:199], v144 offset:21504
	ds_read_b128 v[200:203], v144 offset:22528
	ds_read_b128 v[204:207], v144 offset:23552
	s_waitcnt vmcnt(0)
	s_barrier
	s_waitcnt lgkmcnt(0)
	v_mfma_f32_16x16x32_bf16 v[126:129], v[130:133], v[158:161], v[126:129]
	s_lshl_b32 s18, s16, 7
	s_ashr_i32 s19, s18, 31
	s_lshl_b64 s[18:19], s[18:19], 1
	v_mfma_f32_16x16x32_bf16 v[114:117], v[134:137], v[158:161], v[114:117]
	v_and_b32_e32 v1, 0xfffffc0, v1
	v_lshl_or_b32 v1, v143, 2, v1
	v_mul_lo_u32 v1, v1, s33
	v_mfma_f32_16x16x32_bf16 v[86:89], v[138:141], v[158:161], v[86:89]
	v_lshl_or_b32 v1, v142, 2, v1
	s_lshl_b32 s16, s16, 1
	s_ashr_i32 s17, s16, 31
	v_mfma_f32_16x16x32_bf16 v[54:57], v[154:157], v[158:161], v[54:57]
	s_lshl_b64 s[16:17], s[16:17], 2
	s_add_i32 s24, s24, 1
	v_mfma_f32_16x16x32_bf16 v[122:125], v[130:133], v[162:165], v[122:125]
	v_mfma_f32_16x16x32_bf16 v[102:105], v[134:137], v[162:165], v[102:105]
	v_mfma_f32_16x16x32_bf16 v[70:73], v[138:141], v[162:165], v[70:73]
	v_mfma_f32_16x16x32_bf16 v[38:41], v[154:157], v[162:165], v[38:41]
	v_mfma_f32_16x16x32_bf16 v[118:121], v[130:133], v[166:169], v[118:121]
	v_mfma_f32_16x16x32_bf16 v[90:93], v[134:137], v[166:169], v[90:93]
	v_mfma_f32_16x16x32_bf16 v[58:61], v[138:141], v[166:169], v[58:61]
	v_mfma_f32_16x16x32_bf16 v[26:29], v[154:157], v[166:169], v[26:29]
	v_mfma_f32_16x16x32_bf16 v[110:113], v[130:133], v[180:183], v[110:113]
	v_mfma_f32_16x16x32_bf16 v[78:81], v[134:137], v[180:183], v[78:81]
	v_mfma_f32_16x16x32_bf16 v[46:49], v[138:141], v[180:183], v[46:49]
	v_mfma_f32_16x16x32_bf16 v[18:21], v[154:157], v[180:183], v[18:21]
	v_mfma_f32_16x16x32_bf16 v[106:109], v[130:133], v[192:195], v[106:109]
	v_mfma_f32_16x16x32_bf16 v[74:77], v[134:137], v[192:195], v[74:77]
	v_mfma_f32_16x16x32_bf16 v[42:45], v[138:141], v[192:195], v[42:45]
	v_mfma_f32_16x16x32_bf16 v[14:17], v[154:157], v[192:195], v[14:17]
	v_mfma_f32_16x16x32_bf16 v[98:101], v[130:133], v[196:199], v[98:101]
	v_mfma_f32_16x16x32_bf16 v[66:69], v[134:137], v[196:199], v[66:69]
	v_mfma_f32_16x16x32_bf16 v[34:37], v[138:141], v[196:199], v[34:37]
	v_mfma_f32_16x16x32_bf16 v[10:13], v[154:157], v[196:199], v[10:13]
	v_mfma_f32_16x16x32_bf16 v[94:97], v[130:133], v[200:203], v[94:97]
	v_mfma_f32_16x16x32_bf16 v[158:161], v[134:137], v[200:203], v[62:65]
	v_mfma_f32_16x16x32_bf16 v[162:165], v[138:141], v[200:203], v[30:33]
	v_mfma_f32_16x16x32_bf16 v[6:9], v[154:157], v[200:203], v[6:9]
	v_mfma_f32_16x16x32_bf16 v[82:85], v[130:133], v[204:207], v[82:85]
	v_mfma_f32_16x16x32_bf16 v[50:53], v[134:137], v[204:207], v[50:53]
	v_mfma_f32_16x16x32_bf16 v[130:133], v[138:141], v[204:207], v[22:25]
	v_mfma_f32_16x16x32_bf16 v[2:5], v[154:157], v[204:207], v[2:5]
	ds_read_b128 v[134:137], v145 offset:24576
	ds_read_b128 v[138:141], v145 offset:25600
	ds_read_b128 v[154:157], v145 offset:26624
	ds_read_b128 v[166:169], v145 offset:27648
	ds_read_b128 v[22:25], v144 offset:40960
	ds_read_b128 v[30:33], v144 offset:41984
	ds_read_b128 v[62:65], v144 offset:43008
	ds_read_b128 v[180:183], v144 offset:44032
	ds_read_b128 v[192:195], v144 offset:45056
	ds_read_b128 v[196:199], v144 offset:46080
	ds_read_b128 v[200:203], v144 offset:47104
	ds_read_b128 v[204:207], v144 offset:48128
	s_waitcnt lgkmcnt(0)
	v_mfma_f32_16x16x32_bf16 v[224:227], v[166:169], v[30:33], v[38:41]
	v_mfma_f32_16x16x32_bf16 v[38:41], v[154:157], v[196:199], v[34:37]
	v_mfma_f32_16x16x32_bf16 v[34:37], v[166:169], v[204:207], v[2:5]
	s_nop 2
	v_mov_b32_e32 v2, v170
	v_mfma_f32_16x16x32_bf16 v[208:211], v[138:141], v[22:25], v[114:117]
	v_add_u32_e32 v2, s4, v2
	v_ashrrev_i32_e32 v3, 31, v2
	v_lshlrev_b64 v[2:3], 11, v[2:3]
	v_lshl_add_u64 v[2:3], s[8:9], 0, v[2:3]
	v_lshl_add_u64 v[2:3], v[2:3], 0, s[18:19]
	v_mfma_f32_16x16x32_bf16 v[212:215], v[166:169], v[22:25], v[54:57]
	v_mfma_f32_16x16x32_bf16 v[216:219], v[134:137], v[30:33], v[122:125]
	v_mfma_f32_16x16x32_bf16 v[220:223], v[138:141], v[30:33], v[102:105]
	v_mfma_f32_16x16x32_bf16 v[228:231], v[134:137], v[62:65], v[118:121]
	v_mfma_f32_16x16x32_bf16 v[90:93], v[138:141], v[62:65], v[90:93]
	v_mfma_f32_16x16x32_bf16 v[232:235], v[154:157], v[62:65], v[58:61]
	v_mfma_f32_16x16x32_bf16 v[236:239], v[166:169], v[62:65], v[26:29]
	v_mfma_f32_16x16x32_bf16 v[240:243], v[134:137], v[180:183], v[110:113]
	v_mfma_f32_16x16x32_bf16 v[244:247], v[138:141], v[180:183], v[78:81]
	v_mfma_f32_16x16x32_bf16 v[248:251], v[154:157], v[180:183], v[46:49]
	v_mfma_f32_16x16x32_bf16 v[62:65], v[134:137], v[192:195], v[106:109]
	v_mfma_f32_16x16x32_bf16 v[46:49], v[138:141], v[192:195], v[74:77]
	v_mfma_f32_16x16x32_bf16 v[74:77], v[134:137], v[196:199], v[98:101]
	v_mfma_f32_16x16x32_bf16 v[54:57], v[138:141], v[196:199], v[66:69]
	v_mfma_f32_16x16x32_bf16 v[58:61], v[138:141], v[200:203], v[158:161]
	v_mfma_f32_16x16x32_bf16 v[66:69], v[138:141], v[204:207], v[50:53]
	flat_load_dwordx4 v[138:141], v[2:3]
	flat_load_dwordx4 v[122:125], v[2:3] offset:16
	flat_load_dwordx4 v[118:121], v[2:3] offset:32
	flat_load_dwordx4 v[114:117], v[2:3] offset:48
	flat_load_dwordx4 v[110:113], v[2:3] offset:64
	flat_load_dwordx4 v[106:109], v[2:3] offset:80
	flat_load_dwordx4 v[102:105], v[2:3] offset:96
	flat_load_dwordx4 v[98:101], v[2:3] offset:112
	s_waitcnt vmcnt(0) lgkmcnt(0)
	s_barrier
	v_mfma_f32_16x16x32_bf16 v[126:129], v[134:137], v[22:25], v[126:129]
	s_nop 7
	ds_write2_b32 v1, v126, v216 offset1:16
	ds_write2_b32 v1, v127, v217 offset0:68 offset1:84
	ds_write2_b32 v1, v128, v218 offset0:136 offset1:152
	ds_write2_b32 v1, v129, v219 offset0:204 offset1:220
	ds_write2_b32 v1, v228, v240 offset0:32 offset1:48
	ds_write2_b32 v1, v229, v241 offset0:100 offset1:116
	ds_write2_b32 v1, v230, v242 offset0:168 offset1:184
	ds_write2_b32 v1, v231, v243 offset0:236 offset1:252
	v_mfma_f32_16x16x32_bf16 v[86:89], v[154:157], v[22:25], v[86:89]
	v_mfma_f32_16x16x32_bf16 v[70:73], v[154:157], v[30:33], v[70:73]
	v_mfma_f32_16x16x32_bf16 v[180:183], v[166:169], v[180:183], v[18:21]
	v_mfma_f32_16x16x32_bf16 v[78:81], v[134:137], v[200:203], v[94:97]
	v_mfma_f32_16x16x32_bf16 v[82:85], v[134:137], v[204:207], v[82:85]
	v_add_u32_e32 v135, 0x3000, v1
	v_add_u32_e32 v134, 0x3400, v1
	v_mov_b32_e32 v136, v170
	v_mfma_f32_16x16x32_bf16 v[50:53], v[154:157], v[204:207], v[130:133]
	v_lshlrev_b32_e32 v137, 16, v138
	s_nop 1
	v_add_u32_e32 v130, 0x1000, v1
	v_add_u32_e32 v131, 0x1400, v1
	v_add_u32_e32 v132, 0x2000, v1
	v_add_u32_e32 v133, 0x2400, v1
	ds_write2_b32 v130, v208, v220 offset0:64 offset1:80
	ds_write2_b32 v130, v209, v221 offset0:132 offset1:148
	ds_write2_b32 v130, v210, v222 offset0:200 offset1:216
	ds_write2_b32 v131, v211, v223 offset0:12 offset1:28
	ds_write2_b32 v130, v90, v244 offset0:96 offset1:112
	ds_write2_b32 v130, v91, v245 offset0:164 offset1:180
	ds_write2_b32 v130, v92, v246 offset0:232 offset1:248
	ds_write2_b32 v131, v93, v247 offset0:44 offset1:60
	ds_write2_b32 v132, v86, v70 offset0:128 offset1:144
	ds_write2_b32 v132, v87, v71 offset0:196 offset1:212
	ds_write2_b32 v133, v88, v72 offset0:8 offset1:24
	ds_write2_b32 v133, v89, v73 offset0:76 offset1:92
	ds_write2_b32 v132, v232, v248 offset0:160 offset1:176
	ds_write2_b32 v132, v233, v249 offset0:228 offset1:244
	ds_write2_b32 v133, v234, v250 offset0:40 offset1:56
	ds_write2_b32 v133, v235, v251 offset0:108 offset1:124
	ds_write2_b32 v135, v212, v224 offset0:192 offset1:208
	ds_write2_b32 v134, v213, v225 offset0:4 offset1:20
	ds_write2_b32 v134, v214, v226 offset0:72 offset1:88
	ds_write2_b32 v134, v215, v227 offset0:140 offset1:156
	ds_write2_b32 v135, v236, v180 offset0:224 offset1:240
	ds_write2_b32 v134, v237, v181 offset0:36 offset1:52
	ds_write2_b32 v134, v238, v182 offset0:104 offset1:120
	ds_write2_b32 v134, v239, v183 offset0:172 offset1:188
	s_waitcnt lgkmcnt(0)
	s_barrier
	v_mfma_f32_16x16x32_bf16 v[30:33], v[154:157], v[192:195], v[42:45]
	v_add_u32_e32 v126, s4, v136
	v_ashrrev_i32_e32 v127, 31, v126
	v_lshlrev_b64 v[2:3], 11, v[126:127]
	v_lshl_add_u64 v[2:3], s[8:9], 0, v[2:3]
	v_lshl_add_u64 v[128:129], v[2:3], 0, s[18:19]
	v_mul_lo_u32 v136, v136, s33
	v_mfma_f32_16x16x32_bf16 v[18:21], v[166:169], v[192:195], v[14:17]
	v_and_b32_e32 v138, 0xffff0000, v138
	v_mfma_f32_16x16x32_bf16 v[22:25], v[166:169], v[196:199], v[10:13]
	v_mfma_f32_16x16x32_bf16 v[42:45], v[154:157], v[200:203], v[162:165]
	v_mfma_f32_16x16x32_bf16 v[26:29], v[166:169], v[200:203], v[6:9]
	flat_load_dwordx4 v[94:97], v[128:129] offset:128
	flat_load_dwordx4 v[90:93], v[128:129] offset:144
	flat_load_dwordx4 v[86:89], v[128:129] offset:160
	flat_load_dwordx4 v[70:73], v[128:129] offset:176
	flat_load_dwordx4 v[14:17], v[128:129] offset:192
	flat_load_dwordx4 v[10:13], v[128:129] offset:208
	flat_load_dwordx4 v[6:9], v[128:129] offset:224
	flat_load_dwordx4 v[2:5], v[128:129] offset:240
	ds_read_b128 v[142:145], v136
	ds_read_b128 v[154:157], v136 offset:16
	s_waitcnt lgkmcnt(0)
	v_add_f32_e32 v137, v142, v137
	v_add_f32_e32 v138, v143, v138
	v_cvt_pk_bf16_f32 v138, v137, v138
	v_lshlrev_b32_e32 v137, 16, v139
	v_and_b32_e32 v139, 0xffff0000, v139
	v_add_f32_e32 v137, v144, v137
	v_add_f32_e32 v139, v145, v139
	v_cvt_pk_bf16_f32 v139, v137, v139
	v_lshlrev_b32_e32 v137, 16, v140
	v_and_b32_e32 v140, 0xffff0000, v140
	v_add_f32_e32 v137, v154, v137
	v_add_f32_e32 v140, v155, v140
	v_cvt_pk_bf16_f32 v140, v137, v140
	v_lshlrev_b32_e32 v137, 16, v141
	v_and_b32_e32 v141, 0xffff0000, v141
	v_add_f32_e32 v137, v156, v137
	v_add_f32_e32 v141, v157, v141
	v_and_b32_e32 v142, 0xffff0000, v138
	v_cvt_pk_bf16_f32 v141, v137, v141
	v_lshlrev_b32_e32 v137, 16, v138
	v_mul_f32_e32 v153, v142, v142
	v_lshlrev_b32_e32 v143, 16, v139
	v_fmac_f32_e32 v153, v137, v137
	v_and_b32_e32 v144, 0xffff0000, v139
	v_fmac_f32_e32 v153, v143, v143
	v_lshlrev_b32_e32 v145, 16, v140
	v_fmac_f32_e32 v153, v144, v144
	ds_write_b128 v136, v[138:141]
	v_and_b32_e32 v147, 0xffff0000, v140
	v_lshlrev_b32_e32 v149, 16, v141
	v_and_b32_e32 v151, 0xffff0000, v141
	v_fmac_f32_e32 v153, v145, v145
	ds_read_b128 v[138:141], v136 offset:32
	ds_read_b128 v[142:145], v136 offset:48
	v_lshlrev_b32_e32 v137, 16, v122
	v_and_b32_e32 v122, 0xffff0000, v122
	v_fmac_f32_e32 v153, v147, v147
	s_waitcnt lgkmcnt(0)
	v_add_f32_e32 v137, v138, v137
	v_add_f32_e32 v122, v139, v122
	v_cvt_pk_bf16_f32 v122, v137, v122
	v_lshlrev_b32_e32 v137, 16, v123
	v_and_b32_e32 v123, 0xffff0000, v123
	v_add_f32_e32 v137, v140, v137
	v_add_f32_e32 v123, v141, v123
	v_cvt_pk_bf16_f32 v123, v137, v123
	v_lshlrev_b32_e32 v137, 16, v124
	v_and_b32_e32 v124, 0xffff0000, v124
	v_add_f32_e32 v137, v142, v137
	v_add_f32_e32 v124, v143, v124
	v_cvt_pk_bf16_f32 v124, v137, v124
	v_lshlrev_b32_e32 v137, 16, v125
	v_and_b32_e32 v125, 0xffff0000, v125
	v_add_f32_e32 v137, v144, v137
	v_add_f32_e32 v125, v145, v125
	v_and_b32_e32 v138, 0xffff0000, v122
	v_cvt_pk_bf16_f32 v125, v137, v125
	v_lshlrev_b32_e32 v137, 16, v122
	v_mul_f32_e32 v138, v138, v138
	v_lshlrev_b32_e32 v139, 16, v123
	v_fmac_f32_e32 v138, v137, v137
	v_and_b32_e32 v140, 0xffff0000, v123
	v_fmac_f32_e32 v138, v139, v139
	v_lshlrev_b32_e32 v141, 16, v124
	v_fmac_f32_e32 v138, v140, v140
	v_and_b32_e32 v142, 0xffff0000, v124
	v_fmac_f32_e32 v138, v141, v141
	v_lshlrev_b32_e32 v143, 16, v125
	v_fmac_f32_e32 v138, v142, v142
	v_fmac_f32_e32 v153, v149, v149
	v_and_b32_e32 v144, 0xffff0000, v125
	v_fmac_f32_e32 v138, v143, v143
	v_fmac_f32_e32 v153, v151, v151
	v_fmac_f32_e32 v138, v144, v144
	ds_write_b128 v136, v[122:125] offset:16
	v_add_f32_e32 v137, v153, v138
	ds_read_b128 v[122:125], v136 offset:64
	ds_read_b128 v[138:141], v136 offset:80
	v_lshlrev_b32_e32 v142, 16, v118
	v_and_b32_e32 v118, 0xffff0000, v118
	s_waitcnt lgkmcnt(0)
	v_add_f32_e32 v122, v122, v142
	v_add_f32_e32 v118, v123, v118
	v_cvt_pk_bf16_f32 v118, v122, v118
	v_lshlrev_b32_e32 v122, 16, v119
	v_and_b32_e32 v119, 0xffff0000, v119
	v_add_f32_e32 v122, v124, v122
	v_add_f32_e32 v119, v125, v119
	v_cvt_pk_bf16_f32 v119, v122, v119
	v_lshlrev_b32_e32 v122, 16, v120
	v_and_b32_e32 v120, 0xffff0000, v120
	v_add_f32_e32 v122, v138, v122
	v_add_f32_e32 v120, v139, v120
	v_cvt_pk_bf16_f32 v120, v122, v120
	v_lshlrev_b32_e32 v122, 16, v121
	v_and_b32_e32 v121, 0xffff0000, v121
	v_add_f32_e32 v122, v140, v122
	v_add_f32_e32 v121, v141, v121
	v_and_b32_e32 v123, 0xffff0000, v118
	v_cvt_pk_bf16_f32 v121, v122, v121
	v_lshlrev_b32_e32 v122, 16, v118
	v_mul_f32_e32 v123, v123, v123
	v_lshlrev_b32_e32 v124, 16, v119
	v_fmac_f32_e32 v123, v122, v122
	v_and_b32_e32 v125, 0xffff0000, v119
	v_fmac_f32_e32 v123, v124, v124
	v_lshlrev_b32_e32 v138, 16, v120
	v_fmac_f32_e32 v123, v125, v125
	v_and_b32_e32 v139, 0xffff0000, v120
	v_fmac_f32_e32 v123, v138, v138
	v_lshlrev_b32_e32 v140, 16, v121
	v_fmac_f32_e32 v123, v139, v139
	v_and_b32_e32 v141, 0xffff0000, v121
	v_fmac_f32_e32 v123, v140, v140
	v_fmac_f32_e32 v123, v141, v141
	ds_write_b128 v136, v[118:121] offset:32
	v_add_f32_e32 v137, v137, v123
	ds_read_b128 v[118:121], v136 offset:96
	ds_read_b128 v[122:125], v136 offset:112
	v_lshlrev_b32_e32 v138, 16, v114
	v_and_b32_e32 v114, 0xffff0000, v114
	s_waitcnt lgkmcnt(0)
	v_add_f32_e32 v118, v118, v138
	v_add_f32_e32 v114, v119, v114
	v_cvt_pk_bf16_f32 v114, v118, v114
	v_lshlrev_b32_e32 v118, 16, v115
	v_and_b32_e32 v115, 0xffff0000, v115
	v_add_f32_e32 v118, v120, v118
	v_add_f32_e32 v115, v121, v115
	v_cvt_pk_bf16_f32 v115, v118, v115
	v_lshlrev_b32_e32 v118, 16, v116
	v_and_b32_e32 v116, 0xffff0000, v116
	v_add_f32_e32 v118, v122, v118
	v_add_f32_e32 v116, v123, v116
	v_cvt_pk_bf16_f32 v116, v118, v116
	v_lshlrev_b32_e32 v118, 16, v117
	v_and_b32_e32 v117, 0xffff0000, v117
	v_add_f32_e32 v118, v124, v118
	v_add_f32_e32 v117, v125, v117
	v_and_b32_e32 v119, 0xffff0000, v114
	v_cvt_pk_bf16_f32 v117, v118, v117
	v_lshlrev_b32_e32 v118, 16, v114
	v_mul_f32_e32 v119, v119, v119
	v_lshlrev_b32_e32 v120, 16, v115
	v_fmac_f32_e32 v119, v118, v118
	v_and_b32_e32 v121, 0xffff0000, v115
	v_fmac_f32_e32 v119, v120, v120
	v_lshlrev_b32_e32 v122, 16, v116
	v_fmac_f32_e32 v119, v121, v121
	v_and_b32_e32 v123, 0xffff0000, v116
	v_fmac_f32_e32 v119, v122, v122
	v_lshlrev_b32_e32 v124, 16, v117
	v_fmac_f32_e32 v119, v123, v123
	v_and_b32_e32 v125, 0xffff0000, v117
	v_fmac_f32_e32 v119, v124, v124
	v_fmac_f32_e32 v119, v125, v125
	ds_write_b128 v136, v[114:117] offset:48
	v_add_f32_e32 v122, v137, v119
	ds_read_b128 v[114:117], v136 offset:128
	ds_read_b128 v[118:121], v136 offset:144
	v_lshlrev_b32_e32 v123, 16, v110
	v_and_b32_e32 v110, 0xffff0000, v110
	s_waitcnt lgkmcnt(0)
	v_add_f32_e32 v114, v114, v123
	v_add_f32_e32 v110, v115, v110
	v_cvt_pk_bf16_f32 v110, v114, v110
	v_lshlrev_b32_e32 v114, 16, v111
	v_and_b32_e32 v111, 0xffff0000, v111
	v_add_f32_e32 v114, v116, v114
	v_add_f32_e32 v111, v117, v111
	v_cvt_pk_bf16_f32 v111, v114, v111
	v_lshlrev_b32_e32 v114, 16, v112
	v_and_b32_e32 v112, 0xffff0000, v112
	v_add_f32_e32 v114, v118, v114
	v_add_f32_e32 v112, v119, v112
	v_cvt_pk_bf16_f32 v112, v114, v112
	v_lshlrev_b32_e32 v114, 16, v113
	v_and_b32_e32 v113, 0xffff0000, v113
	v_add_f32_e32 v114, v120, v114
	v_add_f32_e32 v113, v121, v113
	v_and_b32_e32 v115, 0xffff0000, v110
	v_cvt_pk_bf16_f32 v113, v114, v113
	v_lshlrev_b32_e32 v114, 16, v110
	v_mul_f32_e32 v115, v115, v115
	v_lshlrev_b32_e32 v116, 16, v111
	v_fmac_f32_e32 v115, v114, v114
	v_and_b32_e32 v117, 0xffff0000, v111
	v_fmac_f32_e32 v115, v116, v116
	v_lshlrev_b32_e32 v118, 16, v112
	v_fmac_f32_e32 v115, v117, v117
	v_and_b32_e32 v119, 0xffff0000, v112
	v_fmac_f32_e32 v115, v118, v118
	v_lshlrev_b32_e32 v120, 16, v113
	v_fmac_f32_e32 v115, v119, v119
	v_and_b32_e32 v121, 0xffff0000, v113
	v_fmac_f32_e32 v115, v120, v120
	v_fmac_f32_e32 v115, v121, v121
	ds_write_b128 v136, v[110:113] offset:64
	v_add_f32_e32 v118, v122, v115
	ds_read_b128 v[110:113], v136 offset:160
	ds_read_b128 v[114:117], v136 offset:176
	v_lshlrev_b32_e32 v119, 16, v106
	v_and_b32_e32 v106, 0xffff0000, v106
	s_waitcnt lgkmcnt(0)
	v_add_f32_e32 v110, v110, v119
	v_add_f32_e32 v106, v111, v106
	v_cvt_pk_bf16_f32 v106, v110, v106
	v_lshlrev_b32_e32 v110, 16, v107
	v_and_b32_e32 v107, 0xffff0000, v107
	v_add_f32_e32 v110, v112, v110
	v_add_f32_e32 v107, v113, v107
	v_cvt_pk_bf16_f32 v107, v110, v107
	v_lshlrev_b32_e32 v110, 16, v108
	v_and_b32_e32 v108, 0xffff0000, v108
	v_add_f32_e32 v110, v114, v110
	v_add_f32_e32 v108, v115, v108
	v_cvt_pk_bf16_f32 v108, v110, v108
	v_lshlrev_b32_e32 v110, 16, v109
	v_and_b32_e32 v109, 0xffff0000, v109
	v_add_f32_e32 v110, v116, v110
	v_add_f32_e32 v109, v117, v109
	v_and_b32_e32 v111, 0xffff0000, v106
	v_cvt_pk_bf16_f32 v109, v110, v109
	v_lshlrev_b32_e32 v110, 16, v106
	v_mul_f32_e32 v111, v111, v111
	v_lshlrev_b32_e32 v112, 16, v107
	v_fmac_f32_e32 v111, v110, v110
	v_and_b32_e32 v113, 0xffff0000, v107
	v_fmac_f32_e32 v111, v112, v112
	v_lshlrev_b32_e32 v114, 16, v108
	v_fmac_f32_e32 v111, v113, v113
	v_and_b32_e32 v115, 0xffff0000, v108
	v_fmac_f32_e32 v111, v114, v114
	v_lshlrev_b32_e32 v116, 16, v109
	v_fmac_f32_e32 v111, v115, v115
	v_and_b32_e32 v117, 0xffff0000, v109
	v_fmac_f32_e32 v111, v116, v116
	v_fmac_f32_e32 v111, v117, v117
	ds_write_b128 v136, v[106:109] offset:80
	v_add_f32_e32 v114, v118, v111
	ds_read_b128 v[106:109], v136 offset:192
	ds_read_b128 v[110:113], v136 offset:208
	v_lshlrev_b32_e32 v115, 16, v102
	v_and_b32_e32 v102, 0xffff0000, v102
	s_waitcnt lgkmcnt(0)
	v_add_f32_e32 v106, v106, v115
	v_add_f32_e32 v102, v107, v102
	v_cvt_pk_bf16_f32 v102, v106, v102
	v_lshlrev_b32_e32 v106, 16, v103
	v_and_b32_e32 v103, 0xffff0000, v103
	v_add_f32_e32 v106, v108, v106
	v_add_f32_e32 v103, v109, v103
	v_cvt_pk_bf16_f32 v103, v106, v103
	v_lshlrev_b32_e32 v106, 16, v104
	v_and_b32_e32 v104, 0xffff0000, v104
	v_add_f32_e32 v106, v110, v106
	v_add_f32_e32 v104, v111, v104
	v_cvt_pk_bf16_f32 v104, v106, v104
	v_lshlrev_b32_e32 v106, 16, v105
	v_and_b32_e32 v105, 0xffff0000, v105
	v_add_f32_e32 v106, v112, v106
	v_add_f32_e32 v105, v113, v105
	v_and_b32_e32 v107, 0xffff0000, v102
	v_cvt_pk_bf16_f32 v105, v106, v105
	v_lshlrev_b32_e32 v106, 16, v102
	v_mul_f32_e32 v107, v107, v107
	v_lshlrev_b32_e32 v108, 16, v103
	v_fmac_f32_e32 v107, v106, v106
	v_and_b32_e32 v109, 0xffff0000, v103
	v_fmac_f32_e32 v107, v108, v108
	v_lshlrev_b32_e32 v110, 16, v104
	v_fmac_f32_e32 v107, v109, v109
	v_and_b32_e32 v111, 0xffff0000, v104
	v_fmac_f32_e32 v107, v110, v110
	v_lshlrev_b32_e32 v112, 16, v105
	v_fmac_f32_e32 v107, v111, v111
	v_and_b32_e32 v113, 0xffff0000, v105
	v_fmac_f32_e32 v107, v112, v112
	v_fmac_f32_e32 v107, v113, v113
	ds_write_b128 v136, v[102:105] offset:96
	v_add_f32_e32 v110, v114, v107
	ds_read_b128 v[102:105], v136 offset:224
	ds_read_b128 v[106:109], v136 offset:240
	v_lshlrev_b32_e32 v111, 16, v98
	v_and_b32_e32 v98, 0xffff0000, v98
	s_waitcnt lgkmcnt(0)
	v_add_f32_e32 v102, v102, v111
	v_add_f32_e32 v98, v103, v98
	v_cvt_pk_bf16_f32 v98, v102, v98
	v_lshlrev_b32_e32 v102, 16, v99
	v_and_b32_e32 v99, 0xffff0000, v99
	v_add_f32_e32 v102, v104, v102
	v_add_f32_e32 v99, v105, v99
	v_cvt_pk_bf16_f32 v99, v102, v99
	v_lshlrev_b32_e32 v102, 16, v100
	v_and_b32_e32 v100, 0xffff0000, v100
	v_add_f32_e32 v102, v106, v102
	v_add_f32_e32 v100, v107, v100
	v_cvt_pk_bf16_f32 v100, v102, v100
	v_lshlrev_b32_e32 v102, 16, v101
	v_and_b32_e32 v101, 0xffff0000, v101
	v_add_f32_e32 v102, v108, v102
	v_add_f32_e32 v101, v109, v101
	v_and_b32_e32 v103, 0xffff0000, v98
	v_cvt_pk_bf16_f32 v101, v102, v101
	v_lshlrev_b32_e32 v102, 16, v98
	v_mul_f32_e32 v103, v103, v103
	v_lshlrev_b32_e32 v104, 16, v99
	v_fmac_f32_e32 v103, v102, v102
	v_and_b32_e32 v105, 0xffff0000, v99
	v_fmac_f32_e32 v103, v104, v104
	v_lshlrev_b32_e32 v106, 16, v100
	v_fmac_f32_e32 v103, v105, v105
	v_and_b32_e32 v107, 0xffff0000, v100
	v_fmac_f32_e32 v103, v106, v106
	v_lshlrev_b32_e32 v108, 16, v101
	v_fmac_f32_e32 v103, v107, v107
	v_and_b32_e32 v109, 0xffff0000, v101
	v_fmac_f32_e32 v103, v108, v108
	ds_write_b128 v136, v[98:101] offset:112
	v_and_b32_e32 v102, 63, v170
	v_lshrrev_b32_e32 v108, 3, v102
	v_sub_u32_e32 v108, v108, v102
	v_and_b32_e32 v102, 7, v102
	v_lshlrev_b32_e32 v102, 4, v102
	v_mul_i32_i24_e32 v98, 0x800, v108
	v_add_u32_e32 v98, v98, v102
	v_mul_i32_i24_e32 v108, 0x110, v108
	v_add3_u32 v108, v108, v102, v136
	s_waitcnt lgkmcnt(0)
	ds_read_b128 v[104:107], v108 offset:0
	v_mov_b32_e32 v100, v98
	v_ashrrev_i32_e32 v101, 31, v100
	v_lshl_add_u64 v[112:113], v[100:101], 0, v[128:129]
	s_waitcnt lgkmcnt(0)
	global_store_dwordx4 v[112:113], v[104:107], off
	ds_read_b128 v[116:119], v108 offset:2176
	v_add_u32_e32 v100, 0x4000, v98
	v_ashrrev_i32_e32 v101, 31, v100
	v_lshl_add_u64 v[112:113], v[100:101], 0, v[128:129]
	s_waitcnt lgkmcnt(0)
	global_store_dwordx4 v[112:113], v[116:119], off
	ds_read_b128 v[104:107], v108 offset:4352
	v_add_u32_e32 v100, 0x8000, v98
	v_ashrrev_i32_e32 v101, 31, v100
	v_lshl_add_u64 v[112:113], v[100:101], 0, v[128:129]
	s_waitcnt lgkmcnt(0)
	global_store_dwordx4 v[112:113], v[104:107], off
	ds_read_b128 v[116:119], v108 offset:6528
	v_add_u32_e32 v100, 0xc000, v98
	v_ashrrev_i32_e32 v101, 31, v100
	v_lshl_add_u64 v[112:113], v[100:101], 0, v[128:129]
	s_waitcnt lgkmcnt(0)
	global_store_dwordx4 v[112:113], v[116:119], off
	ds_read_b128 v[104:107], v108 offset:8704
	v_add_u32_e32 v100, 0x10000, v98
	v_ashrrev_i32_e32 v101, 31, v100
	v_lshl_add_u64 v[112:113], v[100:101], 0, v[128:129]
	s_waitcnt lgkmcnt(0)
	global_store_dwordx4 v[112:113], v[104:107], off
	ds_read_b128 v[116:119], v108 offset:10880
	v_add_u32_e32 v100, 0x14000, v98
	v_ashrrev_i32_e32 v101, 31, v100
	v_lshl_add_u64 v[112:113], v[100:101], 0, v[128:129]
	s_waitcnt lgkmcnt(0)
	global_store_dwordx4 v[112:113], v[116:119], off
	ds_read_b128 v[104:107], v108 offset:13056
	v_add_u32_e32 v100, 0x18000, v98
	v_ashrrev_i32_e32 v101, 31, v100
	v_lshl_add_u64 v[112:113], v[100:101], 0, v[128:129]
	s_waitcnt lgkmcnt(0)
	global_store_dwordx4 v[112:113], v[104:107], off
	ds_read_b128 v[116:119], v108 offset:15232
	v_add_u32_e32 v100, 0x1c000, v98
	v_ashrrev_i32_e32 v101, 31, v100
	v_lshl_add_u64 v[112:113], v[100:101], 0, v[128:129]
	s_waitcnt lgkmcnt(0)
	global_store_dwordx4 v[112:113], v[116:119], off
	v_fmac_f32_e32 v103, v109, v109
	v_add_f32_e32 v102, v110, v103
	v_lshlrev_b64 v[98:99], 6, v[126:127]
	v_lshl_add_u64 v[98:99], s[6:7], 0, v[98:99]
	v_lshl_add_u64 v[98:99], v[98:99], 0, s[16:17]
	flat_store_dword v[98:99], v102
	s_waitcnt lgkmcnt(0)
	s_barrier
	ds_write2_b32 v1, v62, v74 offset1:16
	ds_write2_b32 v1, v63, v75 offset0:68 offset1:84
	ds_write2_b32 v1, v64, v76 offset0:136 offset1:152
	ds_write2_b32 v1, v65, v77 offset0:204 offset1:220
	ds_write2_b32 v1, v78, v82 offset0:32 offset1:48
	ds_write2_b32 v1, v79, v83 offset0:100 offset1:116
	ds_write2_b32 v1, v80, v84 offset0:168 offset1:184
	ds_write2_b32 v1, v81, v85 offset0:236 offset1:252
	ds_write2_b32 v130, v46, v54 offset0:64 offset1:80
	ds_write2_b32 v130, v47, v55 offset0:132 offset1:148
	ds_write2_b32 v130, v48, v56 offset0:200 offset1:216
	ds_write2_b32 v131, v49, v57 offset0:12 offset1:28
	ds_write2_b32 v130, v58, v66 offset0:96 offset1:112
	ds_write2_b32 v130, v59, v67 offset0:164 offset1:180
	ds_write2_b32 v130, v60, v68 offset0:232 offset1:248
	ds_write2_b32 v131, v61, v69 offset0:44 offset1:60
	ds_write2_b32 v132, v30, v38 offset0:128 offset1:144
	ds_write2_b32 v132, v31, v39 offset0:196 offset1:212
	ds_write2_b32 v133, v32, v40 offset0:8 offset1:24
	ds_write2_b32 v133, v33, v41 offset0:76 offset1:92
	ds_write2_b32 v132, v42, v50 offset0:160 offset1:176
	ds_write2_b32 v132, v43, v51 offset0:228 offset1:244
	ds_write2_b32 v133, v44, v52 offset0:40 offset1:56
	ds_write2_b32 v133, v45, v53 offset0:108 offset1:124
	ds_write2_b32 v135, v18, v22 offset0:192 offset1:208
	ds_write2_b32 v134, v19, v23 offset0:4 offset1:20
	ds_write2_b32 v134, v20, v24 offset0:72 offset1:88
	ds_write2_b32 v134, v21, v25 offset0:140 offset1:156
	ds_write2_b32 v135, v26, v34 offset0:224 offset1:240
	ds_write2_b32 v134, v27, v35 offset0:36 offset1:52
	ds_write2_b32 v134, v28, v36 offset0:104 offset1:120
	ds_write2_b32 v134, v29, v37 offset0:172 offset1:188
	v_mov_b32_e32 v1, v170
	s_waitcnt lgkmcnt(0)
	s_barrier
	s_waitcnt vmcnt(0)
	v_lshlrev_b32_e32 v28, 16, v94
	v_add_u32_e32 v18, s4, v1
	v_ashrrev_i32_e32 v19, 31, v18
	v_lshlrev_b64 v[20:21], 11, v[18:19]
	v_lshl_add_u64 v[20:21], s[38:39], 0, v[20:21]
	v_mul_lo_u32 v1, v1, s33
	v_lshl_add_u64 v[32:33], v[20:21], 0, s[18:19]
	ds_read_b128 v[20:23], v1
	ds_read_b128 v[24:27], v1 offset:16
	s_mov_b64 s[4:5], 0
	s_waitcnt lgkmcnt(1)
	v_add_f32_e32 v20, v20, v28
	v_and_b32_e32 v28, 0xffff0000, v94
	v_add_f32_e32 v21, v21, v28
	v_cvt_pk_bf16_f32 v28, v20, v21
	v_and_b32_e32 v21, 0xffff0000, v95
	v_lshlrev_b32_e32 v20, 16, v95
	v_add_f32_e32 v21, v23, v21
	v_add_f32_e32 v20, v22, v20
	v_cvt_pk_bf16_f32 v29, v20, v21
	v_and_b32_e32 v21, 0xffff0000, v96
	v_lshlrev_b32_e32 v20, 16, v96
	s_waitcnt lgkmcnt(0)
	v_add_f32_e32 v21, v25, v21
	v_add_f32_e32 v20, v24, v20
	v_cvt_pk_bf16_f32 v30, v20, v21
	v_and_b32_e32 v21, 0xffff0000, v97
	v_lshlrev_b32_e32 v20, 16, v97
	v_add_f32_e32 v21, v27, v21
	v_add_f32_e32 v20, v26, v20
	v_cvt_pk_bf16_f32 v31, v20, v21
	v_and_b32_e32 v21, 0xffff0000, v28
	v_lshlrev_b32_e32 v20, 16, v28
	v_mul_f32_e32 v34, v21, v21
	v_lshlrev_b32_e32 v22, 16, v29
	v_fmac_f32_e32 v34, v20, v20
	v_and_b32_e32 v23, 0xffff0000, v29
	v_fmac_f32_e32 v34, v22, v22
	v_lshlrev_b32_e32 v24, 16, v30
	v_fmac_f32_e32 v34, v23, v23
	v_and_b32_e32 v25, 0xffff0000, v30
	v_fmac_f32_e32 v34, v24, v24
	v_add_co_u32_e32 v20, vcc, s90, v32
	v_lshlrev_b32_e32 v26, 16, v31
	v_fmac_f32_e32 v34, v25, v25
	v_addc_co_u32_e32 v21, vcc, 0, v33, vcc
	v_and_b32_e32 v27, 0xffff0000, v31
	v_fmac_f32_e32 v34, v26, v26
	v_mul_u32_u24_e32 v35, 0x110, v170
	ds_write_b128 v35, v[28:31]
	v_fmac_f32_e32 v34, v27, v27
	ds_read_b128 v[22:25], v1 offset:32
	ds_read_b128 v[26:29], v1 offset:48
	v_lshlrev_b32_e32 v30, 16, v90
	s_waitcnt lgkmcnt(0)
	v_add_f32_e32 v22, v22, v30
	v_and_b32_e32 v30, 0xffff0000, v90
	v_add_f32_e32 v23, v23, v30
	v_cvt_pk_bf16_f32 v22, v22, v23
	v_lshlrev_b32_e32 v23, 16, v91
	v_add_f32_e32 v23, v24, v23
	v_and_b32_e32 v24, 0xffff0000, v91
	v_add_f32_e32 v24, v25, v24
	v_cvt_pk_bf16_f32 v23, v23, v24
	v_lshlrev_b32_e32 v24, 16, v92
	v_and_b32_e32 v25, 0xffff0000, v92
	v_add_f32_e32 v24, v26, v24
	v_add_f32_e32 v25, v27, v25
	v_cvt_pk_bf16_f32 v24, v24, v25
	v_lshlrev_b32_e32 v25, 16, v93
	v_and_b32_e32 v26, 0xffff0000, v93
	v_add_f32_e32 v25, v28, v25
	v_add_f32_e32 v26, v29, v26
	v_and_b32_e32 v27, 0xffff0000, v22
	v_cvt_pk_bf16_f32 v25, v25, v26
	v_lshlrev_b32_e32 v26, 16, v22
	v_mul_f32_e32 v27, v27, v27
	v_lshlrev_b32_e32 v28, 16, v23
	v_fmac_f32_e32 v27, v26, v26
	v_and_b32_e32 v29, 0xffff0000, v23
	v_fmac_f32_e32 v27, v28, v28
	v_lshlrev_b32_e32 v30, 16, v24
	v_fmac_f32_e32 v27, v29, v29
	v_and_b32_e32 v31, 0xffff0000, v24
	v_fmac_f32_e32 v27, v30, v30
	v_lshlrev_b32_e32 v32, 16, v25
	v_fmac_f32_e32 v27, v31, v31
	v_and_b32_e32 v33, 0xffff0000, v25
	v_fmac_f32_e32 v27, v32, v32
	v_fmac_f32_e32 v27, v33, v33
	ds_write_b128 v35, v[22:25] offset:16
	v_add_f32_e32 v30, v34, v27
	ds_read_b128 v[22:25], v1 offset:64
	ds_read_b128 v[26:29], v1 offset:80
	v_lshlrev_b32_e32 v31, 16, v86
	s_waitcnt lgkmcnt(0)
	v_add_f32_e32 v22, v22, v31
	v_and_b32_e32 v31, 0xffff0000, v86
	v_add_f32_e32 v23, v23, v31
	v_cvt_pk_bf16_f32 v22, v22, v23
	v_lshlrev_b32_e32 v23, 16, v87
	v_add_f32_e32 v23, v24, v23
	v_and_b32_e32 v24, 0xffff0000, v87
	v_add_f32_e32 v24, v25, v24
	v_cvt_pk_bf16_f32 v23, v23, v24
	v_lshlrev_b32_e32 v24, 16, v88
	v_and_b32_e32 v25, 0xffff0000, v88
	v_add_f32_e32 v24, v26, v24
	v_add_f32_e32 v25, v27, v25
	v_cvt_pk_bf16_f32 v24, v24, v25
	v_lshlrev_b32_e32 v25, 16, v89
	v_and_b32_e32 v26, 0xffff0000, v89
	v_add_f32_e32 v25, v28, v25
	v_add_f32_e32 v26, v29, v26
	v_and_b32_e32 v27, 0xffff0000, v22
	v_cvt_pk_bf16_f32 v25, v25, v26
	v_lshlrev_b32_e32 v26, 16, v22
	v_mul_f32_e32 v27, v27, v27
	v_lshlrev_b32_e32 v28, 16, v23
	v_fmac_f32_e32 v27, v26, v26
	v_and_b32_e32 v29, 0xffff0000, v23
	v_fmac_f32_e32 v27, v28, v28
	v_lshlrev_b32_e32 v31, 16, v24
	v_fmac_f32_e32 v27, v29, v29
	v_and_b32_e32 v32, 0xffff0000, v24
	v_fmac_f32_e32 v27, v31, v31
	v_lshlrev_b32_e32 v33, 16, v25
	v_fmac_f32_e32 v27, v32, v32
	v_and_b32_e32 v34, 0xffff0000, v25
	v_fmac_f32_e32 v27, v33, v33
	v_fmac_f32_e32 v27, v34, v34
	ds_write_b128 v35, v[22:25] offset:32
	v_add_f32_e32 v30, v30, v27
	ds_read_b128 v[22:25], v1 offset:96
	ds_read_b128 v[26:29], v1 offset:112
	v_lshlrev_b32_e32 v31, 16, v70
	s_waitcnt lgkmcnt(0)
	v_add_f32_e32 v22, v22, v31
	v_and_b32_e32 v31, 0xffff0000, v70
	v_add_f32_e32 v23, v23, v31
	v_cvt_pk_bf16_f32 v22, v22, v23
	v_lshlrev_b32_e32 v23, 16, v71
	v_add_f32_e32 v23, v24, v23
	v_and_b32_e32 v24, 0xffff0000, v71
	v_add_f32_e32 v24, v25, v24
	v_cvt_pk_bf16_f32 v23, v23, v24
	v_lshlrev_b32_e32 v24, 16, v72
	v_and_b32_e32 v25, 0xffff0000, v72
	v_add_f32_e32 v24, v26, v24
	v_add_f32_e32 v25, v27, v25
	v_cvt_pk_bf16_f32 v24, v24, v25
	v_lshlrev_b32_e32 v25, 16, v73
	v_and_b32_e32 v26, 0xffff0000, v73
	v_add_f32_e32 v25, v28, v25
	v_add_f32_e32 v26, v29, v26
	v_and_b32_e32 v27, 0xffff0000, v22
	v_cvt_pk_bf16_f32 v25, v25, v26
	v_lshlrev_b32_e32 v26, 16, v22
	v_mul_f32_e32 v27, v27, v27
	v_lshlrev_b32_e32 v28, 16, v23
	v_fmac_f32_e32 v27, v26, v26
	v_and_b32_e32 v29, 0xffff0000, v23
	v_fmac_f32_e32 v27, v28, v28
	v_lshlrev_b32_e32 v31, 16, v24
	v_fmac_f32_e32 v27, v29, v29
	v_and_b32_e32 v32, 0xffff0000, v24
	v_fmac_f32_e32 v27, v31, v31
	v_lshlrev_b32_e32 v33, 16, v25
	v_fmac_f32_e32 v27, v32, v32
	v_and_b32_e32 v34, 0xffff0000, v25
	v_fmac_f32_e32 v27, v33, v33
	v_fmac_f32_e32 v27, v34, v34
	ds_write_b128 v35, v[22:25] offset:48
	v_add_f32_e32 v30, v30, v27
	ds_read_b128 v[22:25], v1 offset:128
	ds_read_b128 v[26:29], v1 offset:144
	v_lshlrev_b32_e32 v31, 16, v14
	v_and_b32_e32 v14, 0xffff0000, v14
	s_waitcnt lgkmcnt(0)
	v_add_f32_e32 v22, v22, v31
	v_add_f32_e32 v14, v23, v14
	v_cvt_pk_bf16_f32 v14, v22, v14
	v_lshlrev_b32_e32 v22, 16, v15
	v_and_b32_e32 v15, 0xffff0000, v15
	v_add_f32_e32 v22, v24, v22
	v_add_f32_e32 v15, v25, v15
	v_cvt_pk_bf16_f32 v15, v22, v15
	v_lshlrev_b32_e32 v22, 16, v16
	v_and_b32_e32 v16, 0xffff0000, v16
	v_add_f32_e32 v22, v26, v22
	v_add_f32_e32 v16, v27, v16
	v_cvt_pk_bf16_f32 v16, v22, v16
	v_lshlrev_b32_e32 v22, 16, v17
	v_and_b32_e32 v17, 0xffff0000, v17
	v_add_f32_e32 v22, v28, v22
	v_add_f32_e32 v17, v29, v17
	v_and_b32_e32 v23, 0xffff0000, v14
	v_cvt_pk_bf16_f32 v17, v22, v17
	v_lshlrev_b32_e32 v22, 16, v14
	v_mul_f32_e32 v23, v23, v23
	v_lshlrev_b32_e32 v24, 16, v15
	v_fmac_f32_e32 v23, v22, v22
	v_and_b32_e32 v25, 0xffff0000, v15
	v_fmac_f32_e32 v23, v24, v24
	v_lshlrev_b32_e32 v26, 16, v16
	v_fmac_f32_e32 v23, v25, v25
	v_and_b32_e32 v27, 0xffff0000, v16
	v_fmac_f32_e32 v23, v26, v26
	v_lshlrev_b32_e32 v28, 16, v17
	v_fmac_f32_e32 v23, v27, v27
	v_and_b32_e32 v29, 0xffff0000, v17
	v_fmac_f32_e32 v23, v28, v28
	v_fmac_f32_e32 v23, v29, v29
	ds_write_b128 v35, v[14:17] offset:64
	v_add_f32_e32 v26, v30, v23
	ds_read_b128 v[14:17], v1 offset:160
	ds_read_b128 v[22:25], v1 offset:176
	v_lshlrev_b32_e32 v27, 16, v10
	v_and_b32_e32 v10, 0xffff0000, v10
	s_waitcnt lgkmcnt(0)
	v_add_f32_e32 v14, v14, v27
	v_add_f32_e32 v10, v15, v10
	v_cvt_pk_bf16_f32 v10, v14, v10
	v_lshlrev_b32_e32 v14, 16, v11
	v_and_b32_e32 v11, 0xffff0000, v11
	v_add_f32_e32 v14, v16, v14
	v_add_f32_e32 v11, v17, v11
	v_cvt_pk_bf16_f32 v11, v14, v11
	v_lshlrev_b32_e32 v14, 16, v12
	v_and_b32_e32 v12, 0xffff0000, v12
	v_add_f32_e32 v14, v22, v14
	v_add_f32_e32 v12, v23, v12
	v_cvt_pk_bf16_f32 v12, v14, v12
	v_lshlrev_b32_e32 v14, 16, v13
	v_and_b32_e32 v13, 0xffff0000, v13
	v_add_f32_e32 v14, v24, v14
	v_add_f32_e32 v13, v25, v13
	v_and_b32_e32 v15, 0xffff0000, v10
	v_cvt_pk_bf16_f32 v13, v14, v13
	v_lshlrev_b32_e32 v14, 16, v10
	v_mul_f32_e32 v15, v15, v15
	v_lshlrev_b32_e32 v16, 16, v11
	v_fmac_f32_e32 v15, v14, v14
	v_and_b32_e32 v17, 0xffff0000, v11
	v_fmac_f32_e32 v15, v16, v16
	v_lshlrev_b32_e32 v22, 16, v12
	v_fmac_f32_e32 v15, v17, v17
	v_and_b32_e32 v23, 0xffff0000, v12
	v_fmac_f32_e32 v15, v22, v22
	v_lshlrev_b32_e32 v24, 16, v13
	v_fmac_f32_e32 v15, v23, v23
	v_and_b32_e32 v25, 0xffff0000, v13
	v_fmac_f32_e32 v15, v24, v24
	v_fmac_f32_e32 v15, v25, v25
	ds_write_b128 v35, v[10:13] offset:80
	v_add_f32_e32 v22, v26, v15
	ds_read_b128 v[10:13], v1 offset:192
	ds_read_b128 v[14:17], v1 offset:208
	v_lshlrev_b32_e32 v23, 16, v6
	v_and_b32_e32 v6, 0xffff0000, v6
	s_waitcnt lgkmcnt(0)
	v_add_f32_e32 v10, v10, v23
	v_add_f32_e32 v6, v11, v6
	v_cvt_pk_bf16_f32 v6, v10, v6
	v_lshlrev_b32_e32 v10, 16, v7
	v_and_b32_e32 v7, 0xffff0000, v7
	v_add_f32_e32 v10, v12, v10
	v_add_f32_e32 v7, v13, v7
	v_cvt_pk_bf16_f32 v7, v10, v7
	v_lshlrev_b32_e32 v10, 16, v8
	v_and_b32_e32 v8, 0xffff0000, v8
	v_add_f32_e32 v10, v14, v10
	v_add_f32_e32 v8, v15, v8
	v_cvt_pk_bf16_f32 v8, v10, v8
	v_lshlrev_b32_e32 v10, 16, v9
	v_and_b32_e32 v9, 0xffff0000, v9
	v_add_f32_e32 v10, v16, v10
	v_add_f32_e32 v9, v17, v9
	v_and_b32_e32 v11, 0xffff0000, v6
	v_cvt_pk_bf16_f32 v9, v10, v9
	v_lshlrev_b32_e32 v10, 16, v6
	v_mul_f32_e32 v11, v11, v11
	v_lshlrev_b32_e32 v12, 16, v7
	v_fmac_f32_e32 v11, v10, v10
	v_and_b32_e32 v13, 0xffff0000, v7
	v_fmac_f32_e32 v11, v12, v12
	v_lshlrev_b32_e32 v14, 16, v8
	v_fmac_f32_e32 v11, v13, v13
	v_and_b32_e32 v15, 0xffff0000, v8
	v_fmac_f32_e32 v11, v14, v14
	v_lshlrev_b32_e32 v16, 16, v9
	v_fmac_f32_e32 v11, v15, v15
	v_and_b32_e32 v17, 0xffff0000, v9
	v_fmac_f32_e32 v11, v16, v16
	v_fmac_f32_e32 v11, v17, v17
	ds_write_b128 v35, v[6:9] offset:96
	v_add_f32_e32 v14, v22, v11
	ds_read_b128 v[6:9], v1 offset:224
	ds_read_b128 v[10:13], v1 offset:240
	v_lshlrev_b32_e32 v1, 16, v2
	v_and_b32_e32 v2, 0xffff0000, v2
	s_waitcnt lgkmcnt(0)
	v_add_f32_e32 v1, v6, v1
	v_add_f32_e32 v2, v7, v2
	v_cvt_pk_bf16_f32 v2, v1, v2
	v_lshlrev_b32_e32 v1, 16, v3
	v_and_b32_e32 v3, 0xffff0000, v3
	v_add_f32_e32 v1, v8, v1
	v_add_f32_e32 v3, v9, v3
	v_cvt_pk_bf16_f32 v3, v1, v3
	v_lshlrev_b32_e32 v1, 16, v4
	v_and_b32_e32 v4, 0xffff0000, v4
	v_add_f32_e32 v1, v10, v1
	v_add_f32_e32 v4, v11, v4
	v_cvt_pk_bf16_f32 v4, v1, v4
	v_lshlrev_b32_e32 v1, 16, v5
	v_and_b32_e32 v5, 0xffff0000, v5
	v_add_f32_e32 v1, v12, v1
	v_add_f32_e32 v5, v13, v5
	v_and_b32_e32 v6, 0xffff0000, v2
	v_cvt_pk_bf16_f32 v5, v1, v5
	v_lshlrev_b32_e32 v1, 16, v2
	v_mul_f32_e32 v6, v6, v6
	v_lshlrev_b32_e32 v7, 16, v3
	v_fmac_f32_e32 v6, v1, v1
	v_and_b32_e32 v8, 0xffff0000, v3
	v_fmac_f32_e32 v6, v7, v7
	v_lshlrev_b32_e32 v9, 16, v4
	v_fmac_f32_e32 v6, v8, v8
	v_and_b32_e32 v10, 0xffff0000, v4
	v_fmac_f32_e32 v6, v9, v9
	v_lshlrev_b32_e32 v11, 16, v5
	v_fmac_f32_e32 v6, v10, v10
	v_and_b32_e32 v12, 0xffff0000, v5
	v_fmac_f32_e32 v6, v11, v11
	ds_write_b128 v35, v[2:5] offset:112
	v_and_b32_e32 v34, 63, v170
	v_lshrrev_b32_e32 v48, 3, v34
	v_sub_u32_e32 v48, v48, v34
	v_and_b32_e32 v34, 7, v34
	v_lshlrev_b32_e32 v34, 4, v34
	v_mul_i32_i24_e32 v2, 0x800, v48
	v_add_u32_e32 v2, v2, v34
	v_mul_i32_i24_e32 v48, 0x110, v48
	v_add3_u32 v48, v48, v34, v35
	s_waitcnt lgkmcnt(0)
	ds_read_b128 v[36:39], v48 offset:0
	v_mov_b32_e32 v44, v2
	v_ashrrev_i32_e32 v45, 31, v44
	v_lshl_add_u64 v[46:47], v[44:45], 0, v[20:21]
	s_waitcnt lgkmcnt(0)
	global_store_dwordx4 v[46:47], v[36:39], off offset:128
	ds_read_b128 v[40:43], v48 offset:2176
	v_add_u32_e32 v44, 0x4000, v2
	v_ashrrev_i32_e32 v45, 31, v44
	v_lshl_add_u64 v[46:47], v[44:45], 0, v[20:21]
	s_waitcnt lgkmcnt(0)
	global_store_dwordx4 v[46:47], v[40:43], off offset:128
	ds_read_b128 v[36:39], v48 offset:4352
	v_add_u32_e32 v44, 0x8000, v2
	v_ashrrev_i32_e32 v45, 31, v44
	v_lshl_add_u64 v[46:47], v[44:45], 0, v[20:21]
	s_waitcnt lgkmcnt(0)
	global_store_dwordx4 v[46:47], v[36:39], off offset:128
	ds_read_b128 v[40:43], v48 offset:6528
	v_add_u32_e32 v44, 0xc000, v2
	v_ashrrev_i32_e32 v45, 31, v44
	v_lshl_add_u64 v[46:47], v[44:45], 0, v[20:21]
	s_waitcnt lgkmcnt(0)
	global_store_dwordx4 v[46:47], v[40:43], off offset:128
	ds_read_b128 v[36:39], v48 offset:8704
	v_add_u32_e32 v44, 0x10000, v2
	v_ashrrev_i32_e32 v45, 31, v44
	v_lshl_add_u64 v[46:47], v[44:45], 0, v[20:21]
	s_waitcnt lgkmcnt(0)
	global_store_dwordx4 v[46:47], v[36:39], off offset:128
	ds_read_b128 v[40:43], v48 offset:10880
	v_add_u32_e32 v44, 0x14000, v2
	v_ashrrev_i32_e32 v45, 31, v44
	v_lshl_add_u64 v[46:47], v[44:45], 0, v[20:21]
	s_waitcnt lgkmcnt(0)
	global_store_dwordx4 v[46:47], v[40:43], off offset:128
	ds_read_b128 v[36:39], v48 offset:13056
	v_add_u32_e32 v44, 0x18000, v2
	v_ashrrev_i32_e32 v45, 31, v44
	v_lshl_add_u64 v[46:47], v[44:45], 0, v[20:21]
	s_waitcnt lgkmcnt(0)
	global_store_dwordx4 v[46:47], v[36:39], off offset:128
	ds_read_b128 v[40:43], v48 offset:15232
	v_add_u32_e32 v44, 0x1c000, v2
	v_ashrrev_i32_e32 v45, 31, v44
	v_lshl_add_u64 v[46:47], v[44:45], 0, v[20:21]
	s_waitcnt lgkmcnt(0)
	global_store_dwordx4 v[46:47], v[40:43], off offset:128
	v_fmac_f32_e32 v6, v12, v12
	v_add_f32_e32 v1, v14, v6
	v_lshlrev_b64 v[2:3], 6, v[18:19]
	v_lshl_add_u64 v[2:3], s[6:7], 0, v[2:3]
	v_lshl_add_u64 v[2:3], v[2:3], 0, s[16:17]
	flat_store_dword v[2:3], v1 offset:4
	s_branch .LBB0_457

.LBB0_516:
	s_mul_i32 s17, s5, 0x6000
	s_add_i32 s25, s17, 0xffffa000
	s_cmp_lg_u32 s5, 0
	s_cselect_b32 s25, s25, 0xc000
	v_add_u32_e32 v154, s25, v157
	v_add_u32_e32 v156, 0x1000, v154
	v_readfirstlane_b32 s25, v154
	s_waitcnt vmcnt(6)
	s_barrier
	v_lshl_add_u64 v[180:181], v[168:169], 0, s[18:19]
	s_mov_b32 m0, s25
	v_readfirstlane_b32 s25, v156
	v_add_u32_e32 v156, 0x2000, v154
	global_load_lds_dwordx4 v[180:181], off
	v_lshl_add_u64 v[180:181], v[166:167], 0, s[18:19]
	s_mov_b32 m0, s25
	v_readfirstlane_b32 s25, v156
	v_add_u32_e32 v156, 0x3000, v154
	global_load_lds_dwordx4 v[180:181], off
	v_lshl_add_u64 v[180:181], v[164:165], 0, s[18:19]
	s_mov_b32 m0, s25
	v_readfirstlane_b32 s25, v156
	v_add_u32_e32 v156, 0x4000, v154
	global_load_lds_dwordx4 v[180:181], off
	v_lshl_add_u64 v[180:181], v[162:163], 0, s[18:19]
	s_mov_b32 m0, s25
	v_readfirstlane_b32 s25, v156
	v_add_u32_e32 v154, 0x5000, v154
	global_load_lds_dwordx4 v[180:181], off
	v_lshl_add_u64 v[180:181], v[160:161], 0, s[18:19]
	s_mov_b32 m0, s25
	v_readfirstlane_b32 s25, v154
	global_load_lds_dwordx4 v[180:181], off
	v_lshl_add_u64 v[180:181], v[158:159], 0, s[18:19]
	s_mov_b32 m0, s25
	v_or_b32_e32 v154, s17, v155
	global_load_lds_dwordx4 v[180:181], off
	v_add_u32_e32 v154, v154, v153
	ds_read_b128 v[180:183], v154
	ds_read_b128 v[192:195], v154 offset:1024
	ds_read_b128 v[196:199], v154 offset:2048
	ds_read_b128 v[200:203], v154 offset:3072
	v_or_b32_e32 v154, s17, v151
	ds_read_b128 v[204:207], v154 offset:16384
	ds_read_b128 v[208:211], v154 offset:17408
	ds_read_b128 v[212:215], v154 offset:18432
	ds_read_b128 v[216:219], v154 offset:19456
	ds_read_b128 v[220:223], v154 offset:20480
	ds_read_b128 v[224:227], v154 offset:21504
	ds_read_b128 v[228:231], v154 offset:22528
	ds_read_b128 v[232:235], v154 offset:23552
	s_add_i32 s17, s5, 1
	s_waitcnt lgkmcnt(0)
	v_mfma_f32_16x16x32_bf16 v[142:145], v[180:183], v[204:207], v[142:145]
	s_cmp_lg_u32 s5, 2
	s_cselect_b32 s5, s17, 0
	s_add_u32 s18, s18, 64
	v_mfma_f32_16x16x32_bf16 v[134:137], v[192:195], v[204:207], v[134:137]
	s_addc_u32 s19, s19, 0
	s_cmpk_lg_i32 s18, 0x780
	v_mfma_f32_16x16x32_bf16 v[122:125], v[196:199], v[204:207], v[122:125]
	v_mfma_f32_16x16x32_bf16 v[114:117], v[200:203], v[204:207], v[114:117]
	v_mfma_f32_16x16x32_bf16 v[138:141], v[180:183], v[208:211], v[138:141]
	v_mfma_f32_16x16x32_bf16 v[130:133], v[192:195], v[208:211], v[130:133]
	v_mfma_f32_16x16x32_bf16 v[118:121], v[196:199], v[208:211], v[118:121]
	v_mfma_f32_16x16x32_bf16 v[78:81], v[200:203], v[208:211], v[78:81]
	v_mfma_f32_16x16x32_bf16 v[126:129], v[180:183], v[212:215], v[126:129]
	v_mfma_f32_16x16x32_bf16 v[110:113], v[192:195], v[212:215], v[110:113]
	v_mfma_f32_16x16x32_bf16 v[74:77], v[196:199], v[212:215], v[74:77]
	v_mfma_f32_16x16x32_bf16 v[46:49], v[200:203], v[212:215], v[46:49]
	v_mfma_f32_16x16x32_bf16 v[106:109], v[180:183], v[216:219], v[106:109]
	v_mfma_f32_16x16x32_bf16 v[66:69], v[192:195], v[216:219], v[66:69]
	v_mfma_f32_16x16x32_bf16 v[38:41], v[196:199], v[216:219], v[38:41]
	v_mfma_f32_16x16x32_bf16 v[18:21], v[200:203], v[216:219], v[18:21]
	v_mfma_f32_16x16x32_bf16 v[86:89], v[180:183], v[220:223], v[86:89]
	v_mfma_f32_16x16x32_bf16 v[58:61], v[192:195], v[220:223], v[58:61]
	v_mfma_f32_16x16x32_bf16 v[34:37], v[196:199], v[220:223], v[34:37]
	v_mfma_f32_16x16x32_bf16 v[14:17], v[200:203], v[220:223], v[14:17]
	v_mfma_f32_16x16x32_bf16 v[82:85], v[180:183], v[224:227], v[82:85]
	v_mfma_f32_16x16x32_bf16 v[54:57], v[192:195], v[224:227], v[54:57]
	v_mfma_f32_16x16x32_bf16 v[30:33], v[196:199], v[224:227], v[30:33]
	v_mfma_f32_16x16x32_bf16 v[10:13], v[200:203], v[224:227], v[10:13]
	v_mfma_f32_16x16x32_bf16 v[70:73], v[180:183], v[228:231], v[70:73]
	v_mfma_f32_16x16x32_bf16 v[50:53], v[192:195], v[228:231], v[50:53]
	v_mfma_f32_16x16x32_bf16 v[26:29], v[196:199], v[228:231], v[26:29]
	v_mfma_f32_16x16x32_bf16 v[6:9], v[200:203], v[228:231], v[6:9]
	v_mfma_f32_16x16x32_bf16 v[62:65], v[180:183], v[232:235], v[62:65]
	v_mfma_f32_16x16x32_bf16 v[42:45], v[192:195], v[232:235], v[42:45]
	v_mfma_f32_16x16x32_bf16 v[22:25], v[196:199], v[232:235], v[22:25]
	v_mfma_f32_16x16x32_bf16 v[2:5], v[200:203], v[232:235], v[2:5]
	s_cbranch_scc1 .LBB0_516
	s_waitcnt vmcnt(0)
	v_mov_b32_e32 v156, v103
	v_mov_b32_e32 v157, v104
	v_mov_b32_e32 v158, v99
	v_mov_b32_e32 v159, v100
	v_mov_b32_e32 v103, v105
	v_mov_b32_e32 v99, v101
	v_mov_b32_e32 v100, v95
	v_pk_add_f32 v[102:103], v[156:157], v[102:103]
	v_pk_add_f32 v[98:99], v[158:159], v[98:99]
	v_pk_add_f32 v[94:95], v[94:95], v[100:101]
	v_mov_b32_e32 v100, v97
	v_pk_add_f32 v[102:103], v[102:103], v[102:103] op_sel:[0,1] op_sel_hi:[1,0]
	v_pk_add_f32 v[98:99], v[98:99], v[98:99] op_sel:[0,1] op_sel_hi:[1,0]
	v_pk_add_f32 v[96:97], v[96:97], v[100:101]
	v_mov_b32_e32 v103, v90
	v_mov_b32_e32 v99, v91
	v_mov_b32_e32 v95, v92
	v_mov_b32_e32 v97, v93
	v_pk_add_f32 v[90:91], v[102:103], v[98:99]
	v_pk_add_f32 v[92:93], v[94:95], v[96:97]
	s_waitcnt vmcnt(6)
	s_barrier
	v_pk_add_f32 v[90:91], v[90:91], v[92:93]
	v_add_u32_e32 v103, v155, v153
	v_add_f32_e32 v90, v90, v91
	v_fmamk_f32 v90, v90, 0x3a800000, v172
	v_cmp_gt_f32_e32 vcc, s58, v90
	v_mul_f32_e32 v91, 0x4b800000, v90
	ds_read_b128 v[156:159], v151 offset:23552
	ds_read_b128 v[160:163], v151 offset:22528
	ds_read_b128 v[164:167], v151 offset:21504
	ds_read_b128 v[180:183], v151 offset:20480
	ds_read_b128 v[192:195], v151 offset:19456
	ds_read_b128 v[196:199], v151 offset:18432
	ds_read_b128 v[200:203], v151 offset:17408
	ds_read_b128 v[98:101], v151 offset:16384
	v_cndmask_b32_e32 v90, v90, v91, vcc
	v_rsq_f32_e32 v90, v90
	ds_read_b128 v[204:207], v103 offset:3072
	ds_read_b128 v[208:211], v103 offset:2048
	ds_read_b128 v[212:215], v103 offset:1024
	ds_read_b128 v[216:219], v103
	s_waitcnt lgkmcnt(0)
	v_mfma_f32_16x16x32_bf16 v[142:145], v[216:219], v[98:101], v[142:145]
	v_mul_f32_e32 v91, 0x45800000, v90
	v_cndmask_b32_e32 v90, v90, v91, vcc
	v_mul_f32_e32 v102, 0x3e38aa3b, v90
	v_mfma_f32_16x16x32_bf16 v[94:97], v[212:215], v[98:101], v[134:137]
	s_waitcnt vmcnt(0)
	s_barrier
	v_mfma_f32_16x16x32_bf16 v[90:93], v[208:211], v[98:101], v[122:125]
	v_and_b32_e32 v1, 0xfffffc0, v1
	v_lshl_or_b32 v1, v149, 2, v1
	v_mul_lo_u32 v1, v1, s33
	v_mfma_f32_16x16x32_bf16 v[98:101], v[204:207], v[98:101], v[114:117]
	v_lshl_or_b32 v1, v147, 2, v1
	s_lshl_b32 s16, s16, 7
	s_ashr_i32 s17, s16, 31
	v_mfma_f32_16x16x32_bf16 v[114:117], v[216:219], v[200:203], v[138:141]
	s_lshl_b64 s[16:17], s[16:17], 1
	s_add_i32 s24, s24, 1
	v_mfma_f32_16x16x32_bf16 v[122:125], v[212:215], v[200:203], v[130:133]
	v_mfma_f32_16x16x32_bf16 v[118:121], v[208:211], v[200:203], v[118:121]
	v_mfma_f32_16x16x32_bf16 v[78:81], v[204:207], v[200:203], v[78:81]
	v_mfma_f32_16x16x32_bf16 v[110:113], v[212:215], v[196:199], v[110:113]
	v_mfma_f32_16x16x32_bf16 v[66:69], v[212:215], v[192:195], v[66:69]
	v_mfma_f32_16x16x32_bf16 v[74:77], v[208:211], v[196:199], v[74:77]
	v_mfma_f32_16x16x32_bf16 v[38:41], v[208:211], v[192:195], v[38:41]
	v_mfma_f32_16x16x32_bf16 v[126:129], v[216:219], v[196:199], v[126:129]
	v_mfma_f32_16x16x32_bf16 v[46:49], v[204:207], v[196:199], v[46:49]
	v_mfma_f32_16x16x32_bf16 v[104:107], v[216:219], v[192:195], v[106:109]
	v_mfma_f32_16x16x32_bf16 v[18:21], v[204:207], v[192:195], v[18:21]
	v_mfma_f32_16x16x32_bf16 v[86:89], v[216:219], v[180:183], v[86:89]
	v_mfma_f32_16x16x32_bf16 v[58:61], v[212:215], v[180:183], v[58:61]
	v_mfma_f32_16x16x32_bf16 v[34:37], v[208:211], v[180:183], v[34:37]
	v_mfma_f32_16x16x32_bf16 v[130:133], v[204:207], v[180:183], v[14:17]
	v_mfma_f32_16x16x32_bf16 v[82:85], v[216:219], v[164:167], v[82:85]
	v_mfma_f32_16x16x32_bf16 v[134:137], v[212:215], v[164:167], v[54:57]
	v_mfma_f32_16x16x32_bf16 v[138:141], v[208:211], v[164:167], v[30:33]
	v_mfma_f32_16x16x32_bf16 v[10:13], v[204:207], v[164:167], v[10:13]
	v_mfma_f32_16x16x32_bf16 v[70:73], v[216:219], v[160:163], v[70:73]
	v_mfma_f32_16x16x32_bf16 v[50:53], v[212:215], v[160:163], v[50:53]
	v_mfma_f32_16x16x32_bf16 v[26:29], v[208:211], v[160:163], v[26:29]
	v_mfma_f32_16x16x32_bf16 v[160:163], v[204:207], v[160:163], v[6:9]
	v_mfma_f32_16x16x32_bf16 v[62:65], v[216:219], v[156:159], v[62:65]
	v_mfma_f32_16x16x32_bf16 v[164:167], v[212:215], v[156:159], v[42:45]
	v_mfma_f32_16x16x32_bf16 v[180:183], v[208:211], v[156:159], v[22:25]
	v_mfma_f32_16x16x32_bf16 v[154:157], v[204:207], v[156:159], v[2:5]
	ds_read_b128 v[192:195], v103 offset:24576
	ds_read_b128 v[196:199], v103 offset:25600
	ds_read_b128 v[200:203], v103 offset:26624
	ds_read_b128 v[204:207], v103 offset:27648
	ds_read_b128 v[2:5], v151 offset:40960
	ds_read_b128 v[6:9], v151 offset:41984
	ds_read_b128 v[14:17], v151 offset:43008
	ds_read_b128 v[22:25], v151 offset:44032
	ds_read_b128 v[42:45], v151 offset:45056
	ds_read_b128 v[208:211], v151 offset:46080
	ds_read_b128 v[212:215], v151 offset:47104
	ds_read_b128 v[216:219], v151 offset:48128
	s_waitcnt lgkmcnt(0)
	s_barrier
	v_mfma_f32_16x16x32_bf16 v[142:145], v[192:195], v[2:5], v[142:145]
	v_mfma_f32_16x16x32_bf16 v[94:97], v[196:199], v[2:5], v[94:97]
	v_mfma_f32_16x16x32_bf16 v[90:93], v[200:203], v[2:5], v[90:93]
	v_mfma_f32_16x16x32_bf16 v[98:101], v[204:207], v[2:5], v[98:101]
	v_mfma_f32_16x16x32_bf16 v[114:117], v[192:195], v[6:9], v[114:117]
	v_mfma_f32_16x16x32_bf16 v[122:125], v[196:199], v[6:9], v[122:125]
	v_mfma_f32_16x16x32_bf16 v[118:121], v[200:203], v[6:9], v[118:121]
	v_mfma_f32_16x16x32_bf16 v[78:81], v[204:207], v[6:9], v[78:81]
	v_mfma_f32_16x16x32_bf16 v[108:111], v[196:199], v[14:17], v[110:113]
	v_mfma_f32_16x16x32_bf16 v[224:227], v[196:199], v[22:25], v[66:69]
	v_mfma_f32_16x16x32_bf16 v[74:77], v[200:203], v[14:17], v[74:77]
	s_nop 1
	v_add_u32_e32 v66, 0x1000, v1
	v_add_u32_e32 v67, 0x1400, v1
	v_add_u32_e32 v68, 0x2000, v1
	v_mfma_f32_16x16x32_bf16 v[228:231], v[200:203], v[22:25], v[38:41]
	v_add_u32_e32 v69, 0x2400, v1
	v_mfma_f32_16x16x32_bf16 v[220:223], v[204:207], v[14:17], v[46:49]
	v_mfma_f32_16x16x32_bf16 v[232:235], v[204:207], v[22:25], v[18:21]
	v_mfma_f32_16x16x32_bf16 v[46:49], v[192:195], v[42:45], v[86:89]
	v_mfma_f32_16x16x32_bf16 v[30:33], v[196:199], v[42:45], v[58:61]
	s_nop 1
	v_mov_b32_e32 v88, v170
	v_mfma_f32_16x16x32_bf16 v[58:61], v[192:195], v[212:215], v[70:73]
	s_nop 2
	v_add_u32_e32 v70, 0x3000, v1
	v_add_u32_e32 v71, 0x3400, v1
	v_mfma_f32_16x16x32_bf16 v[126:129], v[192:195], v[14:17], v[126:129]
	v_mfma_f32_16x16x32_bf16 v[104:107], v[192:195], v[22:25], v[104:107]
	ds_write2_b32 v1, v142, v114 offset1:16
	ds_write2_b32 v1, v143, v115 offset0:68 offset1:84
	ds_write2_b32 v1, v144, v116 offset0:136 offset1:152
	ds_write2_b32 v1, v145, v117 offset0:204 offset1:220
	s_nop 3
	ds_write2_b32 v1, v126, v104 offset0:32 offset1:48
	ds_write2_b32 v1, v127, v105 offset0:100 offset1:116
	ds_write2_b32 v1, v128, v106 offset0:168 offset1:184
	ds_write2_b32 v1, v129, v107 offset0:236 offset1:252
	ds_write2_b32 v66, v94, v122 offset0:64 offset1:80
	ds_write2_b32 v66, v95, v123 offset0:132 offset1:148
	ds_write2_b32 v66, v96, v124 offset0:200 offset1:216
	ds_write2_b32 v67, v97, v125 offset0:12 offset1:28
	ds_write2_b32 v66, v108, v224 offset0:96 offset1:112
	ds_write2_b32 v66, v109, v225 offset0:164 offset1:180
	ds_write2_b32 v66, v110, v226 offset0:232 offset1:248
	ds_write2_b32 v67, v111, v227 offset0:44 offset1:60
	ds_write2_b32 v68, v90, v118 offset0:128 offset1:144
	ds_write2_b32 v68, v91, v119 offset0:196 offset1:212
	ds_write2_b32 v69, v92, v120 offset0:8 offset1:24
	ds_write2_b32 v69, v93, v121 offset0:76 offset1:92
	ds_write2_b32 v68, v74, v228 offset0:160 offset1:176
	ds_write2_b32 v68, v75, v229 offset0:228 offset1:244
	ds_write2_b32 v69, v76, v230 offset0:40 offset1:56
	ds_write2_b32 v69, v77, v231 offset0:108 offset1:124
	ds_write2_b32 v70, v98, v78 offset0:192 offset1:208
	ds_write2_b32 v71, v99, v79 offset0:4 offset1:20
	ds_write2_b32 v71, v100, v80 offset0:72 offset1:88
	ds_write2_b32 v71, v101, v81 offset0:140 offset1:156
	ds_write2_b32 v70, v220, v232 offset0:224 offset1:240
	ds_write2_b32 v71, v221, v233 offset0:36 offset1:52
	ds_write2_b32 v71, v222, v234 offset0:104 offset1:120
	ds_write2_b32 v71, v223, v235 offset0:172 offset1:188
	s_waitcnt lgkmcnt(0)
	s_barrier
	v_mfma_f32_16x16x32_bf16 v[54:57], v[192:195], v[208:211], v[82:85]
	v_mul_lo_u32 v89, v88, s33
	ds_read_b128 v[72:75], v89
	ds_read_b128 v[76:79], v89 offset:16
	ds_read_b128 v[80:83], v89 offset:32
	ds_read_b128 v[84:87], v89 offset:48
	s_waitcnt lgkmcnt(3)
	v_mul_f32_e32 v90, v102, v72
	v_mul_f32_e32 v91, v102, v73
	v_mul_f32_e32 v92, v102, v74
	v_mul_f32_e32 v93, v102, v75
	ds_read_b128 v[72:75], v89 offset:64
	v_mfma_f32_16x16x32_bf16 v[2:5], v[204:207], v[42:45], v[130:133]
	s_waitcnt lgkmcnt(3)
	v_mul_f32_e32 v94, v102, v76
	v_mul_f32_e32 v95, v102, v77
	v_mul_f32_e32 v78, v102, v78
	s_waitcnt lgkmcnt(0)
	v_mul_f32_e32 v96, v102, v72
	v_mul_f32_e32 v97, v102, v73
	v_mul_f32_e32 v98, v102, v74
	v_mul_f32_e32 v99, v102, v75
	ds_read_b128 v[72:75], v89 offset:80
	v_mfma_f32_16x16x32_bf16 v[38:41], v[196:199], v[208:211], v[134:137]
	v_mul_f32_e32 v79, v102, v79
	v_mul_f32_e32 v80, v102, v80
	v_mul_f32_e32 v81, v102, v81
	s_waitcnt lgkmcnt(0)
	v_mul_f32_e32 v100, v102, v72
	v_mul_f32_e32 v101, v102, v73
	v_mul_f32_e32 v103, v102, v74
	v_mul_f32_e32 v104, v102, v75
	ds_read_b128 v[72:75], v89 offset:96
	v_mfma_f32_16x16x32_bf16 v[22:25], v[200:203], v[208:211], v[138:141]
	v_mul_f32_e32 v82, v102, v82
	v_mul_f32_e32 v83, v102, v83
	v_mul_f32_e32 v84, v102, v84
	s_waitcnt lgkmcnt(0)
	v_mul_f32_e32 v105, v102, v72
	v_mul_f32_e32 v106, v102, v73
	v_mul_f32_e32 v107, v102, v74
	v_mul_f32_e32 v108, v102, v75
	ds_read_b128 v[72:75], v89 offset:112
	v_mul_f32_e32 v85, v102, v85
	v_mul_f32_e32 v86, v102, v86
	v_mul_f32_e32 v87, v102, v87
	v_mfma_f32_16x16x32_bf16 v[14:17], v[200:203], v[42:45], v[34:37]
	s_waitcnt lgkmcnt(0)
	v_mul_f32_e32 v109, v102, v72
	v_mul_f32_e32 v110, v102, v73
	v_mul_f32_e32 v111, v102, v74
	v_mul_f32_e32 v112, v102, v75
	ds_read_b128 v[72:75], v89 offset:128
	v_mfma_f32_16x16x32_bf16 v[6:9], v[204:207], v[208:211], v[10:13]
	s_waitcnt lgkmcnt(0)
	v_mul_f32_e32 v113, v102, v72
	v_mul_f32_e32 v114, v102, v73
	v_mul_f32_e32 v115, v102, v74
	v_mul_f32_e32 v116, v102, v75
	ds_read_b128 v[72:75], v89 offset:144
	v_mfma_f32_16x16x32_bf16 v[42:45], v[196:199], v[212:215], v[50:53]
	s_waitcnt lgkmcnt(0)
	v_mul_f32_e32 v117, v102, v72
	v_mul_f32_e32 v118, v102, v73
	v_mul_f32_e32 v119, v102, v74
	v_mul_f32_e32 v120, v102, v75
	ds_read_b128 v[72:75], v89 offset:160
	v_mfma_f32_16x16x32_bf16 v[26:29], v[200:203], v[212:215], v[26:29]
	s_waitcnt lgkmcnt(0)
	v_mul_f32_e32 v121, v102, v72
	v_mul_f32_e32 v122, v102, v73
	v_mul_f32_e32 v123, v102, v74
	v_mul_f32_e32 v124, v102, v75
	ds_read_b128 v[72:75], v89 offset:176
	v_mfma_f32_16x16x32_bf16 v[10:13], v[204:207], v[212:215], v[160:163]
	s_waitcnt lgkmcnt(0)
	v_mul_f32_e32 v125, v102, v72
	v_mul_f32_e32 v126, v102, v73
	v_mul_f32_e32 v127, v102, v74
	v_mul_f32_e32 v128, v102, v75
	ds_read_b128 v[72:75], v89 offset:192
	v_mfma_f32_16x16x32_bf16 v[62:65], v[192:195], v[216:219], v[62:65]
	s_waitcnt lgkmcnt(0)
	v_mul_f32_e32 v129, v102, v72
	v_mul_f32_e32 v130, v102, v73
	v_mul_f32_e32 v131, v102, v74
	v_mul_f32_e32 v132, v102, v75
	ds_read_b128 v[72:75], v89 offset:208
	v_mfma_f32_16x16x32_bf16 v[50:53], v[196:199], v[216:219], v[164:167]
	s_waitcnt lgkmcnt(0)
	v_mul_f32_e32 v133, v102, v72
	v_mul_f32_e32 v134, v102, v73
	v_mul_f32_e32 v135, v102, v74
	v_mul_f32_e32 v136, v102, v75
	ds_read_b128 v[72:75], v89 offset:224
	v_mfma_f32_16x16x32_bf16 v[34:37], v[200:203], v[216:219], v[180:183]
	s_waitcnt lgkmcnt(0)
	v_mul_f32_e32 v137, v102, v72
	v_mul_f32_e32 v138, v102, v73
	v_mul_f32_e32 v139, v102, v74
	v_mul_f32_e32 v140, v102, v75
	ds_read_b128 v[72:75], v89 offset:240
	v_mfma_f32_16x16x32_bf16 v[18:21], v[204:207], v[216:219], v[154:157]
	s_waitcnt lgkmcnt(0)
	v_mul_f32_e32 v89, v102, v72
	v_add_u32_e32 v72, s4, v88
	v_mul_f32_e32 v141, v102, v73
	v_ashrrev_i32_e32 v73, 31, v72
	v_lshlrev_b64 v[72:73], 9, v[72:73]
	v_lshl_add_u64 v[72:73], s[36:37], 0, v[72:73]
	v_mul_f32_e32 v142, v102, v74
	v_mul_f32_e32 v143, v102, v75
	v_lshl_add_u64 v[76:77], v[72:73], 0, s[16:17]
	v_cvt_pk_bf16_f32 v72, v90, v91
	v_cvt_pk_bf16_f32 v73, v92, v93
	v_cvt_pk_bf16_f32 v74, v94, v95
	v_cvt_pk_bf16_f32 v75, v78, v79
	v_mul_u32_u24_e32 v78, 0x110, v170
	ds_write_b128 v78, v[72:75]
	s_nop 1
	v_cvt_pk_bf16_f32 v72, v80, v81
	v_cvt_pk_bf16_f32 v73, v82, v83
	v_cvt_pk_bf16_f32 v74, v84, v85
	v_cvt_pk_bf16_f32 v75, v86, v87
	ds_write_b128 v78, v[72:75] offset:16
	s_nop 1
	v_cvt_pk_bf16_f32 v72, v96, v97
	v_cvt_pk_bf16_f32 v73, v98, v99
	v_cvt_pk_bf16_f32 v74, v100, v101
	v_cvt_pk_bf16_f32 v75, v103, v104
	ds_write_b128 v78, v[72:75] offset:32
	s_nop 1
	v_cvt_pk_bf16_f32 v72, v105, v106
	v_cvt_pk_bf16_f32 v73, v107, v108
	v_cvt_pk_bf16_f32 v74, v109, v110
	v_cvt_pk_bf16_f32 v75, v111, v112
	ds_write_b128 v78, v[72:75] offset:48
	s_nop 1
	v_cvt_pk_bf16_f32 v72, v113, v114
	v_cvt_pk_bf16_f32 v73, v115, v116
	v_cvt_pk_bf16_f32 v74, v117, v118
	v_cvt_pk_bf16_f32 v75, v119, v120
	ds_write_b128 v78, v[72:75] offset:64
	s_nop 1
	v_cvt_pk_bf16_f32 v72, v121, v122
	v_cvt_pk_bf16_f32 v73, v123, v124
	v_cvt_pk_bf16_f32 v74, v125, v126
	v_cvt_pk_bf16_f32 v75, v127, v128
	ds_write_b128 v78, v[72:75] offset:80
	s_nop 1
	v_cvt_pk_bf16_f32 v72, v129, v130
	v_cvt_pk_bf16_f32 v73, v131, v132
	v_cvt_pk_bf16_f32 v74, v133, v134
	v_cvt_pk_bf16_f32 v75, v135, v136
	ds_write_b128 v78, v[72:75] offset:96
	s_nop 1
	v_cvt_pk_bf16_f32 v72, v137, v138
	v_cvt_pk_bf16_f32 v73, v139, v140
	v_cvt_pk_bf16_f32 v74, v89, v141
	v_cvt_pk_bf16_f32 v75, v142, v143
	ds_write_b128 v78, v[72:75] offset:112
	v_and_b32_e32 v79, 63, v170
	v_lshrrev_b32_e32 v88, 3, v79
	v_sub_u32_e32 v88, v88, v79
	v_and_b32_e32 v79, 7, v79
	v_lshlrev_b32_e32 v79, 4, v79
	v_mul_i32_i24_e32 v84, 0x200, v88
	v_add_u32_e32 v84, v84, v79
	v_mul_i32_i24_e32 v88, 0x110, v88
	v_add3_u32 v88, v88, v79, v78
	s_waitcnt lgkmcnt(0)
	ds_read_b128 v[72:75], v88 offset:0
	v_mov_b32_e32 v86, v84
	v_ashrrev_i32_e32 v87, 31, v86
	v_lshl_add_u64 v[90:91], v[86:87], 0, v[76:77]
	s_waitcnt lgkmcnt(0)
	global_store_dwordx4 v[90:91], v[72:75], off
	ds_read_b128 v[80:83], v88 offset:2176
	v_add_u32_e32 v86, 0x1000, v84
	v_ashrrev_i32_e32 v87, 31, v86
	v_lshl_add_u64 v[90:91], v[86:87], 0, v[76:77]
	s_waitcnt lgkmcnt(0)
	global_store_dwordx4 v[90:91], v[80:83], off
	ds_read_b128 v[72:75], v88 offset:4352
	v_add_u32_e32 v86, 0x2000, v84
	v_ashrrev_i32_e32 v87, 31, v86
	v_lshl_add_u64 v[90:91], v[86:87], 0, v[76:77]
	s_waitcnt lgkmcnt(0)
	global_store_dwordx4 v[90:91], v[72:75], off
	ds_read_b128 v[80:83], v88 offset:6528
	v_add_u32_e32 v86, 0x3000, v84
	v_ashrrev_i32_e32 v87, 31, v86
	v_lshl_add_u64 v[90:91], v[86:87], 0, v[76:77]
	s_waitcnt lgkmcnt(0)
	global_store_dwordx4 v[90:91], v[80:83], off
	ds_read_b128 v[72:75], v88 offset:8704
	v_add_u32_e32 v86, 0x4000, v84
	v_ashrrev_i32_e32 v87, 31, v86
	v_lshl_add_u64 v[90:91], v[86:87], 0, v[76:77]
	s_waitcnt lgkmcnt(0)
	global_store_dwordx4 v[90:91], v[72:75], off
	ds_read_b128 v[80:83], v88 offset:10880
	v_add_u32_e32 v86, 0x5000, v84
	v_ashrrev_i32_e32 v87, 31, v86
	v_lshl_add_u64 v[90:91], v[86:87], 0, v[76:77]
	s_waitcnt lgkmcnt(0)
	global_store_dwordx4 v[90:91], v[80:83], off
	ds_read_b128 v[72:75], v88 offset:13056
	v_add_u32_e32 v86, 0x6000, v84
	v_ashrrev_i32_e32 v87, 31, v86
	v_lshl_add_u64 v[90:91], v[86:87], 0, v[76:77]
	s_waitcnt lgkmcnt(0)
	global_store_dwordx4 v[90:91], v[72:75], off
	ds_read_b128 v[80:83], v88 offset:15232
	v_add_u32_e32 v86, 0x7000, v84
	v_ashrrev_i32_e32 v87, 31, v86
	v_lshl_add_u64 v[90:91], v[86:87], 0, v[76:77]
	s_waitcnt lgkmcnt(0)
	global_store_dwordx4 v[90:91], v[80:83], off
	s_waitcnt lgkmcnt(0)
	s_barrier
	ds_write2_b32 v1, v46, v54 offset1:16
	ds_write2_b32 v1, v47, v55 offset0:68 offset1:84
	ds_write2_b32 v1, v48, v56 offset0:136 offset1:152
	ds_write2_b32 v1, v49, v57 offset0:204 offset1:220
	ds_write2_b32 v1, v58, v62 offset0:32 offset1:48
	ds_write2_b32 v1, v59, v63 offset0:100 offset1:116
	ds_write2_b32 v1, v60, v64 offset0:168 offset1:184
	ds_write2_b32 v1, v61, v65 offset0:236 offset1:252
	ds_write2_b32 v66, v30, v38 offset0:64 offset1:80
	ds_write2_b32 v66, v31, v39 offset0:132 offset1:148
	ds_write2_b32 v66, v32, v40 offset0:200 offset1:216
	ds_write2_b32 v67, v33, v41 offset0:12 offset1:28
	ds_write2_b32 v66, v42, v50 offset0:96 offset1:112
	ds_write2_b32 v66, v43, v51 offset0:164 offset1:180
	ds_write2_b32 v66, v44, v52 offset0:232 offset1:248
	ds_write2_b32 v67, v45, v53 offset0:44 offset1:60
	ds_write2_b32 v68, v14, v22 offset0:128 offset1:144
	ds_write2_b32 v68, v15, v23 offset0:196 offset1:212
	ds_write2_b32 v69, v16, v24 offset0:8 offset1:24
	ds_write2_b32 v69, v17, v25 offset0:76 offset1:92
	ds_write2_b32 v68, v26, v34 offset0:160 offset1:176
	ds_write2_b32 v68, v27, v35 offset0:228 offset1:244
	ds_write2_b32 v69, v28, v36 offset0:40 offset1:56
	ds_write2_b32 v69, v29, v37 offset0:108 offset1:124
	ds_write2_b32 v70, v2, v6 offset0:192 offset1:208
	ds_write2_b32 v71, v3, v7 offset0:4 offset1:20
	ds_write2_b32 v71, v4, v8 offset0:72 offset1:88
	ds_write2_b32 v71, v5, v9 offset0:140 offset1:156
	ds_write2_b32 v70, v10, v18 offset0:224 offset1:240
	ds_write2_b32 v71, v11, v19 offset0:36 offset1:52
	ds_write2_b32 v71, v12, v20 offset0:104 offset1:120
	ds_write2_b32 v71, v13, v21 offset0:172 offset1:188
	v_mov_b32_e32 v1, v170
	s_waitcnt lgkmcnt(0)
	s_barrier
	s_nop 0
	v_mul_lo_u32 v18, v1, s33
	ds_read_b128 v[2:5], v18
	ds_read_b128 v[6:9], v18 offset:16
	ds_read_b128 v[10:13], v18 offset:32
	ds_read_b128 v[14:17], v18 offset:48
	s_waitcnt lgkmcnt(0)
	v_mul_f32_e32 v19, v102, v2
	v_mul_f32_e32 v20, v102, v3
	v_mul_f32_e32 v21, v102, v4
	v_mul_f32_e32 v22, v102, v5
	ds_read_b128 v[2:5], v18 offset:64
	v_mul_f32_e32 v23, v102, v6
	v_mul_f32_e32 v24, v102, v7
	v_mul_f32_e32 v8, v102, v8
	v_mul_f32_e32 v9, v102, v9
	s_waitcnt lgkmcnt(0)
	v_mul_f32_e32 v25, v102, v2
	v_mul_f32_e32 v26, v102, v3
	v_mul_f32_e32 v27, v102, v4
	v_mul_f32_e32 v28, v102, v5
	ds_read_b128 v[2:5], v18 offset:80
	v_mul_f32_e32 v10, v102, v10
	v_mul_f32_e32 v11, v102, v11
	v_mul_f32_e32 v12, v102, v12
	v_mul_f32_e32 v13, v102, v13
	s_waitcnt lgkmcnt(0)
	v_mul_f32_e32 v29, v102, v2
	v_mul_f32_e32 v30, v102, v3
	v_mul_f32_e32 v31, v102, v4
	v_mul_f32_e32 v32, v102, v5
	ds_read_b128 v[2:5], v18 offset:96
	v_mul_f32_e32 v14, v102, v14
	v_mul_f32_e32 v15, v102, v15
	v_mul_f32_e32 v16, v102, v16
	v_mul_f32_e32 v17, v102, v17
	s_waitcnt lgkmcnt(0)
	v_mul_f32_e32 v33, v102, v2
	v_mul_f32_e32 v34, v102, v3
	v_mul_f32_e32 v35, v102, v4
	v_mul_f32_e32 v36, v102, v5
	ds_read_b128 v[2:5], v18 offset:112
	s_waitcnt lgkmcnt(0)
	v_mul_f32_e32 v37, v102, v2
	v_mul_f32_e32 v38, v102, v3
	v_mul_f32_e32 v39, v102, v4
	v_mul_f32_e32 v40, v102, v5
	ds_read_b128 v[2:5], v18 offset:128
	s_waitcnt lgkmcnt(0)
	v_mul_f32_e32 v41, v102, v2
	v_mul_f32_e32 v42, v102, v3
	v_mul_f32_e32 v43, v102, v4
	v_mul_f32_e32 v44, v102, v5
	ds_read_b128 v[2:5], v18 offset:144
	s_waitcnt lgkmcnt(0)
	v_mul_f32_e32 v45, v102, v2
	v_mul_f32_e32 v46, v102, v3
	v_mul_f32_e32 v47, v102, v4
	v_mul_f32_e32 v48, v102, v5
	ds_read_b128 v[2:5], v18 offset:160
	s_waitcnt lgkmcnt(0)
	v_mul_f32_e32 v49, v102, v2
	v_mul_f32_e32 v50, v102, v3
	v_mul_f32_e32 v51, v102, v4
	v_mul_f32_e32 v52, v102, v5
	ds_read_b128 v[2:5], v18 offset:176
	s_waitcnt lgkmcnt(0)
	v_mul_f32_e32 v53, v102, v2
	v_mul_f32_e32 v54, v102, v3
	v_mul_f32_e32 v55, v102, v4
	v_mul_f32_e32 v56, v102, v5
	ds_read_b128 v[2:5], v18 offset:192
	s_waitcnt lgkmcnt(0)
	v_mul_f32_e32 v57, v102, v2
	v_mul_f32_e32 v58, v102, v3
	v_mul_f32_e32 v59, v102, v4
	v_mul_f32_e32 v60, v102, v5
	ds_read_b128 v[2:5], v18 offset:208
	s_waitcnt lgkmcnt(0)
	v_mul_f32_e32 v61, v102, v2
	v_mul_f32_e32 v62, v102, v3
	v_mul_f32_e32 v63, v102, v4
	v_mul_f32_e32 v64, v102, v5
	ds_read_b128 v[2:5], v18 offset:224
	s_waitcnt lgkmcnt(0)
	v_mul_f32_e32 v65, v102, v2
	v_mul_f32_e32 v66, v102, v3
	v_mul_f32_e32 v67, v102, v4
	v_mul_f32_e32 v68, v102, v5
	ds_read_b128 v[2:5], v18 offset:240
	s_waitcnt lgkmcnt(0)
	v_mul_f32_e32 v18, v102, v2
	v_add_u32_e32 v2, s4, v1
	v_mul_f32_e32 v69, v102, v3
	v_ashrrev_i32_e32 v3, 31, v2
	v_lshlrev_b64 v[2:3], 9, v[2:3]
	v_lshl_add_u64 v[2:3], s[36:37], 0, v[2:3]
	v_mul_f32_e32 v70, v102, v4
	v_mul_f32_e32 v71, v102, v5
	v_lshl_add_u64 v[6:7], v[2:3], 0, s[16:17]
	v_cvt_pk_bf16_f32 v2, v19, v20
	v_cvt_pk_bf16_f32 v3, v21, v22
	v_cvt_pk_bf16_f32 v4, v23, v24
	v_cvt_pk_bf16_f32 v5, v8, v9
	v_mul_u32_u24_e32 v8, 0x110, v170
	ds_write_b128 v8, v[2:5]
	s_mov_b64 s[4:5], 0
	s_nop 0
	v_cvt_pk_bf16_f32 v2, v10, v11
	v_cvt_pk_bf16_f32 v3, v12, v13
	v_cvt_pk_bf16_f32 v4, v14, v15
	v_cvt_pk_bf16_f32 v5, v16, v17
	ds_write_b128 v8, v[2:5] offset:16
	s_nop 1
	v_cvt_pk_bf16_f32 v2, v25, v26
	v_cvt_pk_bf16_f32 v3, v27, v28
	v_cvt_pk_bf16_f32 v4, v29, v30
	v_cvt_pk_bf16_f32 v5, v31, v32
	ds_write_b128 v8, v[2:5] offset:32
	s_nop 1
	v_cvt_pk_bf16_f32 v2, v33, v34
	v_cvt_pk_bf16_f32 v3, v35, v36
	v_cvt_pk_bf16_f32 v4, v37, v38
	v_cvt_pk_bf16_f32 v5, v39, v40
	ds_write_b128 v8, v[2:5] offset:48
	s_nop 1
	v_cvt_pk_bf16_f32 v2, v41, v42
	v_cvt_pk_bf16_f32 v3, v43, v44
	v_cvt_pk_bf16_f32 v4, v45, v46
	v_cvt_pk_bf16_f32 v5, v47, v48
	ds_write_b128 v8, v[2:5] offset:64
	s_nop 1
	v_cvt_pk_bf16_f32 v2, v49, v50
	v_cvt_pk_bf16_f32 v3, v51, v52
	v_cvt_pk_bf16_f32 v4, v53, v54
	v_cvt_pk_bf16_f32 v5, v55, v56
	ds_write_b128 v8, v[2:5] offset:80
	s_nop 1
	v_cvt_pk_bf16_f32 v2, v57, v58
	v_cvt_pk_bf16_f32 v3, v59, v60
	v_cvt_pk_bf16_f32 v4, v61, v62
	v_cvt_pk_bf16_f32 v5, v63, v64
	ds_write_b128 v8, v[2:5] offset:96
	s_nop 1
	v_cvt_pk_bf16_f32 v2, v65, v66
	v_cvt_pk_bf16_f32 v3, v67, v68
	v_cvt_pk_bf16_f32 v4, v18, v69
	v_cvt_pk_bf16_f32 v5, v70, v71
	ds_write_b128 v8, v[2:5] offset:112
	v_and_b32_e32 v9, 63, v170
	v_lshrrev_b32_e32 v16, 3, v9
	v_sub_u32_e32 v16, v16, v9
	v_and_b32_e32 v9, 7, v9
	v_lshlrev_b32_e32 v9, 4, v9
	v_mul_i32_i24_e32 v2, 0x200, v16
	v_add_u32_e32 v2, v2, v9
	v_mul_i32_i24_e32 v16, 0x110, v16
	v_add3_u32 v16, v16, v9, v8
	s_waitcnt lgkmcnt(0)
	ds_read_b128 v[12:15], v16 offset:0
	v_mov_b32_e32 v4, v2
	v_ashrrev_i32_e32 v5, 31, v4
	v_lshl_add_u64 v[10:11], v[4:5], 0, v[6:7]
	s_waitcnt lgkmcnt(0)
	global_store_dwordx4 v[10:11], v[12:15], off offset:128
	ds_read_b128 v[20:23], v16 offset:2176
	v_add_u32_e32 v4, 0x1000, v2
	v_ashrrev_i32_e32 v5, 31, v4
	v_lshl_add_u64 v[10:11], v[4:5], 0, v[6:7]
	s_waitcnt lgkmcnt(0)
	global_store_dwordx4 v[10:11], v[20:23], off offset:128
	ds_read_b128 v[12:15], v16 offset:4352
	v_add_u32_e32 v4, 0x2000, v2
	v_ashrrev_i32_e32 v5, 31, v4
	v_lshl_add_u64 v[10:11], v[4:5], 0, v[6:7]
	s_waitcnt lgkmcnt(0)
	global_store_dwordx4 v[10:11], v[12:15], off offset:128
	ds_read_b128 v[20:23], v16 offset:6528
	v_add_u32_e32 v4, 0x3000, v2
	v_ashrrev_i32_e32 v5, 31, v4
	v_lshl_add_u64 v[10:11], v[4:5], 0, v[6:7]
	s_waitcnt lgkmcnt(0)
	global_store_dwordx4 v[10:11], v[20:23], off offset:128
	ds_read_b128 v[12:15], v16 offset:8704
	v_add_u32_e32 v4, 0x4000, v2
	v_ashrrev_i32_e32 v5, 31, v4
	v_lshl_add_u64 v[10:11], v[4:5], 0, v[6:7]
	s_waitcnt lgkmcnt(0)
	global_store_dwordx4 v[10:11], v[12:15], off offset:128
	ds_read_b128 v[20:23], v16 offset:10880
	v_add_u32_e32 v4, 0x5000, v2
	v_ashrrev_i32_e32 v5, 31, v4
	v_lshl_add_u64 v[10:11], v[4:5], 0, v[6:7]
	s_waitcnt lgkmcnt(0)
	global_store_dwordx4 v[10:11], v[20:23], off offset:128
	ds_read_b128 v[12:15], v16 offset:13056
	v_add_u32_e32 v4, 0x6000, v2
	v_ashrrev_i32_e32 v5, 31, v4
	v_lshl_add_u64 v[10:11], v[4:5], 0, v[6:7]
	s_waitcnt lgkmcnt(0)
	global_store_dwordx4 v[10:11], v[12:15], off offset:128
	ds_read_b128 v[20:23], v16 offset:15232
	v_add_u32_e32 v4, 0x7000, v2
	v_ashrrev_i32_e32 v5, 31, v4
	v_lshl_add_u64 v[10:11], v[4:5], 0, v[6:7]
	s_waitcnt lgkmcnt(0)
	global_store_dwordx4 v[10:11], v[20:23], off offset:128
	s_branch .LBB0_508

.Lbk64_530:
	s_waitcnt vmcnt(0)
	s_barrier
	ds_read_b128 v[192:195], v227
	ds_read_b128 v[196:199], v228
	ds_read_b128 v[200:203], v227 offset:2048
	ds_read_b128 v[204:207], v228 offset:2048
	ds_read_b128 v[208:211], v227 offset:4096
	ds_read_b128 v[212:215], v228 offset:4096
	ds_read_b128 v[216:219], v227 offset:6144
	ds_read_b128 v[220:223], v228 offset:6144
	s_add_u32 s18, s18, 0x80
	s_addc_u32 s19, s19, 0
	s_waitcnt lgkmcnt(0)
	s_barrier
	ds_read_b128 v[154:157], v229 offset:0
	ds_read_b128 v[158:161], v230 offset:0
	ds_read_b128 v[162:165], v229 offset:2048
	ds_read_b128 v[166:169], v230 offset:2048
	s_waitcnt lgkmcnt(2)
	v_mfma_f32_16x16x32_bf16 v[126:129], v[192:195], v[154:157], v[126:129]
	v_mfma_f32_16x16x32_bf16 v[114:117], v[200:203], v[154:157], v[114:117]
	v_mfma_f32_16x16x32_bf16 v[86:89], v[208:211], v[154:157], v[86:89]
	v_mfma_f32_16x16x32_bf16 v[54:57], v[216:219], v[154:157], v[54:57]
	v_readfirstlane_b32 s32, v145
	s_lshl_b32 m0, s32, 3
	v_mov_b32_e32 v226, v224
	global_load_lds_dwordx4 v226, s[18:19]
	v_mfma_f32_16x16x32_bf16 v[126:129], v[196:199], v[158:161], v[126:129]
	v_mfma_f32_16x16x32_bf16 v[114:117], v[204:207], v[158:161], v[114:117]
	v_mfma_f32_16x16x32_bf16 v[86:89], v[212:215], v[158:161], v[86:89]
	v_mfma_f32_16x16x32_bf16 v[54:57], v[220:223], v[158:161], v[54:57]
	s_add_u32 m0, m0, 0x400
	v_add_u32_e32 v226, 0x4000, v224
	global_load_lds_dwordx4 v226, s[18:19]
	ds_read_b128 v[154:157], v229 offset:4096
	ds_read_b128 v[158:161], v230 offset:4096
	s_waitcnt lgkmcnt(2)
	v_mfma_f32_16x16x32_bf16 v[122:125], v[192:195], v[162:165], v[122:125]
	v_mfma_f32_16x16x32_bf16 v[102:105], v[200:203], v[162:165], v[102:105]
	v_mfma_f32_16x16x32_bf16 v[70:73], v[208:211], v[162:165], v[70:73]
	v_mfma_f32_16x16x32_bf16 v[38:41], v[216:219], v[162:165], v[38:41]
	s_add_u32 m0, m0, 0x400
	v_add_u32_e32 v226, 0x8000, v224
	global_load_lds_dwordx4 v226, s[18:19]
	v_mfma_f32_16x16x32_bf16 v[122:125], v[196:199], v[166:169], v[122:125]
	v_mfma_f32_16x16x32_bf16 v[102:105], v[204:207], v[166:169], v[102:105]
	v_mfma_f32_16x16x32_bf16 v[70:73], v[212:215], v[166:169], v[70:73]
	v_mfma_f32_16x16x32_bf16 v[38:41], v[220:223], v[166:169], v[38:41]
	s_add_u32 m0, m0, 0x400
	v_add_u32_e32 v226, 0xc000, v224
	global_load_lds_dwordx4 v226, s[18:19]
	ds_read_b128 v[162:165], v229 offset:6144
	ds_read_b128 v[166:169], v230 offset:6144
	s_waitcnt lgkmcnt(2)
	v_mfma_f32_16x16x32_bf16 v[118:121], v[192:195], v[154:157], v[118:121]
	v_mfma_f32_16x16x32_bf16 v[90:93], v[200:203], v[154:157], v[90:93]
	v_mfma_f32_16x16x32_bf16 v[58:61], v[208:211], v[154:157], v[58:61]
	v_mfma_f32_16x16x32_bf16 v[26:29], v[216:219], v[154:157], v[26:29]
	s_add_u32 m0, m0, 0x400
	v_add_u32_e32 v226, 0x10000, v224
	global_load_lds_dwordx4 v226, s[18:19]
	v_mfma_f32_16x16x32_bf16 v[118:121], v[196:199], v[158:161], v[118:121]
	v_mfma_f32_16x16x32_bf16 v[90:93], v[204:207], v[158:161], v[90:93]
	v_mfma_f32_16x16x32_bf16 v[58:61], v[212:215], v[158:161], v[58:61]
	v_mfma_f32_16x16x32_bf16 v[26:29], v[220:223], v[158:161], v[26:29]
	s_add_u32 m0, m0, 0x400
	v_add_u32_e32 v226, 0x14000, v224
	global_load_lds_dwordx4 v226, s[18:19]
	ds_read_b128 v[154:157], v229 offset:8192
	ds_read_b128 v[158:161], v230 offset:8192
	s_waitcnt lgkmcnt(2)
	v_mfma_f32_16x16x32_bf16 v[110:113], v[192:195], v[162:165], v[110:113]
	v_mfma_f32_16x16x32_bf16 v[78:81], v[200:203], v[162:165], v[78:81]
	v_mfma_f32_16x16x32_bf16 v[46:49], v[208:211], v[162:165], v[46:49]
	v_mfma_f32_16x16x32_bf16 v[18:21], v[216:219], v[162:165], v[18:21]
	s_add_u32 m0, m0, 0x400
	v_add_u32_e32 v226, 0x18000, v224
	global_load_lds_dwordx4 v226, s[18:19]
	v_mfma_f32_16x16x32_bf16 v[110:113], v[196:199], v[166:169], v[110:113]
	v_mfma_f32_16x16x32_bf16 v[78:81], v[204:207], v[166:169], v[78:81]
	v_mfma_f32_16x16x32_bf16 v[46:49], v[212:215], v[166:169], v[46:49]
	v_mfma_f32_16x16x32_bf16 v[18:21], v[220:223], v[166:169], v[18:21]
	s_add_u32 m0, m0, 0x400
	v_add_u32_e32 v226, 0x1c000, v224
	global_load_lds_dwordx4 v226, s[18:19]
	ds_read_b128 v[162:165], v229 offset:10240
	ds_read_b128 v[166:169], v230 offset:10240
	s_waitcnt lgkmcnt(2)
	v_mfma_f32_16x16x32_bf16 v[106:109], v[192:195], v[154:157], v[106:109]
	v_mfma_f32_16x16x32_bf16 v[74:77], v[200:203], v[154:157], v[74:77]
	v_mfma_f32_16x16x32_bf16 v[42:45], v[208:211], v[154:157], v[42:45]
	v_mfma_f32_16x16x32_bf16 v[14:17], v[216:219], v[154:157], v[14:17]
	s_add_u32 m0, s25, 17
	s_and_b32 m0, m0, 1
	s_lshl_b32 m0, m0, 14
	s_add_u32 m0, m0, 0x8000
	v_readfirstlane_b32 s32, v145
	s_lshl_b32 s32, s32, 2
	s_add_u32 m0, m0, s32
	v_mov_b32_e32 v226, v225
	global_load_lds_dwordx4 v226, s[18:19]
	v_mfma_f32_16x16x32_bf16 v[106:109], v[196:199], v[158:161], v[106:109]
	v_mfma_f32_16x16x32_bf16 v[74:77], v[204:207], v[158:161], v[74:77]
	v_mfma_f32_16x16x32_bf16 v[42:45], v[212:215], v[158:161], v[42:45]
	v_mfma_f32_16x16x32_bf16 v[14:17], v[220:223], v[158:161], v[14:17]
	s_add_u32 m0, m0, 0x400
	v_add_u32_e32 v226, 0x4000, v225
	global_load_lds_dwordx4 v226, s[18:19]
	ds_read_b128 v[154:157], v229 offset:12288
	ds_read_b128 v[158:161], v230 offset:12288
	s_waitcnt lgkmcnt(2)
	v_mfma_f32_16x16x32_bf16 v[98:101], v[192:195], v[162:165], v[98:101]
	v_mfma_f32_16x16x32_bf16 v[66:69], v[200:203], v[162:165], v[66:69]
	v_mfma_f32_16x16x32_bf16 v[34:37], v[208:211], v[162:165], v[34:37]
	v_mfma_f32_16x16x32_bf16 v[10:13], v[216:219], v[162:165], v[10:13]
	s_add_u32 m0, m0, 0x400
	v_add_u32_e32 v226, 0x8000, v225
	global_load_lds_dwordx4 v226, s[18:19]
	v_mfma_f32_16x16x32_bf16 v[98:101], v[196:199], v[166:169], v[98:101]
	v_mfma_f32_16x16x32_bf16 v[66:69], v[204:207], v[166:169], v[66:69]
	v_mfma_f32_16x16x32_bf16 v[34:37], v[212:215], v[166:169], v[34:37]
	v_mfma_f32_16x16x32_bf16 v[10:13], v[220:223], v[166:169], v[10:13]
	s_add_u32 m0, m0, 0x400
	v_add_u32_e32 v226, 0xc000, v225
	global_load_lds_dwordx4 v226, s[18:19]
	ds_read_b128 v[162:165], v229 offset:14336
	ds_read_b128 v[166:169], v230 offset:14336
	s_waitcnt lgkmcnt(2)
	v_mfma_f32_16x16x32_bf16 v[94:97], v[192:195], v[154:157], v[94:97]
	v_mfma_f32_16x16x32_bf16 v[62:65], v[200:203], v[154:157], v[62:65]
	v_mfma_f32_16x16x32_bf16 v[30:33], v[208:211], v[154:157], v[30:33]
	v_mfma_f32_16x16x32_bf16 v[6:9], v[216:219], v[154:157], v[6:9]
	v_mfma_f32_16x16x32_bf16 v[94:97], v[196:199], v[158:161], v[94:97]
	v_mfma_f32_16x16x32_bf16 v[62:65], v[204:207], v[158:161], v[62:65]
	v_mfma_f32_16x16x32_bf16 v[30:33], v[212:215], v[158:161], v[30:33]
	v_mfma_f32_16x16x32_bf16 v[6:9], v[220:223], v[158:161], v[6:9]
	s_waitcnt lgkmcnt(0)
	v_mfma_f32_16x16x32_bf16 v[82:85], v[192:195], v[162:165], v[82:85]
	v_mfma_f32_16x16x32_bf16 v[50:53], v[200:203], v[162:165], v[50:53]
	v_mfma_f32_16x16x32_bf16 v[22:25], v[208:211], v[162:165], v[22:25]
	v_mfma_f32_16x16x32_bf16 v[2:5], v[216:219], v[162:165], v[2:5]
	v_mfma_f32_16x16x32_bf16 v[82:85], v[196:199], v[166:169], v[82:85]
	v_mfma_f32_16x16x32_bf16 v[50:53], v[204:207], v[166:169], v[50:53]
	v_mfma_f32_16x16x32_bf16 v[22:25], v[212:215], v[166:169], v[22:25]
	v_mfma_f32_16x16x32_bf16 v[2:5], v[220:223], v[166:169], v[2:5]
	v_xor_b32_e32 v229, 0x4000, v229
	v_xor_b32_e32 v230, 0x4000, v230
	s_add_i32 s25, s25, 1
	s_cmp_lg_u32 s25, 15
	s_cbranch_scc1 .Lbk64_530
	s_waitcnt vmcnt(0)
	s_barrier
	ds_read_b128 v[192:195], v227
	ds_read_b128 v[196:199], v228
	ds_read_b128 v[200:203], v227 offset:2048
	ds_read_b128 v[204:207], v228 offset:2048
	ds_read_b128 v[208:211], v227 offset:4096
	ds_read_b128 v[212:215], v228 offset:4096
	ds_read_b128 v[216:219], v227 offset:6144
	ds_read_b128 v[220:223], v228 offset:6144
	s_waitcnt lgkmcnt(0)
	s_barrier
	ds_read_b128 v[154:157], v229 offset:0
	ds_read_b128 v[158:161], v230 offset:0
	ds_read_b128 v[162:165], v229 offset:2048
	ds_read_b128 v[166:169], v230 offset:2048
	s_waitcnt lgkmcnt(2)
	v_mfma_f32_16x16x32_bf16 v[126:129], v[192:195], v[154:157], v[126:129]
	v_mfma_f32_16x16x32_bf16 v[114:117], v[200:203], v[154:157], v[114:117]
	v_mfma_f32_16x16x32_bf16 v[86:89], v[208:211], v[154:157], v[86:89]
	v_mfma_f32_16x16x32_bf16 v[54:57], v[216:219], v[154:157], v[54:57]
	v_mfma_f32_16x16x32_bf16 v[126:129], v[196:199], v[158:161], v[126:129]
	v_mfma_f32_16x16x32_bf16 v[114:117], v[204:207], v[158:161], v[114:117]
	v_mfma_f32_16x16x32_bf16 v[86:89], v[212:215], v[158:161], v[86:89]
	v_mfma_f32_16x16x32_bf16 v[54:57], v[220:223], v[158:161], v[54:57]
	ds_read_b128 v[154:157], v229 offset:4096
	ds_read_b128 v[158:161], v230 offset:4096
	s_waitcnt lgkmcnt(2)
	v_mfma_f32_16x16x32_bf16 v[122:125], v[192:195], v[162:165], v[122:125]
	v_mfma_f32_16x16x32_bf16 v[102:105], v[200:203], v[162:165], v[102:105]
	v_mfma_f32_16x16x32_bf16 v[70:73], v[208:211], v[162:165], v[70:73]
	v_mfma_f32_16x16x32_bf16 v[38:41], v[216:219], v[162:165], v[38:41]
	v_mfma_f32_16x16x32_bf16 v[122:125], v[196:199], v[166:169], v[122:125]
	v_mfma_f32_16x16x32_bf16 v[102:105], v[204:207], v[166:169], v[102:105]
	v_mfma_f32_16x16x32_bf16 v[70:73], v[212:215], v[166:169], v[70:73]
	v_mfma_f32_16x16x32_bf16 v[38:41], v[220:223], v[166:169], v[38:41]
	ds_read_b128 v[162:165], v229 offset:6144
	ds_read_b128 v[166:169], v230 offset:6144
	s_waitcnt lgkmcnt(2)
	v_mfma_f32_16x16x32_bf16 v[118:121], v[192:195], v[154:157], v[118:121]
	v_mfma_f32_16x16x32_bf16 v[90:93], v[200:203], v[154:157], v[90:93]
	v_mfma_f32_16x16x32_bf16 v[58:61], v[208:211], v[154:157], v[58:61]
	v_mfma_f32_16x16x32_bf16 v[26:29], v[216:219], v[154:157], v[26:29]
	v_mfma_f32_16x16x32_bf16 v[118:121], v[196:199], v[158:161], v[118:121]
	v_mfma_f32_16x16x32_bf16 v[90:93], v[204:207], v[158:161], v[90:93]
	v_mfma_f32_16x16x32_bf16 v[58:61], v[212:215], v[158:161], v[58:61]
	v_mfma_f32_16x16x32_bf16 v[26:29], v[220:223], v[158:161], v[26:29]
	ds_read_b128 v[154:157], v229 offset:8192
	ds_read_b128 v[158:161], v230 offset:8192
	s_waitcnt lgkmcnt(2)
	v_mfma_f32_16x16x32_bf16 v[110:113], v[192:195], v[162:165], v[110:113]
	v_mfma_f32_16x16x32_bf16 v[78:81], v[200:203], v[162:165], v[78:81]
	v_mfma_f32_16x16x32_bf16 v[46:49], v[208:211], v[162:165], v[46:49]
	v_mfma_f32_16x16x32_bf16 v[18:21], v[216:219], v[162:165], v[18:21]
	v_mfma_f32_16x16x32_bf16 v[110:113], v[196:199], v[166:169], v[110:113]
	v_mfma_f32_16x16x32_bf16 v[78:81], v[204:207], v[166:169], v[78:81]
	v_mfma_f32_16x16x32_bf16 v[46:49], v[212:215], v[166:169], v[46:49]
	v_mfma_f32_16x16x32_bf16 v[18:21], v[220:223], v[166:169], v[18:21]
	ds_read_b128 v[162:165], v229 offset:10240
	ds_read_b128 v[166:169], v230 offset:10240
	s_waitcnt lgkmcnt(2)
	v_mfma_f32_16x16x32_bf16 v[106:109], v[192:195], v[154:157], v[106:109]
	v_mfma_f32_16x16x32_bf16 v[74:77], v[200:203], v[154:157], v[74:77]
	v_mfma_f32_16x16x32_bf16 v[42:45], v[208:211], v[154:157], v[42:45]
	v_mfma_f32_16x16x32_bf16 v[14:17], v[216:219], v[154:157], v[14:17]
	v_mfma_f32_16x16x32_bf16 v[106:109], v[196:199], v[158:161], v[106:109]
	v_mfma_f32_16x16x32_bf16 v[74:77], v[204:207], v[158:161], v[74:77]
	v_mfma_f32_16x16x32_bf16 v[42:45], v[212:215], v[158:161], v[42:45]
	v_mfma_f32_16x16x32_bf16 v[14:17], v[220:223], v[158:161], v[14:17]
	ds_read_b128 v[154:157], v229 offset:12288
	ds_read_b128 v[158:161], v230 offset:12288
	s_waitcnt lgkmcnt(2)
	v_mfma_f32_16x16x32_bf16 v[98:101], v[192:195], v[162:165], v[98:101]
	v_mfma_f32_16x16x32_bf16 v[66:69], v[200:203], v[162:165], v[66:69]
	v_mfma_f32_16x16x32_bf16 v[34:37], v[208:211], v[162:165], v[34:37]
	v_mfma_f32_16x16x32_bf16 v[10:13], v[216:219], v[162:165], v[10:13]
	v_mfma_f32_16x16x32_bf16 v[98:101], v[196:199], v[166:169], v[98:101]
	v_mfma_f32_16x16x32_bf16 v[66:69], v[204:207], v[166:169], v[66:69]
	v_mfma_f32_16x16x32_bf16 v[34:37], v[212:215], v[166:169], v[34:37]
	v_mfma_f32_16x16x32_bf16 v[10:13], v[220:223], v[166:169], v[10:13]
	ds_read_b128 v[162:165], v229 offset:14336
	ds_read_b128 v[166:169], v230 offset:14336
	s_waitcnt lgkmcnt(2)
	v_mfma_f32_16x16x32_bf16 v[94:97], v[192:195], v[154:157], v[94:97]
	v_mfma_f32_16x16x32_bf16 v[62:65], v[200:203], v[154:157], v[62:65]
	v_mfma_f32_16x16x32_bf16 v[30:33], v[208:211], v[154:157], v[30:33]
	v_mfma_f32_16x16x32_bf16 v[6:9], v[216:219], v[154:157], v[6:9]
	v_mfma_f32_16x16x32_bf16 v[94:97], v[196:199], v[158:161], v[94:97]
	v_mfma_f32_16x16x32_bf16 v[62:65], v[204:207], v[158:161], v[62:65]
	v_mfma_f32_16x16x32_bf16 v[30:33], v[212:215], v[158:161], v[30:33]
	v_mfma_f32_16x16x32_bf16 v[6:9], v[220:223], v[158:161], v[6:9]
	s_waitcnt lgkmcnt(0)
	v_mfma_f32_16x16x32_bf16 v[82:85], v[192:195], v[162:165], v[82:85]
	v_mfma_f32_16x16x32_bf16 v[50:53], v[200:203], v[162:165], v[50:53]
	v_mfma_f32_16x16x32_bf16 v[22:25], v[208:211], v[162:165], v[22:25]
	v_mfma_f32_16x16x32_bf16 v[2:5], v[216:219], v[162:165], v[2:5]
	v_mfma_f32_16x16x32_bf16 v[82:85], v[196:199], v[166:169], v[82:85]
	v_mfma_f32_16x16x32_bf16 v[50:53], v[204:207], v[166:169], v[50:53]
	v_mfma_f32_16x16x32_bf16 v[22:25], v[212:215], v[166:169], v[22:25]
	v_mfma_f32_16x16x32_bf16 v[2:5], v[220:223], v[166:169], v[2:5]
	s_nop 7
	s_nop 7
	s_waitcnt vmcnt(6)
	v_add_u32_e32 v145, v149, v147
	s_waitcnt vmcnt(0)
	s_waitcnt lgkmcnt(0)
	s_lshl_b32 s18, s16, 7
	s_ashr_i32 s19, s18, 31
	s_lshl_b64 s[18:19], s[18:19], 1
	v_and_b32_e32 v1, 0xfffffc0, v1
	v_lshl_or_b32 v1, v143, 2, v1
	v_mul_lo_u32 v1, v1, s33
	v_lshl_or_b32 v1, v142, 2, v1
	s_lshl_b32 s16, s16, 1
	s_ashr_i32 s17, s16, 31
	s_lshl_b64 s[16:17], s[16:17], 2
	s_add_i32 s24, s24, 1
	v_mov_b64_e32 v[162:163], v[62:63]
	v_mov_b64_e32 v[164:165], v[64:65]
	v_mov_b64_e32 v[166:167], v[30:31]
	v_mov_b64_e32 v[168:169], v[32:33]
	v_mov_b64_e32 v[130:131], v[22:23]
	v_mov_b64_e32 v[132:133], v[24:25]
	s_waitcnt lgkmcnt(0)
	v_mov_b64_e32 v[232:233], v[38:39]
	v_mov_b64_e32 v[234:235], v[40:41]
	v_mov_b64_e32 v[38:39], v[34:35]
	v_mov_b64_e32 v[40:41], v[36:37]
	v_mov_b64_e32 v[34:35], v[2:3]
	v_mov_b64_e32 v[36:37], v[4:5]
	s_nop 2
	v_mov_b32_e32 v2, v170
	v_mov_b64_e32 v[216:217], v[114:115]
	v_mov_b64_e32 v[218:219], v[116:117]
	v_add_u32_e32 v2, s4, v2
	v_ashrrev_i32_e32 v3, 31, v2
	v_lshlrev_b64 v[2:3], 11, v[2:3]
	v_lshl_add_u64 v[2:3], s[8:9], 0, v[2:3]
	v_lshl_add_u64 v[2:3], v[2:3], 0, s[18:19]
	v_mov_b64_e32 v[220:221], v[54:55]
	v_mov_b64_e32 v[222:223], v[56:57]
	v_mov_b64_e32 v[224:225], v[122:123]
	v_mov_b64_e32 v[226:227], v[124:125]
	v_mov_b64_e32 v[228:229], v[102:103]
	v_mov_b64_e32 v[230:231], v[104:105]
	v_mov_b64_e32 v[236:237], v[118:119]
	v_mov_b64_e32 v[238:239], v[120:121]
	v_mov_b64_e32 v[240:241], v[58:59]
	v_mov_b64_e32 v[242:243], v[60:61]
	v_mov_b64_e32 v[244:245], v[26:27]
	v_mov_b64_e32 v[246:247], v[28:29]
	v_mov_b64_e32 v[248:249], v[110:111]
	v_mov_b64_e32 v[250:251], v[112:113]
	v_mov_b64_e32 v[180:181], v[78:79]
	v_mov_b64_e32 v[182:183], v[80:81]
	v_mov_b64_e32 v[154:155], v[46:47]
	v_mov_b64_e32 v[156:157], v[48:49]
	v_mov_b64_e32 v[62:63], v[106:107]
	v_mov_b64_e32 v[64:65], v[108:109]
	v_mov_b64_e32 v[46:47], v[74:75]
	v_mov_b64_e32 v[48:49], v[76:77]
	v_mov_b64_e32 v[74:75], v[98:99]
	v_mov_b64_e32 v[76:77], v[100:101]
	v_mov_b64_e32 v[54:55], v[66:67]
	v_mov_b64_e32 v[56:57], v[68:69]
	v_mov_b64_e32 v[58:59], v[162:163]
	v_mov_b64_e32 v[60:61], v[164:165]
	v_mov_b64_e32 v[66:67], v[50:51]
	v_mov_b64_e32 v[68:69], v[52:53]
	flat_load_dwordx4 v[138:141], v[2:3]
	flat_load_dwordx4 v[122:125], v[2:3] offset:16
	flat_load_dwordx4 v[118:121], v[2:3] offset:32
	flat_load_dwordx4 v[114:117], v[2:3] offset:48
	flat_load_dwordx4 v[110:113], v[2:3] offset:64
	flat_load_dwordx4 v[106:109], v[2:3] offset:80
	flat_load_dwordx4 v[102:105], v[2:3] offset:96
	flat_load_dwordx4 v[98:101], v[2:3] offset:112
	s_waitcnt vmcnt(0) lgkmcnt(0)
	s_barrier
	s_nop 7
	ds_write2_b32 v1, v126, v224 offset1:16
	ds_write2_b32 v1, v127, v225 offset0:68 offset1:84
	ds_write2_b32 v1, v128, v226 offset0:136 offset1:152
	ds_write2_b32 v1, v129, v227 offset0:204 offset1:220
	ds_write2_b32 v1, v236, v248 offset0:32 offset1:48
	ds_write2_b32 v1, v237, v249 offset0:100 offset1:116
	ds_write2_b32 v1, v238, v250 offset0:168 offset1:184
	ds_write2_b32 v1, v239, v251 offset0:236 offset1:252
	v_mov_b64_e32 v[196:197], v[18:19]
	v_mov_b64_e32 v[198:199], v[20:21]
	v_mov_b64_e32 v[78:79], v[94:95]
	v_mov_b64_e32 v[80:81], v[96:97]
	v_add_u32_e32 v135, 0x3000, v1
	v_add_u32_e32 v134, 0x3400, v1
	v_mov_b32_e32 v136, v170
	v_mov_b64_e32 v[50:51], v[130:131]
	v_mov_b64_e32 v[52:53], v[132:133]
	v_lshlrev_b32_e32 v137, 16, v138
	s_nop 1
	v_add_u32_e32 v130, 0x1000, v1
	v_add_u32_e32 v131, 0x1400, v1
	v_add_u32_e32 v132, 0x2000, v1
	v_add_u32_e32 v133, 0x2400, v1
	ds_write2_b32 v130, v216, v228 offset0:64 offset1:80
	ds_write2_b32 v130, v217, v229 offset0:132 offset1:148
	ds_write2_b32 v130, v218, v230 offset0:200 offset1:216
	ds_write2_b32 v131, v219, v231 offset0:12 offset1:28
	ds_write2_b32 v130, v90, v180 offset0:96 offset1:112
	ds_write2_b32 v130, v91, v181 offset0:164 offset1:180
	ds_write2_b32 v130, v92, v182 offset0:232 offset1:248
	ds_write2_b32 v131, v93, v183 offset0:44 offset1:60
	ds_write2_b32 v132, v86, v70 offset0:128 offset1:144
	ds_write2_b32 v132, v87, v71 offset0:196 offset1:212
	ds_write2_b32 v133, v88, v72 offset0:8 offset1:24
	ds_write2_b32 v133, v89, v73 offset0:76 offset1:92
	ds_write2_b32 v132, v240, v154 offset0:160 offset1:176
	ds_write2_b32 v132, v241, v155 offset0:228 offset1:244
	ds_write2_b32 v133, v242, v156 offset0:40 offset1:56
	ds_write2_b32 v133, v243, v157 offset0:108 offset1:124
	ds_write2_b32 v135, v220, v232 offset0:192 offset1:208
	ds_write2_b32 v134, v221, v233 offset0:4 offset1:20
	ds_write2_b32 v134, v222, v234 offset0:72 offset1:88
	ds_write2_b32 v134, v223, v235 offset0:140 offset1:156
	ds_write2_b32 v135, v244, v196 offset0:224 offset1:240
	ds_write2_b32 v134, v245, v197 offset0:36 offset1:52
	ds_write2_b32 v134, v246, v198 offset0:104 offset1:120
	ds_write2_b32 v134, v247, v199 offset0:172 offset1:188
	s_waitcnt lgkmcnt(0)
	s_barrier
	v_mov_b64_e32 v[18:19], v[14:15]
	v_mov_b64_e32 v[20:21], v[16:17]
	v_add_u32_e32 v126, s4, v136
	v_ashrrev_i32_e32 v127, 31, v126
	v_lshlrev_b64 v[2:3], 11, v[126:127]
	v_lshl_add_u64 v[2:3], s[8:9], 0, v[2:3]
	v_lshl_add_u64 v[128:129], v[2:3], 0, s[18:19]
	v_mul_lo_u32 v136, v136, s33
	v_mov_b64_e32 v[22:23], v[10:11]
	v_mov_b64_e32 v[24:25], v[12:13]
	v_and_b32_e32 v138, 0xffff0000, v138
	v_mov_b64_e32 v[26:27], v[6:7]
	v_mov_b64_e32 v[28:29], v[8:9]
	flat_load_dwordx4 v[94:97], v[128:129] offset:128
	flat_load_dwordx4 v[90:93], v[128:129] offset:144
	flat_load_dwordx4 v[86:89], v[128:129] offset:160
	flat_load_dwordx4 v[70:73], v[128:129] offset:176
	flat_load_dwordx4 v[14:17], v[128:129] offset:192
	flat_load_dwordx4 v[10:13], v[128:129] offset:208
	flat_load_dwordx4 v[6:9], v[128:129] offset:224
	flat_load_dwordx4 v[2:5], v[128:129] offset:240
	ds_read_b128 v[142:145], v136
	ds_read_b128 v[154:157], v136 offset:16
	s_waitcnt lgkmcnt(0)
	v_add_f32_e32 v137, v142, v137
	v_add_f32_e32 v138, v143, v138
	v_cvt_pk_bf16_f32 v138, v137, v138
	v_lshlrev_b32_e32 v137, 16, v139
	v_and_b32_e32 v139, 0xffff0000, v139
	v_add_f32_e32 v137, v144, v137
	v_add_f32_e32 v139, v145, v139
	v_cvt_pk_bf16_f32 v139, v137, v139
	v_lshlrev_b32_e32 v137, 16, v140
	v_and_b32_e32 v140, 0xffff0000, v140
	v_add_f32_e32 v137, v154, v137
	v_add_f32_e32 v140, v155, v140
	v_cvt_pk_bf16_f32 v140, v137, v140
	v_lshlrev_b32_e32 v137, 16, v141
	v_and_b32_e32 v141, 0xffff0000, v141
	v_add_f32_e32 v137, v156, v137
	v_add_f32_e32 v141, v157, v141
	v_and_b32_e32 v142, 0xffff0000, v138
	v_cvt_pk_bf16_f32 v141, v137, v141
	v_lshlrev_b32_e32 v137, 16, v138
	v_mul_f32_e32 v153, v142, v142
	v_lshlrev_b32_e32 v143, 16, v139
	v_fmac_f32_e32 v153, v137, v137
	v_and_b32_e32 v144, 0xffff0000, v139
	v_fmac_f32_e32 v153, v143, v143
	v_lshlrev_b32_e32 v145, 16, v140
	v_fmac_f32_e32 v153, v144, v144
	ds_write_b128 v136, v[138:141]
	v_and_b32_e32 v147, 0xffff0000, v140
	v_lshlrev_b32_e32 v149, 16, v141
	v_and_b32_e32 v151, 0xffff0000, v141
	v_fmac_f32_e32 v153, v145, v145
	ds_read_b128 v[138:141], v136 offset:32
	ds_read_b128 v[142:145], v136 offset:48
	v_lshlrev_b32_e32 v137, 16, v122
	v_and_b32_e32 v122, 0xffff0000, v122
	v_fmac_f32_e32 v153, v147, v147
	s_waitcnt lgkmcnt(0)
	v_add_f32_e32 v137, v138, v137
	v_add_f32_e32 v122, v139, v122
	v_cvt_pk_bf16_f32 v122, v137, v122
	v_lshlrev_b32_e32 v137, 16, v123
	v_and_b32_e32 v123, 0xffff0000, v123
	v_add_f32_e32 v137, v140, v137
	v_add_f32_e32 v123, v141, v123
	v_cvt_pk_bf16_f32 v123, v137, v123
	v_lshlrev_b32_e32 v137, 16, v124
	v_and_b32_e32 v124, 0xffff0000, v124
	v_add_f32_e32 v137, v142, v137
	v_add_f32_e32 v124, v143, v124
	v_cvt_pk_bf16_f32 v124, v137, v124
	v_lshlrev_b32_e32 v137, 16, v125
	v_and_b32_e32 v125, 0xffff0000, v125
	v_add_f32_e32 v137, v144, v137
	v_add_f32_e32 v125, v145, v125
	v_and_b32_e32 v138, 0xffff0000, v122
	v_cvt_pk_bf16_f32 v125, v137, v125
	v_lshlrev_b32_e32 v137, 16, v122
	v_mul_f32_e32 v138, v138, v138
	v_lshlrev_b32_e32 v139, 16, v123
	v_fmac_f32_e32 v138, v137, v137
	v_and_b32_e32 v140, 0xffff0000, v123
	v_fmac_f32_e32 v138, v139, v139
	v_lshlrev_b32_e32 v141, 16, v124
	v_fmac_f32_e32 v138, v140, v140
	v_and_b32_e32 v142, 0xffff0000, v124
	v_fmac_f32_e32 v138, v141, v141
	v_lshlrev_b32_e32 v143, 16, v125
	v_fmac_f32_e32 v138, v142, v142
	v_fmac_f32_e32 v153, v149, v149
	v_and_b32_e32 v144, 0xffff0000, v125
	v_fmac_f32_e32 v138, v143, v143
	v_fmac_f32_e32 v153, v151, v151
	v_fmac_f32_e32 v138, v144, v144
	ds_write_b128 v136, v[122:125] offset:16
	v_add_f32_e32 v137, v153, v138
	ds_read_b128 v[122:125], v136 offset:64
	ds_read_b128 v[138:141], v136 offset:80
	v_lshlrev_b32_e32 v142, 16, v118
	v_and_b32_e32 v118, 0xffff0000, v118
	v_mov_b64_e32 v[30:31], v[42:43]
	v_mov_b64_e32 v[32:33], v[44:45]
	s_waitcnt lgkmcnt(0)
	v_add_f32_e32 v122, v122, v142
	v_add_f32_e32 v118, v123, v118
	v_cvt_pk_bf16_f32 v118, v122, v118
	v_lshlrev_b32_e32 v122, 16, v119
	v_and_b32_e32 v119, 0xffff0000, v119
	v_add_f32_e32 v122, v124, v122
	v_add_f32_e32 v119, v125, v119
	v_cvt_pk_bf16_f32 v119, v122, v119
	v_lshlrev_b32_e32 v122, 16, v120
	v_and_b32_e32 v120, 0xffff0000, v120
	v_add_f32_e32 v122, v138, v122
	v_add_f32_e32 v120, v139, v120
	v_cvt_pk_bf16_f32 v120, v122, v120
	v_lshlrev_b32_e32 v122, 16, v121
	v_and_b32_e32 v121, 0xffff0000, v121
	v_add_f32_e32 v122, v140, v122
	v_add_f32_e32 v121, v141, v121
	v_and_b32_e32 v123, 0xffff0000, v118
	v_cvt_pk_bf16_f32 v121, v122, v121
	v_lshlrev_b32_e32 v122, 16, v118
	v_mul_f32_e32 v123, v123, v123
	v_lshlrev_b32_e32 v124, 16, v119
	v_fmac_f32_e32 v123, v122, v122
	v_and_b32_e32 v125, 0xffff0000, v119
	v_fmac_f32_e32 v123, v124, v124
	v_lshlrev_b32_e32 v138, 16, v120
	v_fmac_f32_e32 v123, v125, v125
	v_and_b32_e32 v139, 0xffff0000, v120
	v_fmac_f32_e32 v123, v138, v138
	v_lshlrev_b32_e32 v140, 16, v121
	v_fmac_f32_e32 v123, v139, v139
	v_and_b32_e32 v141, 0xffff0000, v121
	v_fmac_f32_e32 v123, v140, v140
	v_fmac_f32_e32 v123, v141, v141
	ds_write_b128 v136, v[118:121] offset:32
	v_add_f32_e32 v137, v137, v123
	ds_read_b128 v[118:121], v136 offset:96
	ds_read_b128 v[122:125], v136 offset:112
	v_lshlrev_b32_e32 v138, 16, v114
	v_and_b32_e32 v114, 0xffff0000, v114
	v_mov_b64_e32 v[42:43], v[166:167]
	v_mov_b64_e32 v[44:45], v[168:169]
	s_waitcnt lgkmcnt(0)
	v_add_f32_e32 v118, v118, v138
	v_add_f32_e32 v114, v119, v114
	v_cvt_pk_bf16_f32 v114, v118, v114
	v_lshlrev_b32_e32 v118, 16, v115
	v_and_b32_e32 v115, 0xffff0000, v115
	v_add_f32_e32 v118, v120, v118
	v_add_f32_e32 v115, v121, v115
	v_cvt_pk_bf16_f32 v115, v118, v115
	v_lshlrev_b32_e32 v118, 16, v116
	v_and_b32_e32 v116, 0xffff0000, v116
	v_add_f32_e32 v118, v122, v118
	v_add_f32_e32 v116, v123, v116
	v_cvt_pk_bf16_f32 v116, v118, v116
	v_lshlrev_b32_e32 v118, 16, v117
	v_and_b32_e32 v117, 0xffff0000, v117
	v_add_f32_e32 v118, v124, v118
	v_add_f32_e32 v117, v125, v117
	v_and_b32_e32 v119, 0xffff0000, v114
	v_cvt_pk_bf16_f32 v117, v118, v117
	v_lshlrev_b32_e32 v118, 16, v114
	v_mul_f32_e32 v119, v119, v119
	v_lshlrev_b32_e32 v120, 16, v115
	v_fmac_f32_e32 v119, v118, v118
	v_and_b32_e32 v121, 0xffff0000, v115
	v_fmac_f32_e32 v119, v120, v120
	v_lshlrev_b32_e32 v122, 16, v116
	v_fmac_f32_e32 v119, v121, v121
	v_and_b32_e32 v123, 0xffff0000, v116
	v_fmac_f32_e32 v119, v122, v122
	v_lshlrev_b32_e32 v124, 16, v117
	v_fmac_f32_e32 v119, v123, v123
	v_and_b32_e32 v125, 0xffff0000, v117
	v_fmac_f32_e32 v119, v124, v124
	v_fmac_f32_e32 v119, v125, v125
	ds_write_b128 v136, v[114:117] offset:48
	v_add_f32_e32 v122, v137, v119
	ds_read_b128 v[114:117], v136 offset:128
	ds_read_b128 v[118:121], v136 offset:144
	v_lshlrev_b32_e32 v123, 16, v110
	v_and_b32_e32 v110, 0xffff0000, v110
	s_waitcnt lgkmcnt(0)
	v_add_f32_e32 v114, v114, v123
	v_add_f32_e32 v110, v115, v110
	v_cvt_pk_bf16_f32 v110, v114, v110
	v_lshlrev_b32_e32 v114, 16, v111
	v_and_b32_e32 v111, 0xffff0000, v111
	v_add_f32_e32 v114, v116, v114
	v_add_f32_e32 v111, v117, v111
	v_cvt_pk_bf16_f32 v111, v114, v111
	v_lshlrev_b32_e32 v114, 16, v112
	v_and_b32_e32 v112, 0xffff0000, v112
	v_add_f32_e32 v114, v118, v114
	v_add_f32_e32 v112, v119, v112
	v_cvt_pk_bf16_f32 v112, v114, v112
	v_lshlrev_b32_e32 v114, 16, v113
	v_and_b32_e32 v113, 0xffff0000, v113
	v_add_f32_e32 v114, v120, v114
	v_add_f32_e32 v113, v121, v113
	v_and_b32_e32 v115, 0xffff0000, v110
	v_cvt_pk_bf16_f32 v113, v114, v113
	v_lshlrev_b32_e32 v114, 16, v110
	v_mul_f32_e32 v115, v115, v115
	v_lshlrev_b32_e32 v116, 16, v111
	v_fmac_f32_e32 v115, v114, v114
	v_and_b32_e32 v117, 0xffff0000, v111
	v_fmac_f32_e32 v115, v116, v116
	v_lshlrev_b32_e32 v118, 16, v112
	v_fmac_f32_e32 v115, v117, v117
	v_and_b32_e32 v119, 0xffff0000, v112
	v_fmac_f32_e32 v115, v118, v118
	v_lshlrev_b32_e32 v120, 16, v113
	v_fmac_f32_e32 v115, v119, v119
	v_and_b32_e32 v121, 0xffff0000, v113
	v_fmac_f32_e32 v115, v120, v120
	v_fmac_f32_e32 v115, v121, v121
	ds_write_b128 v136, v[110:113] offset:64
	v_add_f32_e32 v118, v122, v115
	ds_read_b128 v[110:113], v136 offset:160
	ds_read_b128 v[114:117], v136 offset:176
	v_lshlrev_b32_e32 v119, 16, v106
	v_and_b32_e32 v106, 0xffff0000, v106
	s_waitcnt lgkmcnt(0)
	v_add_f32_e32 v110, v110, v119
	v_add_f32_e32 v106, v111, v106
	v_cvt_pk_bf16_f32 v106, v110, v106
	v_lshlrev_b32_e32 v110, 16, v107
	v_and_b32_e32 v107, 0xffff0000, v107
	v_add_f32_e32 v110, v112, v110
	v_add_f32_e32 v107, v113, v107
	v_cvt_pk_bf16_f32 v107, v110, v107
	v_lshlrev_b32_e32 v110, 16, v108
	v_and_b32_e32 v108, 0xffff0000, v108
	v_add_f32_e32 v110, v114, v110
	v_add_f32_e32 v108, v115, v108
	v_cvt_pk_bf16_f32 v108, v110, v108
	v_lshlrev_b32_e32 v110, 16, v109
	v_and_b32_e32 v109, 0xffff0000, v109
	v_add_f32_e32 v110, v116, v110
	v_add_f32_e32 v109, v117, v109
	v_and_b32_e32 v111, 0xffff0000, v106
	v_cvt_pk_bf16_f32 v109, v110, v109
	v_lshlrev_b32_e32 v110, 16, v106
	v_mul_f32_e32 v111, v111, v111
	v_lshlrev_b32_e32 v112, 16, v107
	v_fmac_f32_e32 v111, v110, v110
	v_and_b32_e32 v113, 0xffff0000, v107
	v_fmac_f32_e32 v111, v112, v112
	v_lshlrev_b32_e32 v114, 16, v108
	v_fmac_f32_e32 v111, v113, v113
	v_and_b32_e32 v115, 0xffff0000, v108
	v_fmac_f32_e32 v111, v114, v114
	v_lshlrev_b32_e32 v116, 16, v109
	v_fmac_f32_e32 v111, v115, v115
	v_and_b32_e32 v117, 0xffff0000, v109
	v_fmac_f32_e32 v111, v116, v116
	v_fmac_f32_e32 v111, v117, v117
	ds_write_b128 v136, v[106:109] offset:80
	v_add_f32_e32 v114, v118, v111
	ds_read_b128 v[106:109], v136 offset:192
	ds_read_b128 v[110:113], v136 offset:208
	v_lshlrev_b32_e32 v115, 16, v102
	v_and_b32_e32 v102, 0xffff0000, v102
	s_waitcnt lgkmcnt(0)
	v_add_f32_e32 v106, v106, v115
	v_add_f32_e32 v102, v107, v102
	v_cvt_pk_bf16_f32 v102, v106, v102
	v_lshlrev_b32_e32 v106, 16, v103
	v_and_b32_e32 v103, 0xffff0000, v103
	v_add_f32_e32 v106, v108, v106
	v_add_f32_e32 v103, v109, v103
	v_cvt_pk_bf16_f32 v103, v106, v103
	v_lshlrev_b32_e32 v106, 16, v104
	v_and_b32_e32 v104, 0xffff0000, v104
	v_add_f32_e32 v106, v110, v106
	v_add_f32_e32 v104, v111, v104
	v_cvt_pk_bf16_f32 v104, v106, v104
	v_lshlrev_b32_e32 v106, 16, v105
	v_and_b32_e32 v105, 0xffff0000, v105
	v_add_f32_e32 v106, v112, v106
	v_add_f32_e32 v105, v113, v105
	v_and_b32_e32 v107, 0xffff0000, v102
	v_cvt_pk_bf16_f32 v105, v106, v105
	v_lshlrev_b32_e32 v106, 16, v102
	v_mul_f32_e32 v107, v107, v107
	v_lshlrev_b32_e32 v108, 16, v103
	v_fmac_f32_e32 v107, v106, v106
	v_and_b32_e32 v109, 0xffff0000, v103
	v_fmac_f32_e32 v107, v108, v108
	v_lshlrev_b32_e32 v110, 16, v104
	v_fmac_f32_e32 v107, v109, v109
	v_and_b32_e32 v111, 0xffff0000, v104
	v_fmac_f32_e32 v107, v110, v110
	v_lshlrev_b32_e32 v112, 16, v105
	v_fmac_f32_e32 v107, v111, v111
	v_and_b32_e32 v113, 0xffff0000, v105
	v_fmac_f32_e32 v107, v112, v112
	v_fmac_f32_e32 v107, v113, v113
	ds_write_b128 v136, v[102:105] offset:96
	v_add_f32_e32 v110, v114, v107
	ds_read_b128 v[102:105], v136 offset:224
	ds_read_b128 v[106:109], v136 offset:240
	v_lshlrev_b32_e32 v111, 16, v98
	v_and_b32_e32 v98, 0xffff0000, v98
	s_waitcnt lgkmcnt(0)
	v_add_f32_e32 v102, v102, v111
	v_add_f32_e32 v98, v103, v98
	v_cvt_pk_bf16_f32 v98, v102, v98
	v_lshlrev_b32_e32 v102, 16, v99
	v_and_b32_e32 v99, 0xffff0000, v99
	v_add_f32_e32 v102, v104, v102
	v_add_f32_e32 v99, v105, v99
	v_cvt_pk_bf16_f32 v99, v102, v99
	v_lshlrev_b32_e32 v102, 16, v100
	v_and_b32_e32 v100, 0xffff0000, v100
	v_add_f32_e32 v102, v106, v102
	v_add_f32_e32 v100, v107, v100
	v_cvt_pk_bf16_f32 v100, v102, v100
	v_lshlrev_b32_e32 v102, 16, v101
	v_and_b32_e32 v101, 0xffff0000, v101
	v_add_f32_e32 v102, v108, v102
	v_add_f32_e32 v101, v109, v101
	v_and_b32_e32 v103, 0xffff0000, v98
	v_cvt_pk_bf16_f32 v101, v102, v101
	v_lshlrev_b32_e32 v102, 16, v98
	v_mul_f32_e32 v103, v103, v103
	v_lshlrev_b32_e32 v104, 16, v99
	v_fmac_f32_e32 v103, v102, v102
	v_and_b32_e32 v105, 0xffff0000, v99
	v_fmac_f32_e32 v103, v104, v104
	v_lshlrev_b32_e32 v106, 16, v100
	v_fmac_f32_e32 v103, v105, v105
	v_and_b32_e32 v107, 0xffff0000, v100
	v_fmac_f32_e32 v103, v106, v106
	v_lshlrev_b32_e32 v108, 16, v101
	v_fmac_f32_e32 v103, v107, v107
	v_and_b32_e32 v109, 0xffff0000, v101
	v_fmac_f32_e32 v103, v108, v108
	ds_write_b128 v136, v[98:101] offset:112
	v_and_b32_e32 v102, 63, v170
	v_lshrrev_b32_e32 v108, 3, v102
	v_sub_u32_e32 v108, v108, v102
	v_and_b32_e32 v102, 7, v102
	v_lshlrev_b32_e32 v102, 4, v102
	v_mul_i32_i24_e32 v98, 0x800, v108
	v_add_u32_e32 v98, v98, v102
	v_mul_i32_i24_e32 v108, 0x110, v108
	v_add3_u32 v108, v108, v102, v136
	s_waitcnt lgkmcnt(0)
	ds_read_b128 v[104:107], v108 offset:0
	v_mov_b32_e32 v100, v98
	v_ashrrev_i32_e32 v101, 31, v100
	v_lshl_add_u64 v[116:117], v[100:101], 0, v[128:129]
	s_waitcnt lgkmcnt(0)
	global_store_dwordx4 v[116:117], v[104:107], off
	ds_read_b128 v[112:115], v108 offset:2176
	v_add_u32_e32 v100, 0x4000, v98
	v_ashrrev_i32_e32 v101, 31, v100
	v_lshl_add_u64 v[116:117], v[100:101], 0, v[128:129]
	s_waitcnt lgkmcnt(0)
	global_store_dwordx4 v[116:117], v[112:115], off
	ds_read_b128 v[104:107], v108 offset:4352
	v_add_u32_e32 v100, 0x8000, v98
	v_ashrrev_i32_e32 v101, 31, v100
	v_lshl_add_u64 v[116:117], v[100:101], 0, v[128:129]
	s_waitcnt lgkmcnt(0)
	global_store_dwordx4 v[116:117], v[104:107], off
	ds_read_b128 v[112:115], v108 offset:6528
	v_add_u32_e32 v100, 0xc000, v98
	v_ashrrev_i32_e32 v101, 31, v100
	v_lshl_add_u64 v[116:117], v[100:101], 0, v[128:129]
	s_waitcnt lgkmcnt(0)
	global_store_dwordx4 v[116:117], v[112:115], off
	ds_read_b128 v[104:107], v108 offset:8704
	v_add_u32_e32 v100, 0x10000, v98
	v_ashrrev_i32_e32 v101, 31, v100
	v_lshl_add_u64 v[116:117], v[100:101], 0, v[128:129]
	s_waitcnt lgkmcnt(0)
	global_store_dwordx4 v[116:117], v[104:107], off
	ds_read_b128 v[112:115], v108 offset:10880
	v_add_u32_e32 v100, 0x14000, v98
	v_ashrrev_i32_e32 v101, 31, v100
	v_lshl_add_u64 v[116:117], v[100:101], 0, v[128:129]
	s_waitcnt lgkmcnt(0)
	global_store_dwordx4 v[116:117], v[112:115], off
	ds_read_b128 v[104:107], v108 offset:13056
	v_add_u32_e32 v100, 0x18000, v98
	v_ashrrev_i32_e32 v101, 31, v100
	v_lshl_add_u64 v[116:117], v[100:101], 0, v[128:129]
	s_waitcnt lgkmcnt(0)
	global_store_dwordx4 v[116:117], v[104:107], off
	ds_read_b128 v[112:115], v108 offset:15232
	v_add_u32_e32 v100, 0x1c000, v98
	v_ashrrev_i32_e32 v101, 31, v100
	v_lshl_add_u64 v[116:117], v[100:101], 0, v[128:129]
	s_waitcnt lgkmcnt(0)
	global_store_dwordx4 v[116:117], v[112:115], off
	v_fmac_f32_e32 v103, v109, v109
	v_add_f32_e32 v102, v110, v103
	v_lshlrev_b64 v[98:99], 6, v[126:127]
	v_lshl_add_u64 v[98:99], s[6:7], 0, v[98:99]
	v_lshl_add_u64 v[98:99], v[98:99], 0, s[16:17]
	flat_store_dword v[98:99], v102
	s_waitcnt lgkmcnt(0)
	s_barrier
	ds_write2_b32 v1, v62, v74 offset1:16
	ds_write2_b32 v1, v63, v75 offset0:68 offset1:84
	ds_write2_b32 v1, v64, v76 offset0:136 offset1:152
	ds_write2_b32 v1, v65, v77 offset0:204 offset1:220
	ds_write2_b32 v1, v78, v82 offset0:32 offset1:48
	ds_write2_b32 v1, v79, v83 offset0:100 offset1:116
	ds_write2_b32 v1, v80, v84 offset0:168 offset1:184
	ds_write2_b32 v1, v81, v85 offset0:236 offset1:252
	ds_write2_b32 v130, v46, v54 offset0:64 offset1:80
	ds_write2_b32 v130, v47, v55 offset0:132 offset1:148
	ds_write2_b32 v130, v48, v56 offset0:200 offset1:216
	ds_write2_b32 v131, v49, v57 offset0:12 offset1:28
	ds_write2_b32 v130, v58, v66 offset0:96 offset1:112
	ds_write2_b32 v130, v59, v67 offset0:164 offset1:180
	ds_write2_b32 v130, v60, v68 offset0:232 offset1:248
	ds_write2_b32 v131, v61, v69 offset0:44 offset1:60
	ds_write2_b32 v132, v30, v38 offset0:128 offset1:144
	ds_write2_b32 v132, v31, v39 offset0:196 offset1:212
	ds_write2_b32 v133, v32, v40 offset0:8 offset1:24
	ds_write2_b32 v133, v33, v41 offset0:76 offset1:92
	ds_write2_b32 v132, v42, v50 offset0:160 offset1:176
	ds_write2_b32 v132, v43, v51 offset0:228 offset1:244
	ds_write2_b32 v133, v44, v52 offset0:40 offset1:56
	ds_write2_b32 v133, v45, v53 offset0:108 offset1:124
	ds_write2_b32 v135, v18, v22 offset0:192 offset1:208
	ds_write2_b32 v134, v19, v23 offset0:4 offset1:20
	ds_write2_b32 v134, v20, v24 offset0:72 offset1:88
	ds_write2_b32 v134, v21, v25 offset0:140 offset1:156
	ds_write2_b32 v135, v26, v34 offset0:224 offset1:240
	ds_write2_b32 v134, v27, v35 offset0:36 offset1:52
	ds_write2_b32 v134, v28, v36 offset0:104 offset1:120
	ds_write2_b32 v134, v29, v37 offset0:172 offset1:188
	v_mov_b32_e32 v1, v170
	s_waitcnt lgkmcnt(0)
	s_barrier
	s_waitcnt vmcnt(0)
	v_lshlrev_b32_e32 v28, 16, v94
	v_add_u32_e32 v18, s4, v1
	v_ashrrev_i32_e32 v19, 31, v18
	v_lshlrev_b64 v[20:21], 11, v[18:19]
	v_lshl_add_u64 v[20:21], s[38:39], 0, v[20:21]
	v_mul_lo_u32 v1, v1, s33
	v_lshl_add_u64 v[32:33], v[20:21], 0, s[18:19]
	ds_read_b128 v[20:23], v1
	ds_read_b128 v[24:27], v1 offset:16
	s_mov_b64 s[4:5], 0
	s_waitcnt lgkmcnt(1)
	v_add_f32_e32 v20, v20, v28
	v_and_b32_e32 v28, 0xffff0000, v94
	v_add_f32_e32 v21, v21, v28
	v_cvt_pk_bf16_f32 v28, v20, v21
	v_and_b32_e32 v21, 0xffff0000, v95
	v_lshlrev_b32_e32 v20, 16, v95
	v_add_f32_e32 v21, v23, v21
	v_add_f32_e32 v20, v22, v20
	v_cvt_pk_bf16_f32 v29, v20, v21
	v_and_b32_e32 v21, 0xffff0000, v96
	v_lshlrev_b32_e32 v20, 16, v96
	s_waitcnt lgkmcnt(0)
	v_add_f32_e32 v21, v25, v21
	v_add_f32_e32 v20, v24, v20
	v_cvt_pk_bf16_f32 v30, v20, v21
	v_and_b32_e32 v21, 0xffff0000, v97
	v_lshlrev_b32_e32 v20, 16, v97
	v_add_f32_e32 v21, v27, v21
	v_add_f32_e32 v20, v26, v20
	v_cvt_pk_bf16_f32 v31, v20, v21
	v_and_b32_e32 v21, 0xffff0000, v28
	v_lshlrev_b32_e32 v20, 16, v28
	v_mul_f32_e32 v34, v21, v21
	v_lshlrev_b32_e32 v22, 16, v29
	v_fmac_f32_e32 v34, v20, v20
	v_and_b32_e32 v23, 0xffff0000, v29
	v_fmac_f32_e32 v34, v22, v22
	v_lshlrev_b32_e32 v24, 16, v30
	v_fmac_f32_e32 v34, v23, v23
	v_and_b32_e32 v25, 0xffff0000, v30
	v_fmac_f32_e32 v34, v24, v24
	v_add_co_u32_e32 v20, vcc, s90, v32
	v_lshlrev_b32_e32 v26, 16, v31
	v_fmac_f32_e32 v34, v25, v25
	v_addc_co_u32_e32 v21, vcc, 0, v33, vcc
	v_and_b32_e32 v27, 0xffff0000, v31
	v_fmac_f32_e32 v34, v26, v26
	v_mul_u32_u24_e32 v35, 0x110, v170
	ds_write_b128 v35, v[28:31]
	v_fmac_f32_e32 v34, v27, v27
	ds_read_b128 v[22:25], v1 offset:32
	ds_read_b128 v[26:29], v1 offset:48
	v_lshlrev_b32_e32 v30, 16, v90
	s_waitcnt lgkmcnt(0)
	v_add_f32_e32 v22, v22, v30
	v_and_b32_e32 v30, 0xffff0000, v90
	v_add_f32_e32 v23, v23, v30
	v_cvt_pk_bf16_f32 v22, v22, v23
	v_lshlrev_b32_e32 v23, 16, v91
	v_add_f32_e32 v23, v24, v23
	v_and_b32_e32 v24, 0xffff0000, v91
	v_add_f32_e32 v24, v25, v24
	v_cvt_pk_bf16_f32 v23, v23, v24
	v_lshlrev_b32_e32 v24, 16, v92
	v_and_b32_e32 v25, 0xffff0000, v92
	v_add_f32_e32 v24, v26, v24
	v_add_f32_e32 v25, v27, v25
	v_cvt_pk_bf16_f32 v24, v24, v25
	v_lshlrev_b32_e32 v25, 16, v93
	v_and_b32_e32 v26, 0xffff0000, v93
	v_add_f32_e32 v25, v28, v25
	v_add_f32_e32 v26, v29, v26
	v_and_b32_e32 v27, 0xffff0000, v22
	v_cvt_pk_bf16_f32 v25, v25, v26
	v_lshlrev_b32_e32 v26, 16, v22
	v_mul_f32_e32 v27, v27, v27
	v_lshlrev_b32_e32 v28, 16, v23
	v_fmac_f32_e32 v27, v26, v26
	v_and_b32_e32 v29, 0xffff0000, v23
	v_fmac_f32_e32 v27, v28, v28
	v_lshlrev_b32_e32 v30, 16, v24
	v_fmac_f32_e32 v27, v29, v29
	v_and_b32_e32 v31, 0xffff0000, v24
	v_fmac_f32_e32 v27, v30, v30
	v_lshlrev_b32_e32 v32, 16, v25
	v_fmac_f32_e32 v27, v31, v31
	v_and_b32_e32 v33, 0xffff0000, v25
	v_fmac_f32_e32 v27, v32, v32
	v_fmac_f32_e32 v27, v33, v33
	ds_write_b128 v35, v[22:25] offset:16
	v_add_f32_e32 v30, v34, v27
	ds_read_b128 v[22:25], v1 offset:64
	ds_read_b128 v[26:29], v1 offset:80
	v_lshlrev_b32_e32 v31, 16, v86
	s_waitcnt lgkmcnt(0)
	v_add_f32_e32 v22, v22, v31
	v_and_b32_e32 v31, 0xffff0000, v86
	v_add_f32_e32 v23, v23, v31
	v_cvt_pk_bf16_f32 v22, v22, v23
	v_lshlrev_b32_e32 v23, 16, v87
	v_add_f32_e32 v23, v24, v23
	v_and_b32_e32 v24, 0xffff0000, v87
	v_add_f32_e32 v24, v25, v24
	v_cvt_pk_bf16_f32 v23, v23, v24
	v_lshlrev_b32_e32 v24, 16, v88
	v_and_b32_e32 v25, 0xffff0000, v88
	v_add_f32_e32 v24, v26, v24
	v_add_f32_e32 v25, v27, v25
	v_cvt_pk_bf16_f32 v24, v24, v25
	v_lshlrev_b32_e32 v25, 16, v89
	v_and_b32_e32 v26, 0xffff0000, v89
	v_add_f32_e32 v25, v28, v25
	v_add_f32_e32 v26, v29, v26
	v_and_b32_e32 v27, 0xffff0000, v22
	v_cvt_pk_bf16_f32 v25, v25, v26
	v_lshlrev_b32_e32 v26, 16, v22
	v_mul_f32_e32 v27, v27, v27
	v_lshlrev_b32_e32 v28, 16, v23
	v_fmac_f32_e32 v27, v26, v26
	v_and_b32_e32 v29, 0xffff0000, v23
	v_fmac_f32_e32 v27, v28, v28
	v_lshlrev_b32_e32 v31, 16, v24
	v_fmac_f32_e32 v27, v29, v29
	v_and_b32_e32 v32, 0xffff0000, v24
	v_fmac_f32_e32 v27, v31, v31
	v_lshlrev_b32_e32 v33, 16, v25
	v_fmac_f32_e32 v27, v32, v32
	v_and_b32_e32 v34, 0xffff0000, v25
	v_fmac_f32_e32 v27, v33, v33
	v_fmac_f32_e32 v27, v34, v34
	ds_write_b128 v35, v[22:25] offset:32
	v_add_f32_e32 v30, v30, v27
	ds_read_b128 v[22:25], v1 offset:96
	ds_read_b128 v[26:29], v1 offset:112
	v_lshlrev_b32_e32 v31, 16, v70
	s_waitcnt lgkmcnt(0)
	v_add_f32_e32 v22, v22, v31
	v_and_b32_e32 v31, 0xffff0000, v70
	v_add_f32_e32 v23, v23, v31
	v_cvt_pk_bf16_f32 v22, v22, v23
	v_lshlrev_b32_e32 v23, 16, v71
	v_add_f32_e32 v23, v24, v23
	v_and_b32_e32 v24, 0xffff0000, v71
	v_add_f32_e32 v24, v25, v24
	v_cvt_pk_bf16_f32 v23, v23, v24
	v_lshlrev_b32_e32 v24, 16, v72
	v_and_b32_e32 v25, 0xffff0000, v72
	v_add_f32_e32 v24, v26, v24
	v_add_f32_e32 v25, v27, v25
	v_cvt_pk_bf16_f32 v24, v24, v25
	v_lshlrev_b32_e32 v25, 16, v73
	v_and_b32_e32 v26, 0xffff0000, v73
	v_add_f32_e32 v25, v28, v25
	v_add_f32_e32 v26, v29, v26
	v_and_b32_e32 v27, 0xffff0000, v22
	v_cvt_pk_bf16_f32 v25, v25, v26
	v_lshlrev_b32_e32 v26, 16, v22
	v_mul_f32_e32 v27, v27, v27
	v_lshlrev_b32_e32 v28, 16, v23
	v_fmac_f32_e32 v27, v26, v26
	v_and_b32_e32 v29, 0xffff0000, v23
	v_fmac_f32_e32 v27, v28, v28
	v_lshlrev_b32_e32 v31, 16, v24
	v_fmac_f32_e32 v27, v29, v29
	v_and_b32_e32 v32, 0xffff0000, v24
	v_fmac_f32_e32 v27, v31, v31
	v_lshlrev_b32_e32 v33, 16, v25
	v_fmac_f32_e32 v27, v32, v32
	v_and_b32_e32 v34, 0xffff0000, v25
	v_fmac_f32_e32 v27, v33, v33
	v_fmac_f32_e32 v27, v34, v34
	ds_write_b128 v35, v[22:25] offset:48
	v_add_f32_e32 v30, v30, v27
	ds_read_b128 v[22:25], v1 offset:128
	ds_read_b128 v[26:29], v1 offset:144
	v_lshlrev_b32_e32 v31, 16, v14
	v_and_b32_e32 v14, 0xffff0000, v14
	s_waitcnt lgkmcnt(0)
	v_add_f32_e32 v22, v22, v31
	v_add_f32_e32 v14, v23, v14
	v_cvt_pk_bf16_f32 v14, v22, v14
	v_lshlrev_b32_e32 v22, 16, v15
	v_and_b32_e32 v15, 0xffff0000, v15
	v_add_f32_e32 v22, v24, v22
	v_add_f32_e32 v15, v25, v15
	v_cvt_pk_bf16_f32 v15, v22, v15
	v_lshlrev_b32_e32 v22, 16, v16
	v_and_b32_e32 v16, 0xffff0000, v16
	v_add_f32_e32 v22, v26, v22
	v_add_f32_e32 v16, v27, v16
	v_cvt_pk_bf16_f32 v16, v22, v16
	v_lshlrev_b32_e32 v22, 16, v17
	v_and_b32_e32 v17, 0xffff0000, v17
	v_add_f32_e32 v22, v28, v22
	v_add_f32_e32 v17, v29, v17
	v_and_b32_e32 v23, 0xffff0000, v14
	v_cvt_pk_bf16_f32 v17, v22, v17
	v_lshlrev_b32_e32 v22, 16, v14
	v_mul_f32_e32 v23, v23, v23
	v_lshlrev_b32_e32 v24, 16, v15
	v_fmac_f32_e32 v23, v22, v22
	v_and_b32_e32 v25, 0xffff0000, v15
	v_fmac_f32_e32 v23, v24, v24
	v_lshlrev_b32_e32 v26, 16, v16
	v_fmac_f32_e32 v23, v25, v25
	v_and_b32_e32 v27, 0xffff0000, v16
	v_fmac_f32_e32 v23, v26, v26
	v_lshlrev_b32_e32 v28, 16, v17
	v_fmac_f32_e32 v23, v27, v27
	v_and_b32_e32 v29, 0xffff0000, v17
	v_fmac_f32_e32 v23, v28, v28
	v_fmac_f32_e32 v23, v29, v29
	ds_write_b128 v35, v[14:17] offset:64
	v_add_f32_e32 v26, v30, v23
	ds_read_b128 v[14:17], v1 offset:160
	ds_read_b128 v[22:25], v1 offset:176
	v_lshlrev_b32_e32 v27, 16, v10
	v_and_b32_e32 v10, 0xffff0000, v10
	s_waitcnt lgkmcnt(0)
	v_add_f32_e32 v14, v14, v27
	v_add_f32_e32 v10, v15, v10
	v_cvt_pk_bf16_f32 v10, v14, v10
	v_lshlrev_b32_e32 v14, 16, v11
	v_and_b32_e32 v11, 0xffff0000, v11
	v_add_f32_e32 v14, v16, v14
	v_add_f32_e32 v11, v17, v11
	v_cvt_pk_bf16_f32 v11, v14, v11
	v_lshlrev_b32_e32 v14, 16, v12
	v_and_b32_e32 v12, 0xffff0000, v12
	v_add_f32_e32 v14, v22, v14
	v_add_f32_e32 v12, v23, v12
	v_cvt_pk_bf16_f32 v12, v14, v12
	v_lshlrev_b32_e32 v14, 16, v13
	v_and_b32_e32 v13, 0xffff0000, v13
	v_add_f32_e32 v14, v24, v14
	v_add_f32_e32 v13, v25, v13
	v_and_b32_e32 v15, 0xffff0000, v10
	v_cvt_pk_bf16_f32 v13, v14, v13
	v_lshlrev_b32_e32 v14, 16, v10
	v_mul_f32_e32 v15, v15, v15
	v_lshlrev_b32_e32 v16, 16, v11
	v_fmac_f32_e32 v15, v14, v14
	v_and_b32_e32 v17, 0xffff0000, v11
	v_fmac_f32_e32 v15, v16, v16
	v_lshlrev_b32_e32 v22, 16, v12
	v_fmac_f32_e32 v15, v17, v17
	v_and_b32_e32 v23, 0xffff0000, v12
	v_fmac_f32_e32 v15, v22, v22
	v_lshlrev_b32_e32 v24, 16, v13
	v_fmac_f32_e32 v15, v23, v23
	v_and_b32_e32 v25, 0xffff0000, v13
	v_fmac_f32_e32 v15, v24, v24
	v_fmac_f32_e32 v15, v25, v25
	ds_write_b128 v35, v[10:13] offset:80
	v_add_f32_e32 v22, v26, v15
	ds_read_b128 v[10:13], v1 offset:192
	ds_read_b128 v[14:17], v1 offset:208
	v_lshlrev_b32_e32 v23, 16, v6
	v_and_b32_e32 v6, 0xffff0000, v6
	s_waitcnt lgkmcnt(0)
	v_add_f32_e32 v10, v10, v23
	v_add_f32_e32 v6, v11, v6
	v_cvt_pk_bf16_f32 v6, v10, v6
	v_lshlrev_b32_e32 v10, 16, v7
	v_and_b32_e32 v7, 0xffff0000, v7
	v_add_f32_e32 v10, v12, v10
	v_add_f32_e32 v7, v13, v7
	v_cvt_pk_bf16_f32 v7, v10, v7
	v_lshlrev_b32_e32 v10, 16, v8
	v_and_b32_e32 v8, 0xffff0000, v8
	v_add_f32_e32 v10, v14, v10
	v_add_f32_e32 v8, v15, v8
	v_cvt_pk_bf16_f32 v8, v10, v8
	v_lshlrev_b32_e32 v10, 16, v9
	v_and_b32_e32 v9, 0xffff0000, v9
	v_add_f32_e32 v10, v16, v10
	v_add_f32_e32 v9, v17, v9
	v_and_b32_e32 v11, 0xffff0000, v6
	v_cvt_pk_bf16_f32 v9, v10, v9
	v_lshlrev_b32_e32 v10, 16, v6
	v_mul_f32_e32 v11, v11, v11
	v_lshlrev_b32_e32 v12, 16, v7
	v_fmac_f32_e32 v11, v10, v10
	v_and_b32_e32 v13, 0xffff0000, v7
	v_fmac_f32_e32 v11, v12, v12
	v_lshlrev_b32_e32 v14, 16, v8
	v_fmac_f32_e32 v11, v13, v13
	v_and_b32_e32 v15, 0xffff0000, v8
	v_fmac_f32_e32 v11, v14, v14
	v_lshlrev_b32_e32 v16, 16, v9
	v_fmac_f32_e32 v11, v15, v15
	v_and_b32_e32 v17, 0xffff0000, v9
	v_fmac_f32_e32 v11, v16, v16
	v_fmac_f32_e32 v11, v17, v17
	ds_write_b128 v35, v[6:9] offset:96
	v_add_f32_e32 v14, v22, v11
	ds_read_b128 v[6:9], v1 offset:224
	ds_read_b128 v[10:13], v1 offset:240
	v_lshlrev_b32_e32 v1, 16, v2
	v_and_b32_e32 v2, 0xffff0000, v2
	s_waitcnt lgkmcnt(0)
	v_add_f32_e32 v1, v6, v1
	v_add_f32_e32 v2, v7, v2
	v_cvt_pk_bf16_f32 v2, v1, v2
	v_lshlrev_b32_e32 v1, 16, v3
	v_and_b32_e32 v3, 0xffff0000, v3
	v_add_f32_e32 v1, v8, v1
	v_add_f32_e32 v3, v9, v3
	v_cvt_pk_bf16_f32 v3, v1, v3
	v_lshlrev_b32_e32 v1, 16, v4
	v_and_b32_e32 v4, 0xffff0000, v4
	v_add_f32_e32 v1, v10, v1
	v_add_f32_e32 v4, v11, v4
	v_cvt_pk_bf16_f32 v4, v1, v4
	v_lshlrev_b32_e32 v1, 16, v5
	v_and_b32_e32 v5, 0xffff0000, v5
	v_add_f32_e32 v1, v12, v1
	v_add_f32_e32 v5, v13, v5
	v_and_b32_e32 v6, 0xffff0000, v2
	v_cvt_pk_bf16_f32 v5, v1, v5
	v_lshlrev_b32_e32 v1, 16, v2
	v_mul_f32_e32 v6, v6, v6
	v_lshlrev_b32_e32 v7, 16, v3
	v_fmac_f32_e32 v6, v1, v1
	v_and_b32_e32 v8, 0xffff0000, v3
	v_fmac_f32_e32 v6, v7, v7
	v_lshlrev_b32_e32 v9, 16, v4
	v_fmac_f32_e32 v6, v8, v8
	v_and_b32_e32 v10, 0xffff0000, v4
	v_fmac_f32_e32 v6, v9, v9
	v_lshlrev_b32_e32 v11, 16, v5
	v_fmac_f32_e32 v6, v10, v10
	v_and_b32_e32 v12, 0xffff0000, v5
	v_fmac_f32_e32 v6, v11, v11
	ds_write_b128 v35, v[2:5] offset:112
	v_and_b32_e32 v7, 63, v170
	v_lshrrev_b32_e32 v13, 3, v7
	v_sub_u32_e32 v13, v13, v7
	v_and_b32_e32 v7, 7, v7
	v_lshlrev_b32_e32 v7, 4, v7
	v_mul_i32_i24_e32 v2, 0x800, v13
	v_add_u32_e32 v2, v2, v7
	v_mul_i32_i24_e32 v13, 0x110, v13
	v_add3_u32 v13, v13, v7, v35
	s_waitcnt lgkmcnt(0)
	ds_read_b128 v[8:11], v13 offset:0
	v_mov_b32_e32 v4, v2
	v_ashrrev_i32_e32 v5, 31, v4
	v_lshl_add_u64 v[16:17], v[4:5], 0, v[20:21]
	s_waitcnt lgkmcnt(0)
	global_store_dwordx4 v[16:17], v[8:11], off offset:128
	ds_read_b128 v[24:27], v13 offset:2176
	v_add_u32_e32 v4, 0x4000, v2
	v_ashrrev_i32_e32 v5, 31, v4
	v_lshl_add_u64 v[16:17], v[4:5], 0, v[20:21]
	s_waitcnt lgkmcnt(0)
	global_store_dwordx4 v[16:17], v[24:27], off offset:128
	ds_read_b128 v[8:11], v13 offset:4352
	v_add_u32_e32 v4, 0x8000, v2
	v_ashrrev_i32_e32 v5, 31, v4
	v_lshl_add_u64 v[16:17], v[4:5], 0, v[20:21]
	s_waitcnt lgkmcnt(0)
	global_store_dwordx4 v[16:17], v[8:11], off offset:128
	ds_read_b128 v[24:27], v13 offset:6528
	v_add_u32_e32 v4, 0xc000, v2
	v_ashrrev_i32_e32 v5, 31, v4
	v_lshl_add_u64 v[16:17], v[4:5], 0, v[20:21]
	s_waitcnt lgkmcnt(0)
	global_store_dwordx4 v[16:17], v[24:27], off offset:128
	ds_read_b128 v[8:11], v13 offset:8704
	v_add_u32_e32 v4, 0x10000, v2
	v_ashrrev_i32_e32 v5, 31, v4
	v_lshl_add_u64 v[16:17], v[4:5], 0, v[20:21]
	s_waitcnt lgkmcnt(0)
	global_store_dwordx4 v[16:17], v[8:11], off offset:128
	ds_read_b128 v[24:27], v13 offset:10880
	v_add_u32_e32 v4, 0x14000, v2
	v_ashrrev_i32_e32 v5, 31, v4
	v_lshl_add_u64 v[16:17], v[4:5], 0, v[20:21]
	s_waitcnt lgkmcnt(0)
	global_store_dwordx4 v[16:17], v[24:27], off offset:128
	ds_read_b128 v[8:11], v13 offset:13056
	v_add_u32_e32 v4, 0x18000, v2
	v_ashrrev_i32_e32 v5, 31, v4
	v_lshl_add_u64 v[16:17], v[4:5], 0, v[20:21]
	s_waitcnt lgkmcnt(0)
	global_store_dwordx4 v[16:17], v[8:11], off offset:128
	ds_read_b128 v[24:27], v13 offset:15232
	v_add_u32_e32 v4, 0x1c000, v2
	v_ashrrev_i32_e32 v5, 31, v4
	v_lshl_add_u64 v[16:17], v[4:5], 0, v[20:21]
	s_waitcnt lgkmcnt(0)
	global_store_dwordx4 v[16:17], v[24:27], off offset:128
	v_fmac_f32_e32 v6, v12, v12
	v_add_f32_e32 v1, v14, v6
	v_lshlrev_b64 v[2:3], 6, v[18:19]
	v_lshl_add_u64 v[2:3], s[6:7], 0, v[2:3]
	v_lshl_add_u64 v[2:3], v[2:3], 0, s[16:17]
	flat_store_dword v[2:3], v1 offset:4
	s_branch .LBB0_522

.LBB0_553:
	s_mul_i32 s31, s7, 0x6000
	s_add_i32 s40, s31, 0xffffa000
	s_cmp_lg_u32 s7, 0
	s_cselect_b32 s40, s40, 0xc000
	v_add_u32_e32 v153, s40, v147
	v_add_u32_e32 v156, 0x1000, v153
	v_readfirstlane_b32 s40, v153
	s_waitcnt vmcnt(6)
	s_barrier
	v_lshl_add_u64 v[154:155], v[140:141], 0, s[46:47]
	s_mov_b32 m0, s40
	v_readfirstlane_b32 s40, v156
	v_add_u32_e32 v156, 0x2000, v153
	global_load_lds_dwordx4 v[154:155], off
	v_lshl_add_u64 v[154:155], v[138:139], 0, s[46:47]
	s_mov_b32 m0, s40
	v_readfirstlane_b32 s40, v156
	v_add_u32_e32 v156, 0x3000, v153
	global_load_lds_dwordx4 v[154:155], off
	v_lshl_add_u64 v[154:155], v[136:137], 0, s[46:47]
	s_mov_b32 m0, s40
	v_readfirstlane_b32 s40, v156
	v_add_u32_e32 v156, 0x4000, v153
	global_load_lds_dwordx4 v[154:155], off
	v_lshl_add_u64 v[154:155], v[134:135], 0, s[46:47]
	s_mov_b32 m0, s40
	v_readfirstlane_b32 s40, v156
	v_add_u32_e32 v153, 0x5000, v153
	global_load_lds_dwordx4 v[154:155], off
	v_lshl_add_u64 v[154:155], v[132:133], 0, s[46:47]
	s_mov_b32 m0, s40
	v_readfirstlane_b32 s40, v153
	global_load_lds_dwordx4 v[154:155], off
	v_lshl_add_u64 v[154:155], v[130:131], 0, s[46:47]
	s_mov_b32 m0, s40
	v_or_b32_e32 v153, s31, v151
	global_load_lds_dwordx4 v[154:155], off
	v_add_u32_e32 v153, v153, v149
	ds_read_b128 v[158:161], v153
	ds_read_b128 v[162:165], v153 offset:1024
	ds_read_b128 v[166:169], v153 offset:2048
	ds_read_b128 v[192:195], v153 offset:3072
	v_or_b32_e32 v153, s31, v145
	ds_read_b128 v[196:199], v153 offset:16384
	ds_read_b128 v[200:203], v153 offset:17408
	ds_read_b128 v[204:207], v153 offset:18432
	ds_read_b128 v[208:211], v153 offset:19456
	ds_read_b128 v[212:215], v153 offset:20480
	ds_read_b128 v[216:219], v153 offset:21504
	ds_read_b128 v[220:223], v153 offset:22528
	ds_read_b128 v[224:227], v153 offset:23552
	s_add_i32 s31, s7, 1
	s_waitcnt lgkmcnt(0)
	v_mfma_f32_16x16x32_bf16 v[126:129], v[158:161], v[196:199], v[126:129]
	s_cmp_lg_u32 s7, 2
	s_cselect_b32 s7, s31, 0
	s_add_u32 s46, s46, 64
	v_mfma_f32_16x16x32_bf16 v[114:117], v[162:165], v[196:199], v[114:117]
	s_addc_u32 s47, s47, 0
	s_cmpk_lg_i32 s46, 0x780
	v_mfma_f32_16x16x32_bf16 v[94:97], v[166:169], v[196:199], v[94:97]
	v_mfma_f32_16x16x32_bf16 v[58:61], v[192:195], v[196:199], v[58:61]
	v_mfma_f32_16x16x32_bf16 v[122:125], v[158:161], v[200:203], v[122:125]
	v_mfma_f32_16x16x32_bf16 v[110:113], v[162:165], v[200:203], v[110:113]
	v_mfma_f32_16x16x32_bf16 v[82:85], v[166:169], v[200:203], v[82:85]
	v_mfma_f32_16x16x32_bf16 v[50:53], v[192:195], v[200:203], v[50:53]
	v_mfma_f32_16x16x32_bf16 v[118:121], v[158:161], v[204:207], v[118:121]
	v_mfma_f32_16x16x32_bf16 v[102:105], v[162:165], v[204:207], v[102:105]
	v_mfma_f32_16x16x32_bf16 v[70:73], v[166:169], v[204:207], v[70:73]
	v_mfma_f32_16x16x32_bf16 v[30:33], v[192:195], v[204:207], v[30:33]
	v_mfma_f32_16x16x32_bf16 v[106:109], v[158:161], v[208:211], v[106:109]
	v_mfma_f32_16x16x32_bf16 v[74:77], v[162:165], v[208:211], v[74:77]
	v_mfma_f32_16x16x32_bf16 v[42:45], v[166:169], v[208:211], v[42:45]
	v_mfma_f32_16x16x32_bf16 v[18:21], v[192:195], v[208:211], v[18:21]
	v_mfma_f32_16x16x32_bf16 v[98:101], v[158:161], v[212:215], v[98:101]
	v_mfma_f32_16x16x32_bf16 v[66:69], v[162:165], v[212:215], v[66:69]
	v_mfma_f32_16x16x32_bf16 v[38:41], v[166:169], v[212:215], v[38:41]
	v_mfma_f32_16x16x32_bf16 v[14:17], v[192:195], v[212:215], v[14:17]
	v_mfma_f32_16x16x32_bf16 v[90:93], v[158:161], v[216:219], v[90:93]
	v_mfma_f32_16x16x32_bf16 v[62:65], v[162:165], v[216:219], v[62:65]
	v_mfma_f32_16x16x32_bf16 v[34:37], v[166:169], v[216:219], v[34:37]
	v_mfma_f32_16x16x32_bf16 v[10:13], v[192:195], v[216:219], v[10:13]
	v_mfma_f32_16x16x32_bf16 v[86:89], v[158:161], v[220:223], v[86:89]
	v_mfma_f32_16x16x32_bf16 v[54:57], v[162:165], v[220:223], v[54:57]
	v_mfma_f32_16x16x32_bf16 v[26:29], v[166:169], v[220:223], v[26:29]
	v_mfma_f32_16x16x32_bf16 v[6:9], v[192:195], v[220:223], v[6:9]
	v_mfma_f32_16x16x32_bf16 v[78:81], v[158:161], v[224:227], v[78:81]
	v_mfma_f32_16x16x32_bf16 v[46:49], v[162:165], v[224:227], v[46:49]
	v_mfma_f32_16x16x32_bf16 v[22:25], v[166:169], v[224:227], v[22:25]
	v_mfma_f32_16x16x32_bf16 v[2:5], v[192:195], v[224:227], v[2:5]
	s_cbranch_scc1 .LBB0_553
	s_waitcnt vmcnt(6)
	s_barrier
	v_add_u32_e32 v147, v151, v149
	ds_read_b128 v[130:133], v145 offset:23552
	ds_read_b128 v[134:137], v145 offset:22528
	ds_read_b128 v[138:141], v145 offset:21504
	ds_read_b128 v[158:161], v145 offset:20480
	ds_read_b128 v[162:165], v145 offset:19456
	ds_read_b128 v[166:169], v145 offset:18432
	ds_read_b128 v[192:195], v145 offset:17408
	ds_read_b128 v[196:199], v145 offset:16384
	ds_read_b128 v[200:203], v147 offset:3072
	ds_read_b128 v[204:207], v147 offset:2048
	ds_read_b128 v[208:211], v147 offset:1024
	ds_read_b128 v[212:215], v147
	s_waitcnt lgkmcnt(0)
	v_mfma_f32_16x16x32_bf16 v[126:129], v[212:215], v[196:199], v[126:129]
	s_waitcnt vmcnt(0)
	s_barrier
	v_mfma_f32_16x16x32_bf16 v[122:125], v[212:215], v[192:195], v[122:125]
	s_mul_i32 s31, s5, 0x600000
	s_mul_hi_i32 s7, s5, 0x600000
	s_sext_i32_i8 s5, s6
	v_mfma_f32_16x16x32_bf16 v[30:33], v[200:203], v[166:169], v[30:33]
	s_add_u32 s6, s65, s31
	s_addc_u32 s7, s66, s7
	s_lshl_b32 s40, s5, 7
	v_mfma_f32_16x16x32_bf16 v[66:69], v[208:211], v[158:161], v[66:69]
	s_ashr_i32 s41, s40, 31
	s_lshl_b64 s[46:47], s[40:41], 1
	v_mfma_f32_16x16x32_bf16 v[114:117], v[208:211], v[196:199], v[114:117]
	v_mfma_f32_16x16x32_bf16 v[94:97], v[204:207], v[196:199], v[94:97]
	v_mfma_f32_16x16x32_bf16 v[58:61], v[200:203], v[196:199], v[58:61]
	v_mfma_f32_16x16x32_bf16 v[110:113], v[208:211], v[192:195], v[110:113]
	v_mfma_f32_16x16x32_bf16 v[82:85], v[204:207], v[192:195], v[82:85]
	v_mfma_f32_16x16x32_bf16 v[50:53], v[200:203], v[192:195], v[50:53]
	v_mfma_f32_16x16x32_bf16 v[118:121], v[212:215], v[166:169], v[118:121]
	v_mfma_f32_16x16x32_bf16 v[102:105], v[208:211], v[166:169], v[102:105]
	v_mfma_f32_16x16x32_bf16 v[70:73], v[204:207], v[166:169], v[70:73]
	v_mfma_f32_16x16x32_bf16 v[106:109], v[212:215], v[162:165], v[106:109]
	v_mfma_f32_16x16x32_bf16 v[74:77], v[208:211], v[162:165], v[74:77]
	v_mfma_f32_16x16x32_bf16 v[42:45], v[204:207], v[162:165], v[42:45]
	v_mfma_f32_16x16x32_bf16 v[18:21], v[200:203], v[162:165], v[18:21]
	v_mfma_f32_16x16x32_bf16 v[98:101], v[212:215], v[158:161], v[98:101]
	v_mfma_f32_16x16x32_bf16 v[38:41], v[204:207], v[158:161], v[38:41]
	v_mfma_f32_16x16x32_bf16 v[158:161], v[200:203], v[158:161], v[14:17]
	v_mfma_f32_16x16x32_bf16 v[90:93], v[212:215], v[138:141], v[90:93]
	v_mfma_f32_16x16x32_bf16 v[62:65], v[208:211], v[138:141], v[62:65]
	v_mfma_f32_16x16x32_bf16 v[34:37], v[204:207], v[138:141], v[34:37]
	v_mfma_f32_16x16x32_bf16 v[10:13], v[200:203], v[138:141], v[10:13]
	v_mfma_f32_16x16x32_bf16 v[86:89], v[212:215], v[134:137], v[86:89]
	v_mfma_f32_16x16x32_bf16 v[138:141], v[208:211], v[134:137], v[54:57]
	v_mfma_f32_16x16x32_bf16 v[26:29], v[204:207], v[134:137], v[26:29]
	v_mfma_f32_16x16x32_bf16 v[134:137], v[200:203], v[134:137], v[6:9]
	v_mfma_f32_16x16x32_bf16 v[78:81], v[212:215], v[130:133], v[78:81]
	v_mfma_f32_16x16x32_bf16 v[162:165], v[208:211], v[130:133], v[46:49]
	v_mfma_f32_16x16x32_bf16 v[166:169], v[204:207], v[130:133], v[22:25]
	v_mfma_f32_16x16x32_bf16 v[130:133], v[200:203], v[130:133], v[2:5]
	ds_read_b128 v[192:195], v147 offset:24576
	ds_read_b128 v[196:199], v147 offset:25600
	ds_read_b128 v[200:203], v147 offset:26624
	ds_read_b128 v[204:207], v147 offset:27648
	ds_read_b128 v[2:5], v145 offset:40960
	ds_read_b128 v[6:9], v145 offset:41984
	ds_read_b128 v[14:17], v145 offset:43008
	ds_read_b128 v[22:25], v145 offset:44032
	ds_read_b128 v[54:57], v145 offset:45056
	ds_read_b128 v[208:211], v145 offset:46080
	ds_read_b128 v[212:215], v145 offset:47104
	ds_read_b128 v[216:219], v145 offset:48128
	s_waitcnt vmcnt(0) lgkmcnt(0)
	s_barrier
	v_mfma_f32_16x16x32_bf16 v[126:129], v[192:195], v[2:5], v[126:129]
	v_mfma_f32_16x16x32_bf16 v[122:125], v[192:195], v[6:9], v[122:125]
	v_mfma_f32_16x16x32_bf16 v[232:235], v[204:207], v[14:17], v[30:33]
	v_mfma_f32_16x16x32_bf16 v[30:33], v[196:199], v[54:57], v[66:69]
	s_nop 2
	v_and_b32_e32 v66, 0xfffffc0, v142
	v_mfma_f32_16x16x32_bf16 v[114:117], v[196:199], v[2:5], v[114:117]
	v_lshl_or_b32 v66, v144, 2, v66
	v_mul_lo_u32 v66, v66, s33
	v_lshl_or_b32 v66, v143, 2, v66
	v_mfma_f32_16x16x32_bf16 v[94:97], v[200:203], v[2:5], v[94:97]
	v_add_u32_e32 v67, 0x1000, v66
	v_add_u32_e32 v68, 0x1400, v66
	v_add_u32_e32 v69, 0x2000, v66
	v_mfma_f32_16x16x32_bf16 v[220:223], v[204:207], v[2:5], v[58:61]
	v_mfma_f32_16x16x32_bf16 v[110:113], v[196:199], v[6:9], v[110:113]
	v_mfma_f32_16x16x32_bf16 v[82:85], v[200:203], v[6:9], v[82:85]
	v_mfma_f32_16x16x32_bf16 v[224:227], v[204:207], v[6:9], v[50:53]
	v_mfma_f32_16x16x32_bf16 v[102:105], v[196:199], v[14:17], v[102:105]
	v_mfma_f32_16x16x32_bf16 v[74:77], v[196:199], v[22:25], v[74:77]
	v_mfma_f32_16x16x32_bf16 v[228:231], v[200:203], v[14:17], v[70:73]
	v_mfma_f32_16x16x32_bf16 v[70:73], v[192:195], v[22:25], v[106:109]
	v_mfma_f32_16x16x32_bf16 v[106:109], v[200:203], v[22:25], v[42:45]
	v_mfma_f32_16x16x32_bf16 v[118:121], v[192:195], v[14:17], v[118:121]
	ds_write2_b32 v66, v126, v122 offset1:16
	ds_write2_b32 v66, v127, v123 offset0:68 offset1:84
	ds_write2_b32 v66, v128, v124 offset0:136 offset1:152
	ds_write2_b32 v66, v129, v125 offset0:204 offset1:220
	s_nop 3
	ds_write2_b32 v66, v118, v70 offset0:32 offset1:48
	ds_write2_b32 v66, v119, v71 offset0:100 offset1:116
	ds_write2_b32 v66, v120, v72 offset0:168 offset1:184
	ds_write2_b32 v66, v121, v73 offset0:236 offset1:252
	v_add_u32_e32 v70, 0x2400, v66
	v_add_u32_e32 v72, 0x3000, v66
	v_mfma_f32_16x16x32_bf16 v[236:239], v[204:207], v[22:25], v[18:21]
	v_add_u32_e32 v71, 0x3400, v66
	v_mov_b32_e32 v73, v170
	ds_write2_b32 v67, v114, v110 offset0:64 offset1:80
	ds_write2_b32 v67, v115, v111 offset0:132 offset1:148
	ds_write2_b32 v67, v116, v112 offset0:200 offset1:216
	v_mfma_f32_16x16x32_bf16 v[46:49], v[192:195], v[54:57], v[98:101]
	ds_write2_b32 v68, v117, v113 offset0:12 offset1:28
	ds_write2_b32 v67, v102, v74 offset0:96 offset1:112
	ds_write2_b32 v67, v103, v75 offset0:164 offset1:180
	ds_write2_b32 v67, v104, v76 offset0:232 offset1:248
	ds_write2_b32 v68, v105, v77 offset0:44 offset1:60
	ds_write2_b32 v69, v94, v82 offset0:128 offset1:144
	ds_write2_b32 v69, v95, v83 offset0:196 offset1:212
	ds_write2_b32 v70, v96, v84 offset0:8 offset1:24
	ds_write2_b32 v70, v97, v85 offset0:76 offset1:92
	ds_write2_b32 v69, v228, v106 offset0:160 offset1:176
	ds_write2_b32 v69, v229, v107 offset0:228 offset1:244
	ds_write2_b32 v70, v230, v108 offset0:40 offset1:56
	ds_write2_b32 v70, v231, v109 offset0:108 offset1:124
	v_mfma_f32_16x16x32_bf16 v[14:17], v[200:203], v[54:57], v[38:41]
	ds_write2_b32 v72, v220, v224 offset0:192 offset1:208
	ds_write2_b32 v71, v221, v225 offset0:4 offset1:20
	ds_write2_b32 v71, v222, v226 offset0:72 offset1:88
	ds_write2_b32 v71, v223, v227 offset0:140 offset1:156
	ds_write2_b32 v72, v232, v236 offset0:224 offset1:240
	ds_write2_b32 v71, v233, v237 offset0:36 offset1:52
	ds_write2_b32 v71, v234, v238 offset0:104 offset1:120
	ds_write2_b32 v71, v235, v239 offset0:172 offset1:188
	s_waitcnt lgkmcnt(0)
	v_mfma_f32_16x16x32_bf16 v[2:5], v[204:207], v[54:57], v[158:161]
	s_barrier
	v_mfma_f32_16x16x32_bf16 v[54:57], v[192:195], v[208:211], v[90:93]
	s_nop 2
	v_mul_lo_u32 v90, v73, s33
	v_mfma_f32_16x16x32_bf16 v[38:41], v[196:199], v[208:211], v[62:65]
	v_mfma_f32_16x16x32_bf16 v[58:61], v[192:195], v[212:215], v[86:89]
	v_mfma_f32_16x16x32_bf16 v[62:65], v[192:195], v[216:219], v[78:81]
	ds_read_b128 v[74:77], v90
	s_nop 1
	ds_read_b128 v[78:81], v90 offset:16
	ds_read_b128 v[82:85], v90 offset:32
	ds_read_b128 v[86:89], v90 offset:48
	s_waitcnt lgkmcnt(3)
	v_mul_f32_e32 v91, v1, v74
	v_mul_f32_e32 v92, v1, v75
	v_mul_f32_e32 v93, v1, v76
	v_mul_f32_e32 v94, v1, v77
	ds_read_b128 v[74:77], v90 offset:64
	v_mfma_f32_16x16x32_bf16 v[18:21], v[204:207], v[216:219], v[130:133]
	s_waitcnt lgkmcnt(3)
	v_mul_f32_e32 v95, v1, v78
	v_mul_f32_e32 v96, v1, v79
	v_mul_f32_e32 v80, v1, v80
	s_waitcnt lgkmcnt(0)
	v_mul_f32_e32 v97, v1, v74
	v_mul_f32_e32 v98, v1, v75
	v_mul_f32_e32 v99, v1, v76
	v_mul_f32_e32 v100, v1, v77
	ds_read_b128 v[74:77], v90 offset:80
	v_mfma_f32_16x16x32_bf16 v[6:9], v[204:207], v[208:211], v[10:13]
	v_mul_f32_e32 v81, v1, v81
	v_mul_f32_e32 v82, v1, v82
	v_mul_f32_e32 v83, v1, v83
	s_waitcnt lgkmcnt(0)
	v_mul_f32_e32 v101, v1, v74
	v_mul_f32_e32 v102, v1, v75
	v_mul_f32_e32 v103, v1, v76
	v_mul_f32_e32 v104, v1, v77
	ds_read_b128 v[74:77], v90 offset:96
	v_mfma_f32_16x16x32_bf16 v[10:13], v[204:207], v[212:215], v[134:137]
	v_mul_f32_e32 v84, v1, v84
	v_mul_f32_e32 v85, v1, v85
	v_mul_f32_e32 v86, v1, v86
	s_waitcnt lgkmcnt(0)
	v_mul_f32_e32 v105, v1, v74
	v_mul_f32_e32 v106, v1, v75
	v_mul_f32_e32 v107, v1, v76
	v_mul_f32_e32 v108, v1, v77
	ds_read_b128 v[74:77], v90 offset:112
	v_mfma_f32_16x16x32_bf16 v[42:45], v[196:199], v[212:215], v[138:141]
	v_mul_f32_e32 v87, v1, v87
	v_mul_f32_e32 v88, v1, v88
	v_mul_f32_e32 v89, v1, v89
	s_waitcnt lgkmcnt(0)
	v_mul_f32_e32 v109, v1, v74
	v_mul_f32_e32 v110, v1, v75
	v_mul_f32_e32 v111, v1, v76
	v_mul_f32_e32 v112, v1, v77
	ds_read_b128 v[74:77], v90 offset:128
	v_mfma_f32_16x16x32_bf16 v[22:25], v[200:203], v[208:211], v[34:37]
	s_waitcnt lgkmcnt(0)
	v_mul_f32_e32 v113, v1, v74
	v_mul_f32_e32 v114, v1, v75
	v_mul_f32_e32 v115, v1, v76
	v_mul_f32_e32 v116, v1, v77
	ds_read_b128 v[74:77], v90 offset:144
	v_mfma_f32_16x16x32_bf16 v[26:29], v[200:203], v[212:215], v[26:29]
	s_waitcnt lgkmcnt(0)
	v_mul_f32_e32 v117, v1, v74
	v_mul_f32_e32 v118, v1, v75
	v_mul_f32_e32 v119, v1, v76
	v_mul_f32_e32 v120, v1, v77
	ds_read_b128 v[74:77], v90 offset:160
	v_mfma_f32_16x16x32_bf16 v[50:53], v[196:199], v[216:219], v[162:165]
	s_waitcnt lgkmcnt(0)
	v_mul_f32_e32 v121, v1, v74
	v_mul_f32_e32 v122, v1, v75
	v_mul_f32_e32 v123, v1, v76
	v_mul_f32_e32 v124, v1, v77
	ds_read_b128 v[74:77], v90 offset:176
	v_mfma_f32_16x16x32_bf16 v[34:37], v[200:203], v[216:219], v[166:169]
	s_waitcnt lgkmcnt(0)
	v_mul_f32_e32 v125, v1, v74
	v_mul_f32_e32 v126, v1, v75
	v_mul_f32_e32 v127, v1, v76
	v_mul_f32_e32 v128, v1, v77
	ds_read_b128 v[74:77], v90 offset:192
	s_waitcnt lgkmcnt(0)
	v_mul_f32_e32 v129, v1, v74
	v_mul_f32_e32 v130, v1, v75
	v_mul_f32_e32 v131, v1, v76
	v_mul_f32_e32 v132, v1, v77
	ds_read_b128 v[74:77], v90 offset:208
	s_waitcnt lgkmcnt(0)
	v_mul_f32_e32 v133, v1, v74
	v_mul_f32_e32 v134, v1, v75
	v_mul_f32_e32 v135, v1, v76
	v_mul_f32_e32 v136, v1, v77
	ds_read_b128 v[74:77], v90 offset:224
	s_waitcnt lgkmcnt(0)
	v_mul_f32_e32 v137, v1, v74
	v_mul_f32_e32 v138, v1, v75
	v_mul_f32_e32 v139, v1, v76
	v_mul_f32_e32 v140, v1, v77
	ds_read_b128 v[74:77], v90 offset:240
	s_waitcnt lgkmcnt(0)
	v_mul_f32_e32 v90, v1, v74
	v_add_u32_e32 v74, s4, v73
	v_mul_f32_e32 v141, v1, v75
	v_ashrrev_i32_e32 v75, 31, v74
	v_lshlrev_b64 v[74:75], 10, v[74:75]
	v_lshl_add_u64 v[74:75], s[6:7], 0, v[74:75]
	v_mul_f32_e32 v142, v1, v76
	v_mul_f32_e32 v143, v1, v77
	v_lshl_add_u64 v[78:79], v[74:75], 0, s[46:47]
	v_cvt_pk_bf16_f32 v74, v91, v92
	v_cvt_pk_bf16_f32 v75, v93, v94
	v_cvt_pk_bf16_f32 v76, v95, v96
	v_cvt_pk_bf16_f32 v77, v80, v81
	v_mul_u32_u24_e32 v73, 0x110, v170
	ds_write_b128 v73, v[74:77]
	s_nop 1
	v_cvt_pk_bf16_f32 v74, v82, v83
	v_cvt_pk_bf16_f32 v75, v84, v85
	v_cvt_pk_bf16_f32 v76, v86, v87
	v_cvt_pk_bf16_f32 v77, v88, v89
	ds_write_b128 v73, v[74:77] offset:16
	s_nop 1
	v_cvt_pk_bf16_f32 v74, v97, v98
	v_cvt_pk_bf16_f32 v75, v99, v100
	v_cvt_pk_bf16_f32 v76, v101, v102
	v_cvt_pk_bf16_f32 v77, v103, v104
	ds_write_b128 v73, v[74:77] offset:32
	s_nop 1
	v_cvt_pk_bf16_f32 v74, v105, v106
	v_cvt_pk_bf16_f32 v75, v107, v108
	v_cvt_pk_bf16_f32 v76, v109, v110
	v_cvt_pk_bf16_f32 v77, v111, v112
	ds_write_b128 v73, v[74:77] offset:48
	s_nop 1
	v_cvt_pk_bf16_f32 v74, v113, v114
	v_cvt_pk_bf16_f32 v75, v115, v116
	v_cvt_pk_bf16_f32 v76, v117, v118
	v_cvt_pk_bf16_f32 v77, v119, v120
	ds_write_b128 v73, v[74:77] offset:64
	s_nop 1
	v_cvt_pk_bf16_f32 v74, v121, v122
	v_cvt_pk_bf16_f32 v75, v123, v124
	v_cvt_pk_bf16_f32 v76, v125, v126
	v_cvt_pk_bf16_f32 v77, v127, v128
	ds_write_b128 v73, v[74:77] offset:80
	s_nop 1
	v_cvt_pk_bf16_f32 v74, v129, v130
	v_cvt_pk_bf16_f32 v75, v131, v132
	v_cvt_pk_bf16_f32 v76, v133, v134
	v_cvt_pk_bf16_f32 v77, v135, v136
	ds_write_b128 v73, v[74:77] offset:96
	s_nop 1
	v_cvt_pk_bf16_f32 v74, v137, v138
	v_cvt_pk_bf16_f32 v75, v139, v140
	v_cvt_pk_bf16_f32 v76, v90, v141
	v_cvt_pk_bf16_f32 v77, v142, v143
	ds_write_b128 v73, v[74:77] offset:112
	v_and_b32_e32 v91, 63, v170
	v_lshrrev_b32_e32 v92, 3, v91
	v_sub_u32_e32 v92, v92, v91
	v_and_b32_e32 v91, 7, v91
	v_lshlrev_b32_e32 v91, 4, v91
	v_mul_i32_i24_e32 v74, 0x400, v92
	v_add_u32_e32 v74, v74, v91
	v_mul_i32_i24_e32 v92, 0x110, v92
	v_add3_u32 v92, v92, v91, v73
	s_waitcnt lgkmcnt(0)
	ds_read_b128 v[80:83], v92 offset:0
	v_mov_b32_e32 v76, v74
	v_ashrrev_i32_e32 v77, 31, v76
	v_lshl_add_u64 v[88:89], v[76:77], 0, v[78:79]
	s_waitcnt lgkmcnt(0)
	global_store_dwordx4 v[88:89], v[80:83], off
	ds_read_b128 v[84:87], v92 offset:2176
	v_add_u32_e32 v76, 0x2000, v74
	v_ashrrev_i32_e32 v77, 31, v76
	v_lshl_add_u64 v[88:89], v[76:77], 0, v[78:79]
	s_waitcnt lgkmcnt(0)
	global_store_dwordx4 v[88:89], v[84:87], off
	ds_read_b128 v[80:83], v92 offset:4352
	v_add_u32_e32 v76, 0x4000, v74
	v_ashrrev_i32_e32 v77, 31, v76
	v_lshl_add_u64 v[88:89], v[76:77], 0, v[78:79]
	s_waitcnt lgkmcnt(0)
	global_store_dwordx4 v[88:89], v[80:83], off
	ds_read_b128 v[84:87], v92 offset:6528
	v_add_u32_e32 v76, 0x6000, v74
	v_ashrrev_i32_e32 v77, 31, v76
	v_lshl_add_u64 v[88:89], v[76:77], 0, v[78:79]
	s_waitcnt lgkmcnt(0)
	global_store_dwordx4 v[88:89], v[84:87], off
	ds_read_b128 v[80:83], v92 offset:8704
	v_add_u32_e32 v76, 0x8000, v74
	v_ashrrev_i32_e32 v77, 31, v76
	v_lshl_add_u64 v[88:89], v[76:77], 0, v[78:79]
	s_waitcnt lgkmcnt(0)
	global_store_dwordx4 v[88:89], v[80:83], off
	ds_read_b128 v[84:87], v92 offset:10880
	v_add_u32_e32 v76, 0xa000, v74
	v_ashrrev_i32_e32 v77, 31, v76
	v_lshl_add_u64 v[88:89], v[76:77], 0, v[78:79]
	s_waitcnt lgkmcnt(0)
	global_store_dwordx4 v[88:89], v[84:87], off
	ds_read_b128 v[80:83], v92 offset:13056
	v_add_u32_e32 v76, 0xc000, v74
	v_ashrrev_i32_e32 v77, 31, v76
	v_lshl_add_u64 v[88:89], v[76:77], 0, v[78:79]
	s_waitcnt lgkmcnt(0)
	global_store_dwordx4 v[88:89], v[80:83], off
	ds_read_b128 v[84:87], v92 offset:15232
	v_add_u32_e32 v76, 0xe000, v74
	v_ashrrev_i32_e32 v77, 31, v76
	v_lshl_add_u64 v[88:89], v[76:77], 0, v[78:79]
	s_waitcnt lgkmcnt(0)
	global_store_dwordx4 v[88:89], v[84:87], off
	s_waitcnt lgkmcnt(0)
	s_barrier
	ds_write2_b32 v66, v46, v54 offset1:16
	ds_write2_b32 v66, v47, v55 offset0:68 offset1:84
	ds_write2_b32 v66, v48, v56 offset0:136 offset1:152
	ds_write2_b32 v66, v49, v57 offset0:204 offset1:220
	ds_write2_b32 v66, v58, v62 offset0:32 offset1:48
	ds_write2_b32 v66, v59, v63 offset0:100 offset1:116
	ds_write2_b32 v66, v60, v64 offset0:168 offset1:184
	ds_write2_b32 v66, v61, v65 offset0:236 offset1:252
	ds_write2_b32 v67, v30, v38 offset0:64 offset1:80
	ds_write2_b32 v67, v31, v39 offset0:132 offset1:148
	ds_write2_b32 v67, v32, v40 offset0:200 offset1:216
	ds_write2_b32 v68, v33, v41 offset0:12 offset1:28
	ds_write2_b32 v67, v42, v50 offset0:96 offset1:112
	ds_write2_b32 v67, v43, v51 offset0:164 offset1:180
	ds_write2_b32 v67, v44, v52 offset0:232 offset1:248
	ds_write2_b32 v68, v45, v53 offset0:44 offset1:60
	ds_write2_b32 v69, v14, v22 offset0:128 offset1:144
	ds_write2_b32 v69, v15, v23 offset0:196 offset1:212
	ds_write2_b32 v70, v16, v24 offset0:8 offset1:24
	ds_write2_b32 v70, v17, v25 offset0:76 offset1:92
	ds_write2_b32 v69, v26, v34 offset0:160 offset1:176
	ds_write2_b32 v69, v27, v35 offset0:228 offset1:244
	ds_write2_b32 v70, v28, v36 offset0:40 offset1:56
	ds_write2_b32 v70, v29, v37 offset0:108 offset1:124
	ds_write2_b32 v72, v2, v6 offset0:192 offset1:208
	ds_write2_b32 v71, v3, v7 offset0:4 offset1:20
	ds_write2_b32 v71, v4, v8 offset0:72 offset1:88
	ds_write2_b32 v71, v5, v9 offset0:140 offset1:156
	ds_write2_b32 v72, v10, v18 offset0:224 offset1:240
	ds_write2_b32 v71, v11, v19 offset0:36 offset1:52
	ds_write2_b32 v71, v12, v20 offset0:104 offset1:120
	ds_write2_b32 v71, v13, v21 offset0:172 offset1:188
	v_mov_b32_e32 v18, v170
	s_waitcnt lgkmcnt(0)
	s_barrier
	s_nop 0
	v_mul_lo_u32 v19, v18, s33
	ds_read_b128 v[2:5], v19
	ds_read_b128 v[6:9], v19 offset:16
	ds_read_b128 v[10:13], v19 offset:32
	ds_read_b128 v[14:17], v19 offset:48
	s_waitcnt lgkmcnt(0)
	v_mul_f32_e32 v20, v1, v2
	v_mul_f32_e32 v21, v1, v3
	v_mul_f32_e32 v22, v1, v4
	v_mul_f32_e32 v23, v1, v5
	ds_read_b128 v[2:5], v19 offset:64
	v_mul_f32_e32 v24, v1, v6
	v_mul_f32_e32 v25, v1, v7
	v_mul_f32_e32 v8, v1, v8
	v_mul_f32_e32 v9, v1, v9
	s_waitcnt lgkmcnt(0)
	v_mul_f32_e32 v26, v1, v2
	v_mul_f32_e32 v27, v1, v3
	v_mul_f32_e32 v28, v1, v4
	v_mul_f32_e32 v29, v1, v5
	ds_read_b128 v[2:5], v19 offset:80
	v_mul_f32_e32 v10, v1, v10
	v_mul_f32_e32 v11, v1, v11
	v_mul_f32_e32 v12, v1, v12
	v_mul_f32_e32 v13, v1, v13
	s_waitcnt lgkmcnt(0)
	v_mul_f32_e32 v30, v1, v2
	v_mul_f32_e32 v31, v1, v3
	v_mul_f32_e32 v32, v1, v4
	v_mul_f32_e32 v33, v1, v5
	ds_read_b128 v[2:5], v19 offset:96
	v_mul_f32_e32 v14, v1, v14
	v_mul_f32_e32 v15, v1, v15
	v_mul_f32_e32 v16, v1, v16
	v_mul_f32_e32 v17, v1, v17
	s_waitcnt lgkmcnt(0)
	v_mul_f32_e32 v34, v1, v2
	v_mul_f32_e32 v35, v1, v3
	v_mul_f32_e32 v36, v1, v4
	v_mul_f32_e32 v37, v1, v5
	ds_read_b128 v[2:5], v19 offset:112
	s_waitcnt lgkmcnt(0)
	v_mul_f32_e32 v38, v1, v2
	v_mul_f32_e32 v39, v1, v3
	v_mul_f32_e32 v40, v1, v4
	v_mul_f32_e32 v41, v1, v5
	ds_read_b128 v[2:5], v19 offset:128
	s_waitcnt lgkmcnt(0)
	v_mul_f32_e32 v42, v1, v2
	v_mul_f32_e32 v43, v1, v3
	v_mul_f32_e32 v44, v1, v4
	v_mul_f32_e32 v45, v1, v5
	ds_read_b128 v[2:5], v19 offset:144
	s_waitcnt lgkmcnt(0)
	v_mul_f32_e32 v46, v1, v2
	v_mul_f32_e32 v47, v1, v3
	v_mul_f32_e32 v48, v1, v4
	v_mul_f32_e32 v49, v1, v5
	ds_read_b128 v[2:5], v19 offset:160
	s_waitcnt lgkmcnt(0)
	v_mul_f32_e32 v50, v1, v2
	v_mul_f32_e32 v51, v1, v3
	v_mul_f32_e32 v52, v1, v4
	v_mul_f32_e32 v53, v1, v5
	ds_read_b128 v[2:5], v19 offset:176
	s_waitcnt lgkmcnt(0)
	v_mul_f32_e32 v54, v1, v2
	v_mul_f32_e32 v55, v1, v3
	v_mul_f32_e32 v56, v1, v4
	v_mul_f32_e32 v57, v1, v5
	ds_read_b128 v[2:5], v19 offset:192
	s_waitcnt lgkmcnt(0)
	v_mul_f32_e32 v58, v1, v2
	v_mul_f32_e32 v59, v1, v3
	v_mul_f32_e32 v60, v1, v4
	v_mul_f32_e32 v61, v1, v5
	ds_read_b128 v[2:5], v19 offset:208
	s_waitcnt lgkmcnt(0)
	v_mul_f32_e32 v62, v1, v2
	v_mul_f32_e32 v63, v1, v3
	v_mul_f32_e32 v64, v1, v4
	v_mul_f32_e32 v65, v1, v5
	ds_read_b128 v[2:5], v19 offset:224
	s_waitcnt lgkmcnt(0)
	v_mul_f32_e32 v66, v1, v2
	v_mul_f32_e32 v67, v1, v3
	v_mul_f32_e32 v68, v1, v4
	v_mul_f32_e32 v69, v1, v5
	ds_read_b128 v[2:5], v19 offset:240
	s_waitcnt lgkmcnt(0)
	v_mul_f32_e32 v19, v1, v2
	v_add_u32_e32 v2, s4, v18
	v_mul_f32_e32 v70, v1, v3
	v_ashrrev_i32_e32 v3, 31, v2
	v_lshlrev_b64 v[2:3], 10, v[2:3]
	v_lshl_add_u64 v[2:3], s[6:7], 0, v[2:3]
	v_mul_f32_e32 v71, v1, v4
	v_mul_f32_e32 v1, v1, v5
	v_lshl_add_u64 v[6:7], v[2:3], 0, s[46:47]
	v_cvt_pk_bf16_f32 v2, v20, v21
	v_cvt_pk_bf16_f32 v3, v22, v23
	v_cvt_pk_bf16_f32 v4, v24, v25
	v_cvt_pk_bf16_f32 v5, v8, v9
	v_mul_u32_u24_e32 v8, 0x110, v170
	ds_write_b128 v8, v[2:5]
	s_mov_b64 s[4:5], 0
	s_nop 0
	v_cvt_pk_bf16_f32 v2, v10, v11
	v_cvt_pk_bf16_f32 v3, v12, v13
	v_cvt_pk_bf16_f32 v4, v14, v15
	v_cvt_pk_bf16_f32 v5, v16, v17
	ds_write_b128 v8, v[2:5] offset:16
	s_nop 1
	v_cvt_pk_bf16_f32 v2, v26, v27
	v_cvt_pk_bf16_f32 v3, v28, v29
	v_cvt_pk_bf16_f32 v4, v30, v31
	v_cvt_pk_bf16_f32 v5, v32, v33
	ds_write_b128 v8, v[2:5] offset:32
	s_nop 1
	v_cvt_pk_bf16_f32 v2, v34, v35
	v_cvt_pk_bf16_f32 v3, v36, v37
	v_cvt_pk_bf16_f32 v4, v38, v39
	v_cvt_pk_bf16_f32 v5, v40, v41
	ds_write_b128 v8, v[2:5] offset:48
	s_nop 1
	v_cvt_pk_bf16_f32 v2, v42, v43
	v_cvt_pk_bf16_f32 v3, v44, v45
	v_cvt_pk_bf16_f32 v4, v46, v47
	v_cvt_pk_bf16_f32 v5, v48, v49
	ds_write_b128 v8, v[2:5] offset:64
	s_nop 1
	v_cvt_pk_bf16_f32 v2, v50, v51
	v_cvt_pk_bf16_f32 v3, v52, v53
	v_cvt_pk_bf16_f32 v4, v54, v55
	v_cvt_pk_bf16_f32 v5, v56, v57
	ds_write_b128 v8, v[2:5] offset:80
	s_nop 1
	v_cvt_pk_bf16_f32 v2, v58, v59
	v_cvt_pk_bf16_f32 v3, v60, v61
	v_cvt_pk_bf16_f32 v4, v62, v63
	v_cvt_pk_bf16_f32 v5, v64, v65
	ds_write_b128 v8, v[2:5] offset:96
	s_nop 1
	v_cvt_pk_bf16_f32 v2, v66, v67
	v_cvt_pk_bf16_f32 v3, v68, v69
	v_cvt_pk_bf16_f32 v4, v19, v70
	v_cvt_pk_bf16_f32 v5, v71, v1
	ds_write_b128 v8, v[2:5] offset:112
	v_and_b32_e32 v9, 63, v170
	v_lshrrev_b32_e32 v16, 3, v9
	v_sub_u32_e32 v16, v16, v9
	v_and_b32_e32 v9, 7, v9
	v_lshlrev_b32_e32 v9, 4, v9
	v_mul_i32_i24_e32 v2, 0x400, v16
	v_add_u32_e32 v2, v2, v9
	v_mul_i32_i24_e32 v16, 0x110, v16
	v_add3_u32 v16, v16, v9, v8
	s_waitcnt lgkmcnt(0)
	ds_read_b128 v[12:15], v16 offset:0
	v_mov_b32_e32 v4, v2
	v_ashrrev_i32_e32 v5, 31, v4
	v_lshl_add_u64 v[10:11], v[4:5], 0, v[6:7]
	s_waitcnt lgkmcnt(0)
	global_store_dwordx4 v[10:11], v[12:15], off offset:128
	ds_read_b128 v[20:23], v16 offset:2176
	v_add_u32_e32 v4, 0x2000, v2
	v_ashrrev_i32_e32 v5, 31, v4
	v_lshl_add_u64 v[10:11], v[4:5], 0, v[6:7]
	s_waitcnt lgkmcnt(0)
	global_store_dwordx4 v[10:11], v[20:23], off offset:128
	ds_read_b128 v[12:15], v16 offset:4352
	v_add_u32_e32 v4, 0x4000, v2
	v_ashrrev_i32_e32 v5, 31, v4
	v_lshl_add_u64 v[10:11], v[4:5], 0, v[6:7]
	s_waitcnt lgkmcnt(0)
	global_store_dwordx4 v[10:11], v[12:15], off offset:128
	ds_read_b128 v[20:23], v16 offset:6528
	v_add_u32_e32 v4, 0x6000, v2
	v_ashrrev_i32_e32 v5, 31, v4
	v_lshl_add_u64 v[10:11], v[4:5], 0, v[6:7]
	s_waitcnt lgkmcnt(0)
	global_store_dwordx4 v[10:11], v[20:23], off offset:128
	ds_read_b128 v[12:15], v16 offset:8704
	v_add_u32_e32 v4, 0x8000, v2
	v_ashrrev_i32_e32 v5, 31, v4
	v_lshl_add_u64 v[10:11], v[4:5], 0, v[6:7]
	s_waitcnt lgkmcnt(0)
	global_store_dwordx4 v[10:11], v[12:15], off offset:128
	ds_read_b128 v[20:23], v16 offset:10880
	v_add_u32_e32 v4, 0xa000, v2
	v_ashrrev_i32_e32 v5, 31, v4
	v_lshl_add_u64 v[10:11], v[4:5], 0, v[6:7]
	s_waitcnt lgkmcnt(0)
	global_store_dwordx4 v[10:11], v[20:23], off offset:128
	ds_read_b128 v[12:15], v16 offset:13056
	v_add_u32_e32 v4, 0xc000, v2
	v_ashrrev_i32_e32 v5, 31, v4
	v_lshl_add_u64 v[10:11], v[4:5], 0, v[6:7]
	s_waitcnt lgkmcnt(0)
	global_store_dwordx4 v[10:11], v[12:15], off offset:128
	ds_read_b128 v[20:23], v16 offset:15232
	v_add_u32_e32 v4, 0xe000, v2
	v_ashrrev_i32_e32 v5, 31, v4
	v_lshl_add_u64 v[10:11], v[4:5], 0, v[6:7]
	s_waitcnt lgkmcnt(0)
	global_store_dwordx4 v[10:11], v[20:23], off offset:128
